# restore barrier of trailing half moved after next-tile setup; removed vmcnt(0) inside acc zeroing (P5,P6)
# speedup vs baseline: 1.0005x; 1.0005x over previous
; #define LAS __attribute__((address_space(3)))
; __global__ void __launch_bounds__(512, 2) mk_fwd(Args a) {
;     extern __shared__ __attribute__((aligned(16))) unsigned char lds_raw[];
;     LAS unsigned char* lds = (LAS unsigned char*)lds_raw;
;     cg::grid_group grid = cg::this_grid();
;     const int tid = threadIdx.x, lane = tid & 63, wave = __builtin_amdgcn_readfirstlane(tid >> 6);
;     const int G = gridDim.x, bx = blockIdx.x;
;     const float* x_p = a.in[0]; const float* x_s = a.in[1]; const float* rel_bias = a.in[2]; const float* g_mix = a.in[3]; const float* w_in = a.in[4]; const float* b_gate = a.in[5];
;     const float* w_a = a.in[6]; const float* w_b = a.in[7]; const float* w_out = a.in[8]; const float* sink = a.in[9]; const float* g_mlp = a.in[10]; const float* w_up = a.in[11]; const float* w_dn = a.in[12]; const float* g_fin = a.in[13];
;     unsigned char* ws = a.ws; float* out = a.out;
;     bf16* Win_t = (bf16*)(ws + WS_WIN); bf16* Wa_t = (bf16*)(ws + WS_WA); bf16* Wb_t = (bf16*)(ws + WS_WB); bf16* Wout_t = (bf16*)(ws + WS_WOUT); bf16* Wup_t = (bf16*)(ws + WS_WUP); bf16* Wdn_t = (bf16*)(ws + WS_WDN);
;     float* SSQ1 = (float*)(ws + WS_SSQ1); float* SSQ2 = (float*)(ws + WS_SSQ2);
;     bf16* XN = (bf16*)(ws + WS_XN); bf16* OA = (bf16*)(ws + WS_OA); bf16* OB = (bf16*)(ws + WS_OB); bf16* X1B = (bf16*)(ws + WS_X1B);
;     bf16* Zb = (bf16*)(ws + WS_Z); bf16* MRG = (bf16*)(ws + WS_MRG); bf16* Hb = (bf16*)(ws + WS_H); bf16* Gt = (bf16*)(ws + WS_G);
;     bf16* OBG = (bf16*)((unsigned char*)out + DO_OBG); float* LSE = (float*)((unsigned char*)out + DO_LSE);
;     grid.sync();
;     const int gw = bx * 8 + wave, NGW = G * 8;
;     unsigned* bar_ctr = (unsigned*)ws; unsigned bar_n = 0;
;     const unsigned my_xcc = (unsigned)__builtin_amdgcn_s_getreg((3 << 11) | 20) & 0xFu;
;     if (tid == 0) *(LAS unsigned*)(lds + RING_BYTES + 64) = __hip_atomic_fetch_add(bar_ctr + 512 + 64 * (my_xcc & 7u), 1u, __ATOMIC_RELAXED, __HIP_MEMORY_SCOPE_AGENT);
_Z6mk_fwd4Args:
	s_load_dword s24, s[0:1], 0x80
	s_load_dwordx16 s[36:51], s[0:1], 0x0
	s_load_dwordx16 s[8:23], s[0:1], 0x40
	v_and_b32_e32 v254, 0x3ff, v0
	s_nop 0
	v_readfirstlane_b32 s25, v254
	s_waitcnt lgkmcnt(0)
	s_mov_b32 s100, 0
	s_getreg_b32 s3, hwreg(HW_REG_XCC_ID, 0, 4)
	v_cmp_eq_u32_e64 s[0:1], 0, v254
	s_mov_b64 s[4:5], exec
	s_nop 0
	v_writelane_b32 v255, s0, 0
	s_nop 1
	v_writelane_b32 v255, s1, 1
	s_and_b64 s[0:1], s[4:5], s[0:1]
	s_mov_b64 exec, s[0:1]
	s_cbranch_execz .LBB0_14
	s_mov_b64 s[26:27], exec
	v_mbcnt_lo_u32_b32 v0, s26, 0
	v_mbcnt_hi_u32_b32 v0, s27, v0
	v_cmp_eq_u32_e32 vcc, 0, v0
	s_and_saveexec_b64 s[6:7], vcc
	s_cbranch_execz .LBB0_13
	s_lshl_b32 s0, s3, 8
	s_and_b32 s0, s0, 0x700
	s_bcnt1_i32_b64 s1, s[26:27]
	v_mov_b32_e32 v1, s0
	v_mov_b32_e32 v2, s1
	global_atomic_add v1, v1, v2, s[22:23] offset:2048 sc0

; template <class Epi, class Sched, bool ALIGN_EPI = false, bool SP2 = false, bool FP8 = false>
; __device__ __forceinline__ void gemm_phase(PG8_LAS unsigned char* lds, const Gemm g, const Sched& S, const Epi& E) {
;     ...
;         const bool has_next = S.next(ui + 1, nxt);
;         const char* nA = has_next ? (const char*)g.A + (size_t)nxt.pm * tstep : cA; const char* nB = has_next ? (const char*)g.Bt + (size_t)nxt.pn * tstep : cB;
; #pragma unroll 1
;         for (int t = 0; t < nt; t += 2) {
;             if constexpr (Epi::MID_T > 0) { if (t == Epi::MID_T) E.mid(acc, cur, wr, wc, fr, fq); }
;             const bool last = (t == nt - 2);
;             const char* a1 = cA + (size_t)(t + 1) * kstep;
;             const char* a2 = last ? nA : cA + (size_t)(t + 2) * kstep; const char* b2 = last ? nB : cB + (size_t)(t + 2) * kstep;
;             const char* a3 = a2 + kstep; const char* b3 = b2 + kstep;
;             if (last && has_next) S.a_ready(nxt);
;             if constexpr (SP2) {
;             PG8_LDB(B0, 0, 0); PG8_LDB(B1, 0, 1); PG8_SCHED; PG8_LDA(At, 0, 0); PG8_STAGE(PG8_SA(1, 1), a1 + hstep, voffA);
;             PG8_WAIT_V(8); PG8_WAIT_L(0); PG8_BAR; PG8_MMA(0, 0, At, B0); PG8_MMA(0, 1, At, B1); PG8_BAR; PG8_SCHED;
;             PG8_LDA(At, 0, 1); PG8_STAGE(PG8_SB(0, 0), b2, voffB); PG8_STAGE(PG8_SB(0, 1), b2 + hstep, voffB); PG8_STAGE(PG8_SA(0, 0), a2, voffA);
;             PG8_WAIT_V(8); PG8_WAIT_L(0); PG8_BAR; PG8_MMA(1, 0, At, B0); PG8_MMA(1, 1, At, B1); PG8_BAR; PG8_SCHED;
;             PG8_LDB(B0, 1, 0); PG8_LDB(B1, 1, 1); PG8_SCHED; PG8_LDA(At, 1, 0); PG8_STAGE(PG8_SA(0, 1), a2 + hstep, voffA);
;             PG8_WAIT_V(8); PG8_WAIT_L(0); PG8_BAR; PG8_MMA(0, 0, At, B0); PG8_MMA(0, 1, At, B1); PG8_BAR; PG8_SCHED;
;             PG8_LDA(At, 1, 1); PG8_STAGE(PG8_SB(1, 0), b3, voffB); PG8_STAGE(PG8_SB(1, 1), b3 + hstep, voffB); PG8_STAGE(PG8_SA(1, 0), a3, voffA);
;             PG8_WAIT_V(8); PG8_WAIT_L(0); PG8_BAR; PG8_MMA(1, 0, At, B0); PG8_MMA(1, 1, At, B1); PG8_BAR; PG8_SCHED;
;             } else {
;             PG8_LDB(B0, 0, 0); PG8_SCHED; PG8_LDA(At, 0, 0); PG8_STAGE(PG8_SA(1, 1), a1 + hstep, voffA);
;             PG8_WAIT_L(8); PG8_BAR; PG8_WAIT_L(0); PG8_MMA(0, 0, At, B0); PG8_BAR; PG8_SCHED;
;             PG8_LDB(B1, 0, 1); PG8_STAGE(PG8_SB(0, 0), b2, voffB);
;             PG8_BAR; PG8_WAIT_L(0); PG8_MMA(0, 1, At, B1); PG8_BAR;
.LBB0_101:
	s_ashr_i32 s65, s64, 31
	s_lshl_b64 s[0:1], s[64:65], 18
	s_add_u32 s66, s16, s0
	s_addc_u32 s67, s17, s1
	s_and_b64 s[0:1], s[4:5], exec
	s_cselect_b32 s15, s67, s71
	s_cselect_b32 s65, s66, s70
	s_ashr_i32 s63, s62, 31
	s_lshl_b64 s[0:1], s[62:63], 18
	s_add_u32 s68, s54, s0
	s_addc_u32 s69, s55, s1
	s_and_b64 s[0:1], s[4:5], exec
	s_cselect_b32 s63, s69, s73
	s_cselect_b32 s91, s68, s72
	s_add_u32 s70, s70, 0x20080
	s_addc_u32 s71, s71, 0
	s_add_u32 s92, s72, 0x100
	s_addc_u32 s93, s73, 0
	s_mov_b32 s94, -2
	s_cmp_eq_u32 s100, 0
	s_cbranch_scc1 .Lmy_nobar_P1
	s_barrier
	s_mov_b32 s100, 0
.Lmy_nobar_P1:
.LBB0_102:
	v_add_u32_e32 v140, s87, v160
	ds_read_b128 v[128:131], v140
	ds_read_b128 v[132:135], v140 offset:1024
	ds_read_b128 v[136:139], v140 offset:2048
	ds_read_b128 v[140:143], v140 offset:3072
	s_add_u32 s0, s70, 0xfffe0080
	s_addc_u32 s1, s71, -1
	s_cmp_eq_u32 s94, 4
	s_cselect_b32 s75, s15, s1
	s_cselect_b32 s74, s65, s0
	s_cselect_b32 s73, s63, s93
	s_cselect_b32 s72, s91, s92
	v_mov_b32_e32 v144, v156
	ds_read_b128 v[164:167], v161
	ds_read_b128 v[168:171], v161 offset:1024
	ds_read_b128 v[178:181], v161 offset:2048
	ds_read_b128 v[182:185], v161 offset:3072
	ds_read_b128 v[186:189], v161 offset:4096
	ds_read_b128 v[190:193], v161 offset:5120
	ds_read_b128 v[198:201], v161 offset:6144
	ds_read_b128 v[202:205], v161 offset:7168
	s_add_i32 m0, s77, 0xc000
	s_nop 0
	global_load_lds_dwordx4 v144, s[70:71]
	v_mov_b32_e32 v144, v158
	s_add_i32 m0, s77, 0xe000
	s_nop 0
	global_load_lds_dwordx4 v144, s[70:71]
	s_waitcnt lgkmcnt(8)
	s_barrier
	s_waitcnt lgkmcnt(0)
	s_setprio 1
	s_waitcnt lgkmcnt(0)
	v_mfma_scale_f32_16x16x128_f8f6f4 v[124:127], v[128:135], v[164:171], v[124:127], v162, v162 op_sel_hi:[0,0,0]
	v_mfma_scale_f32_16x16x128_f8f6f4 v[120:123], v[136:143], v[164:171], v[120:123], v162, v162 op_sel_hi:[0,0,0]
	v_mfma_scale_f32_16x16x128_f8f6f4 v[150:153], v[128:135], v[178:185], v[108:111], v162, v162 op_sel_hi:[0,0,0]
	v_mfma_scale_f32_16x16x128_f8f6f4 v[172:175], v[136:143], v[178:185], v[104:107], v162, v162 op_sel_hi:[0,0,0]
	v_mfma_scale_f32_16x16x128_f8f6f4 v[206:209], v[128:135], v[186:193], v[92:95], v162, v162 op_sel_hi:[0,0,0]
	v_mfma_scale_f32_16x16x128_f8f6f4 v[210:213], v[136:143], v[186:193], v[88:91], v162, v162 op_sel_hi:[0,0,0]
	v_mfma_scale_f32_16x16x128_f8f6f4 v[214:217], v[128:135], v[198:205], v[76:79], v162, v162 op_sel_hi:[0,0,0]
	v_mfma_scale_f32_16x16x128_f8f6f4 v[218:221], v[136:143], v[198:205], v[72:75], v162, v162 op_sel_hi:[0,0,0]
	s_setprio 0
	s_barrier
	s_nop 1
	v_add_u32_e32 v92, s88, v160
	v_mov_b32_e32 v104, v157
	s_add_i32 s0, s87, s3
	ds_read_b128 v[72:75], v92
	ds_read_b128 v[76:79], v92 offset:1024
	ds_read_b128 v[88:91], v92 offset:2048
	ds_read_b128 v[92:95], v92 offset:3072
	s_mov_b32 m0, s0
	s_nop 0
	global_load_lds_dwordx4 v104, s[72:73]
	v_mov_b32_e32 v104, v159
	s_add_i32 m0, s0, 0x2000
	s_nop 0
	global_load_lds_dwordx4 v104, s[72:73]
	s_barrier
	s_waitcnt lgkmcnt(0)
	s_setprio 1
	s_waitcnt lgkmcnt(0)
	v_mfma_scale_f32_16x16x128_f8f6f4 v[116:119], v[72:79], v[164:171], v[116:119], v162, v162 op_sel_hi:[0,0,0]
	v_mfma_scale_f32_16x16x128_f8f6f4 v[112:115], v[88:95], v[164:171], v[112:115], v162, v162 op_sel_hi:[0,0,0]
	v_mfma_scale_f32_16x16x128_f8f6f4 v[164:167], v[72:79], v[178:185], v[100:103], v162, v162 op_sel_hi:[0,0,0]
	v_mfma_scale_f32_16x16x128_f8f6f4 v[168:171], v[88:95], v[178:185], v[96:99], v162, v162 op_sel_hi:[0,0,0]
	v_mfma_scale_f32_16x16x128_f8f6f4 v[178:181], v[72:79], v[186:193], v[84:87], v162, v162 op_sel_hi:[0,0,0]
	v_mfma_scale_f32_16x16x128_f8f6f4 v[182:185], v[88:95], v[186:193], v[80:83], v162, v162 op_sel_hi:[0,0,0]
	v_mfma_scale_f32_16x16x128_f8f6f4 v[186:189], v[72:79], v[198:205], v[68:71], v162, v162 op_sel_hi:[0,0,0]
	v_mfma_scale_f32_16x16x128_f8f6f4 v[190:193], v[88:95], v[198:205], v[64:67], v162, v162 op_sel_hi:[0,0,0]
	s_setprio 0
	v_mov_b32_e32 v144, v156
	s_mov_b32 m0, s77
	s_barrier
	s_nop 2
	ds_read_b128 v[64:67], v161 offset:16384
	ds_read_b128 v[68:71], v161 offset:17408
	ds_read_b128 v[80:83], v161 offset:18432
	ds_read_b128 v[84:87], v161 offset:19456
	ds_read_b128 v[96:99], v161 offset:20480
	ds_read_b128 v[100:103], v161 offset:21504
	ds_read_b128 v[104:107], v161 offset:22528
	ds_read_b128 v[108:111], v161 offset:23552
	s_nop 0
	global_load_lds_dwordx4 v144, s[74:75]
	v_mov_b32_e32 v144, v158
	s_mov_b32 m0, s78
	s_nop 0
	global_load_lds_dwordx4 v144, s[74:75]
	s_barrier
	s_waitcnt lgkmcnt(0)
	s_setprio 1
	s_waitcnt lgkmcnt(0)
	v_mfma_scale_f32_16x16x128_f8f6f4 v[60:63], v[128:135], v[64:71], v[60:63], v162, v162 op_sel_hi:[0,0,0]
	v_mfma_scale_f32_16x16x128_f8f6f4 v[56:59], v[136:143], v[64:71], v[56:59], v162, v162 op_sel_hi:[0,0,0]
	v_mfma_scale_f32_16x16x128_f8f6f4 v[198:201], v[128:135], v[80:87], v[44:47], v162, v162 op_sel_hi:[0,0,0]
	v_mfma_scale_f32_16x16x128_f8f6f4 v[202:205], v[136:143], v[80:87], v[40:43], v162, v162 op_sel_hi:[0,0,0]
	v_mfma_scale_f32_16x16x128_f8f6f4 v[222:225], v[128:135], v[96:103], v[28:31], v162, v162 op_sel_hi:[0,0,0]
	v_mfma_scale_f32_16x16x128_f8f6f4 v[226:229], v[136:143], v[96:103], v[24:27], v162, v162 op_sel_hi:[0,0,0]
	v_mfma_scale_f32_16x16x128_f8f6f4 v[230:233], v[128:135], v[104:111], v[12:15], v162, v162 op_sel_hi:[0,0,0]
	v_mfma_scale_f32_16x16x128_f8f6f4 v[234:237], v[136:143], v[104:111], v[8:11], v162, v162 op_sel_hi:[0,0,0]
	s_setprio 0
	s_barrier
	s_add_u32 s0, s72, 0x20000
	s_addc_u32 s1, s73, 0
	s_nop 2
	v_mov_b32_e32 v8, v157
	s_add_i32 s95, s88, s3
	s_mov_b32 m0, s95
	s_nop 0
	global_load_lds_dwordx4 v8, s[0:1]
	v_mov_b32_e32 v8, v159
	s_add_i32 m0, s95, 0x2000
	s_nop 0
	global_load_lds_dwordx4 v8, s[0:1]
	s_waitcnt vmcnt(6)
	s_barrier
; #define PG8_STAGE(bufoff, gbase, voff) do { _Pragma("unroll") for (int _i = 0; _i < 2; ++_i) { unsigned vo_ = (voff)[_i]; if constexpr (FP8) asm volatile("" : "+v"(vo_)); \
;         __builtin_amdgcn_global_load_lds((const unsigned*)((const char*)(gbase) + vo_), (PG8_LAS unsigned*)(lds + (bufoff) + ldsw + _i * 8192), 16, 0, 0); } } while (0)
; #define PG8_LDA(dst, b, h) do { _Pragma("unroll") for (int m = 0; m < 4; ++m) _Pragma("unroll") for (int k = 0; k < 2; ++k) dst[m][k] = *(const PG8_LAS bf16x8*)(lds + PG8_SA(b, h) + aoff + m * 2048 + k * 1024); } while (0)
; #define PG8_LDB(dst, b, h) do { _Pragma("unroll") for (int n = 0; n < 2; ++n) _Pragma("unroll") for (int k = 0; k < 2; ++k) dst[n][k] = *(const PG8_LAS bf16x8*)(lds + PG8_SB(b, h) + boff + n * 2048 + k * 1024); } while (0)
; #define PG8_WAIT_V(n) asm volatile("s_waitcnt vmcnt(" #n ")" ::: "memory")
; #define PG8_WAIT_L(n) asm volatile("s_waitcnt lgkmcnt(" #n ")" ::: "memory")
; #define PG8_BAR __builtin_amdgcn_s_barrier()
; #define PG8_SCHED __builtin_amdgcn_sched_barrier(0)
; template <class Epi, class Sched, bool ALIGN_EPI = false, bool SP2 = false, bool FP8 = false>
; __device__ __forceinline__ void gemm_phase(PG8_LAS unsigned char* lds, const Gemm g, const Sched& S, const Epi& E) {
;     ...
;             PG8_WAIT_V(6); PG8_BAR; PG8_MMA(1, 1, At, B1); PG8_BAR;
;             PG8_LDB(B0, 1, 0); PG8_SCHED; PG8_LDA(At, 1, 0); PG8_STAGE(PG8_SA(0, 1), a2 + hstep, voffA);
;             PG8_WAIT_L(8); PG8_BAR; PG8_WAIT_L(0); PG8_MMA(0, 0, At, B0); PG8_BAR; PG8_SCHED;
;             PG8_LDB(B1, 1, 1); PG8_STAGE(PG8_SB(1, 0), b3, voffB);
;             PG8_BAR; PG8_WAIT_L(0); PG8_MMA(0, 1, At, B1); PG8_BAR;
	s_setprio 1
	v_mfma_scale_f32_16x16x128_f8f6f4 v[52:55], v[72:79], v[64:71], v[52:55], v162, v162 op_sel_hi:[0,0,0]
	v_mfma_scale_f32_16x16x128_f8f6f4 v[48:51], v[88:95], v[64:71], v[48:51], v162, v162 op_sel_hi:[0,0,0]
	v_mfma_scale_f32_16x16x128_f8f6f4 v[238:241], v[72:79], v[80:87], v[36:39], v162, v162 op_sel_hi:[0,0,0]
	v_mfma_scale_f32_16x16x128_f8f6f4 v[242:245], v[88:95], v[80:87], v[32:35], v162, v162 op_sel_hi:[0,0,0]
	v_mfma_scale_f32_16x16x128_f8f6f4 v[246:249], v[72:79], v[96:103], v[20:23], v162, v162 op_sel_hi:[0,0,0]
	v_mfma_scale_f32_16x16x128_f8f6f4 v[250:253], v[88:95], v[96:103], v[16:19], v162, v162 op_sel_hi:[0,0,0]
	v_mfma_scale_f32_16x16x128_f8f6f4 v[194:197], v[72:79], v[104:111], v[4:7], v162, v162 op_sel_hi:[0,0,0]
	v_mfma_scale_f32_16x16x128_f8f6f4 v[146:149], v[88:95], v[104:111], v[0:3], v162, v162 op_sel_hi:[0,0,0]
	s_setprio 0
	s_add_i32 s95, 0, 0x18000
	v_add_u32_e32 v8, s95, v160
	s_barrier
	s_nop 2
	ds_read_b128 v[0:3], v8
	ds_read_b128 v[4:7], v8 offset:1024
	ds_read_b128 v[16:19], v8 offset:2048
	ds_read_b128 v[20:23], v8 offset:3072
	s_add_u32 s0, s74, 0x20000
	v_mov_b32_e32 v64, v156
	s_mov_b32 m0, s79
	ds_read_b128 v[8:11], v161 offset:32768
	ds_read_b128 v[12:15], v161 offset:33792
	ds_read_b128 v[24:27], v161 offset:34816
	ds_read_b128 v[28:31], v161 offset:35840
	ds_read_b128 v[32:35], v161 offset:36864
	ds_read_b128 v[36:39], v161 offset:37888
	ds_read_b128 v[40:43], v161 offset:38912
	ds_read_b128 v[44:47], v161 offset:39936
	s_addc_u32 s1, s75, 0
	s_nop 0
	global_load_lds_dwordx4 v64, s[0:1]
	v_mov_b32_e32 v64, v158
	s_mov_b32 m0, s80
	s_nop 0
	global_load_lds_dwordx4 v64, s[0:1]
	s_waitcnt lgkmcnt(8)
	s_barrier
	s_waitcnt lgkmcnt(0)
	s_setprio 1
	s_waitcnt lgkmcnt(0)
	v_mfma_scale_f32_16x16x128_f8f6f4 v[124:127], v[0:7], v[8:15], v[124:127], v162, v162 op_sel_hi:[0,0,0]
	v_mfma_scale_f32_16x16x128_f8f6f4 v[120:123], v[16:23], v[8:15], v[120:123], v162, v162 op_sel_hi:[0,0,0]
	v_mfma_scale_f32_16x16x128_f8f6f4 v[108:111], v[0:7], v[24:31], v[150:153], v162, v162 op_sel_hi:[0,0,0]
	v_mfma_scale_f32_16x16x128_f8f6f4 v[104:107], v[16:23], v[24:31], v[172:175], v162, v162 op_sel_hi:[0,0,0]
	v_mfma_scale_f32_16x16x128_f8f6f4 v[92:95], v[0:7], v[32:39], v[206:209], v162, v162 op_sel_hi:[0,0,0]
	v_mfma_scale_f32_16x16x128_f8f6f4 v[88:91], v[16:23], v[32:39], v[210:213], v162, v162 op_sel_hi:[0,0,0]
	v_mfma_scale_f32_16x16x128_f8f6f4 v[76:79], v[0:7], v[40:47], v[214:217], v162, v162 op_sel_hi:[0,0,0]
	v_mfma_scale_f32_16x16x128_f8f6f4 v[72:75], v[16:23], v[40:47], v[218:221], v162, v162 op_sel_hi:[0,0,0]
	s_setprio 0
	s_barrier
	s_add_i32 s96, 0, 0x1c000
	v_add_u32_e32 v64, s96, v160
	v_mov_b32_e32 v144, v157
	ds_read_b128 v[128:131], v64
	ds_read_b128 v[132:135], v64 offset:1024
	ds_read_b128 v[136:139], v64 offset:2048
	ds_read_b128 v[140:143], v64 offset:3072
	s_add_i32 s0, s95, s3
	v_lshl_add_u64 v[64:65], s[72:73], 0, v[144:145]
	v_lshl_add_u64 v[64:65], v[64:65], 0, s[8:9]
	s_mov_b32 m0, s0
	v_mov_b32_e32 v144, v159
	global_load_lds_dwordx4 v[64:65], off
	s_add_i32 m0, s0, 0x2000
	v_lshl_add_u64 v[64:65], s[72:73], 0, v[144:145]
	v_lshl_add_u64 v[64:65], v[64:65], 0, s[8:9]
	global_load_lds_dwordx4 v[64:65], off
	s_barrier
; #define PG8_STAGE(bufoff, gbase, voff) do { _Pragma("unroll") for (int _i = 0; _i < 2; ++_i) { unsigned vo_ = (voff)[_i]; if constexpr (FP8) asm volatile("" : "+v"(vo_)); \
;         __builtin_amdgcn_global_load_lds((const unsigned*)((const char*)(gbase) + vo_), (PG8_LAS unsigned*)(lds + (bufoff) + ldsw + _i * 8192), 16, 0, 0); } } while (0)
; #define PG8_LDA(dst, b, h) do { _Pragma("unroll") for (int m = 0; m < 4; ++m) _Pragma("unroll") for (int k = 0; k < 2; ++k) dst[m][k] = *(const PG8_LAS bf16x8*)(lds + PG8_SA(b, h) + aoff + m * 2048 + k * 1024); } while (0)
; #define PG8_WAIT_V(n) asm volatile("s_waitcnt vmcnt(" #n ")" ::: "memory")
; #define PG8_WAIT_L(n) asm volatile("s_waitcnt lgkmcnt(" #n ")" ::: "memory")
; #define PG8_BAR __builtin_amdgcn_s_barrier()
; #define PG8_SCHED __builtin_amdgcn_sched_barrier(0)
; template <class Epi, class Sched, bool ALIGN_EPI = false, bool SP2 = false, bool FP8 = false>
; __device__ __forceinline__ void gemm_phase(PG8_LAS unsigned char* lds, const Gemm g, const Sched& S, const Epi& E) {
;     ...
;             PG8_BAR; PG8_WAIT_L(0); PG8_MMA(0, 1, At, B1); PG8_BAR;
;             PG8_LDA(At, 1, 1); PG8_STAGE(PG8_SA(1, 0), a3, voffA);
;             PG8_BAR; PG8_WAIT_L(0); PG8_MMA(1, 0, At, B0); PG8_BAR; PG8_SCHED;
;             PG8_STAGE(PG8_SB(1, 1), b3 + hstep, voffB);
;             PG8_WAIT_V(6); PG8_BAR; PG8_MMA(1, 1, At, B1); PG8_BAR;
;             }
;         }
;         if constexpr (ALIGN_EPI) { if (wr == 0) PG8_BAR; }
	s_waitcnt lgkmcnt(0)
	s_setprio 1
	s_waitcnt lgkmcnt(0)
	v_mfma_scale_f32_16x16x128_f8f6f4 v[116:119], v[128:135], v[8:15], v[116:119], v162, v162 op_sel_hi:[0,0,0]
	v_mfma_scale_f32_16x16x128_f8f6f4 v[112:115], v[136:143], v[8:15], v[112:115], v162, v162 op_sel_hi:[0,0,0]
	v_mfma_scale_f32_16x16x128_f8f6f4 v[100:103], v[128:135], v[24:31], v[164:167], v162, v162 op_sel_hi:[0,0,0]
	v_mfma_scale_f32_16x16x128_f8f6f4 v[96:99], v[136:143], v[24:31], v[168:171], v162, v162 op_sel_hi:[0,0,0]
	v_mfma_scale_f32_16x16x128_f8f6f4 v[84:87], v[128:135], v[32:39], v[178:181], v162, v162 op_sel_hi:[0,0,0]
	v_mfma_scale_f32_16x16x128_f8f6f4 v[80:83], v[136:143], v[32:39], v[182:185], v162, v162 op_sel_hi:[0,0,0]
	v_mfma_scale_f32_16x16x128_f8f6f4 v[68:71], v[128:135], v[40:47], v[186:189], v162, v162 op_sel_hi:[0,0,0]
	v_mfma_scale_f32_16x16x128_f8f6f4 v[64:67], v[136:143], v[40:47], v[190:193], v162, v162 op_sel_hi:[0,0,0]
	s_setprio 0
	v_mov_b32_e32 v144, v156
	s_barrier
	ds_read_b128 v[32:35], v161 offset:49152
	ds_read_b128 v[36:39], v161 offset:50176
	ds_read_b128 v[164:167], v161 offset:51200
	ds_read_b128 v[168:171], v161 offset:52224
	ds_read_b128 v[178:181], v161 offset:53248
	ds_read_b128 v[182:185], v161 offset:54272
	ds_read_b128 v[186:189], v161 offset:55296
	ds_read_b128 v[190:193], v161 offset:56320
	s_mov_b32 m0, s83
	v_lshl_add_u64 v[8:9], s[74:75], 0, v[144:145]
	v_lshl_add_u64 v[8:9], v[8:9], 0, s[8:9]
	v_mov_b32_e32 v144, v158
	global_load_lds_dwordx4 v[8:9], off
	s_mov_b32 m0, s84
	v_lshl_add_u64 v[8:9], s[74:75], 0, v[144:145]
	v_lshl_add_u64 v[8:9], v[8:9], 0, s[8:9]
	global_load_lds_dwordx4 v[8:9], off
	s_barrier
	s_waitcnt lgkmcnt(0)
	s_setprio 1
	s_waitcnt lgkmcnt(0)
	v_mfma_scale_f32_16x16x128_f8f6f4 v[60:63], v[0:7], v[32:39], v[60:63], v162, v162 op_sel_hi:[0,0,0]
	v_mfma_scale_f32_16x16x128_f8f6f4 v[56:59], v[16:23], v[32:39], v[56:59], v162, v162 op_sel_hi:[0,0,0]
	v_mfma_scale_f32_16x16x128_f8f6f4 v[44:47], v[0:7], v[164:171], v[198:201], v162, v162 op_sel_hi:[0,0,0]
	v_mfma_scale_f32_16x16x128_f8f6f4 v[40:43], v[16:23], v[164:171], v[202:205], v162, v162 op_sel_hi:[0,0,0]
	v_mfma_scale_f32_16x16x128_f8f6f4 v[28:31], v[0:7], v[178:185], v[222:225], v162, v162 op_sel_hi:[0,0,0]
	v_mfma_scale_f32_16x16x128_f8f6f4 v[24:27], v[16:23], v[178:185], v[226:229], v162, v162 op_sel_hi:[0,0,0]
	v_mfma_scale_f32_16x16x128_f8f6f4 v[12:15], v[0:7], v[186:193], v[230:233], v162, v162 op_sel_hi:[0,0,0]
	v_mfma_scale_f32_16x16x128_f8f6f4 v[8:11], v[16:23], v[186:193], v[234:237], v162, v162 op_sel_hi:[0,0,0]
	s_setprio 0
	s_barrier
	s_add_u32 s0, s72, 0x20080
	s_addc_u32 s1, s73, 0
	v_mov_b32_e32 v0, v157
	s_add_i32 s72, s96, s3
	s_mov_b32 m0, s72
	s_nop 0
	global_load_lds_dwordx4 v0, s[0:1]
	v_mov_b32_e32 v0, v159
	s_add_i32 m0, s72, 0x2000
	s_nop 0
	global_load_lds_dwordx4 v0, s[0:1]
	s_waitcnt vmcnt(6)
	s_barrier
	s_setprio 1
	v_mfma_scale_f32_16x16x128_f8f6f4 v[52:55], v[128:135], v[32:39], v[52:55], v162, v162 op_sel_hi:[0,0,0]
	v_mfma_scale_f32_16x16x128_f8f6f4 v[48:51], v[136:143], v[32:39], v[48:51], v162, v162 op_sel_hi:[0,0,0]
	v_mfma_scale_f32_16x16x128_f8f6f4 v[36:39], v[128:135], v[164:171], v[238:241], v162, v162 op_sel_hi:[0,0,0]
	v_mfma_scale_f32_16x16x128_f8f6f4 v[32:35], v[136:143], v[164:171], v[242:245], v162, v162 op_sel_hi:[0,0,0]
	v_mfma_scale_f32_16x16x128_f8f6f4 v[20:23], v[128:135], v[178:185], v[246:249], v162, v162 op_sel_hi:[0,0,0]
	v_mfma_scale_f32_16x16x128_f8f6f4 v[16:19], v[136:143], v[178:185], v[250:253], v162, v162 op_sel_hi:[0,0,0]
	v_mfma_scale_f32_16x16x128_f8f6f4 v[4:7], v[128:135], v[186:193], v[194:197], v162, v162 op_sel_hi:[0,0,0]
	v_mfma_scale_f32_16x16x128_f8f6f4 v[0:3], v[136:143], v[186:193], v[146:149], v162, v162 op_sel_hi:[0,0,0]
	s_setprio 0
	s_add_i32 s94, s94, 2
	s_add_u32 s70, s70, 0x100
	s_addc_u32 s71, s71, 0
	s_add_u32 s92, s92, 0x100
	s_addc_u32 s93, s93, 0
	s_cmp_gt_u32 s94, 5
	s_barrier
	s_cbranch_scc0 .LBB0_102
	s_and_b64 vcc, exec, s[44:45]
	s_cbranch_vccz .LBB0_105
	s_barrier

; #define PG8_BAR __builtin_amdgcn_s_barrier()
; template <class Epi, class Sched, bool ALIGN_EPI = false, bool SP2 = false, bool FP8 = false>
; __device__ __forceinline__ void gemm_phase(PG8_LAS unsigned char* lds, const Gemm g, const Sched& S, const Epi& E) {
;     ...
;         if (!has_next) break;
; #pragma unroll
;         for (int a = 0; a < 2; ++a)
; #pragma unroll
;             for (int b = 0; b < 2; ++b)
; #pragma unroll
;                 for (int m = 0; m < 4; ++m)
; #pragma unroll
;                     for (int n = 0; n < 2; ++n) { acc[a][b][m][n] = (f32x4){0.f, 0.f, 0.f, 0.f}; if constexpr (FP8) asm volatile("" : "+v"(acc[a][b][m][n])); }
;         cur = nxt; cA = nA; cB = nB; ++ui;
;         if constexpr (ALIGN_EPI) { if (wr == 1) PG8_BAR; }
.LBB0_113:
	s_andn2_b64 vcc, exec, s[4:5]
	s_mov_b64 s[4:5], -1
	s_cbranch_vccnz .LBB0_98
	s_mov_b32 s13, s12
	s_mov_b32 s14, s12
	s_mov_b32 s15, s12
	v_mov_b64_e32 v[0:1], s[12:13]
	v_mov_b64_e32 v[126:127], s[14:15]
	v_mov_b64_e32 v[122:123], s[14:15]
	v_mov_b64_e32 v[110:111], s[14:15]
	v_mov_b64_e32 v[106:107], s[14:15]
	v_mov_b64_e32 v[94:95], s[14:15]
	v_mov_b64_e32 v[90:91], s[14:15]
	v_mov_b64_e32 v[78:79], s[14:15]
	v_mov_b64_e32 v[74:75], s[14:15]
	v_mov_b64_e32 v[118:119], s[14:15]
	v_mov_b64_e32 v[114:115], s[14:15]
	v_mov_b64_e32 v[102:103], s[14:15]
	v_mov_b64_e32 v[98:99], s[14:15]
	v_mov_b64_e32 v[86:87], s[14:15]
	v_mov_b64_e32 v[82:83], s[14:15]
	v_mov_b64_e32 v[70:71], s[14:15]
	v_mov_b64_e32 v[66:67], s[14:15]
	v_mov_b64_e32 v[62:63], s[14:15]
	v_mov_b64_e32 v[58:59], s[14:15]
	v_mov_b64_e32 v[46:47], s[14:15]
	v_mov_b64_e32 v[42:43], s[14:15]
	v_mov_b64_e32 v[30:31], s[14:15]
	v_mov_b64_e32 v[26:27], s[14:15]
	v_mov_b64_e32 v[12:13], s[12:13]
	v_mov_b64_e32 v[8:9], s[12:13]
	v_mov_b64_e32 v[54:55], s[14:15]
	v_mov_b64_e32 v[50:51], s[14:15]
	v_mov_b64_e32 v[38:39], s[14:15]
	v_mov_b64_e32 v[34:35], s[14:15]
	v_mov_b64_e32 v[22:23], s[14:15]
	v_mov_b64_e32 v[18:19], s[14:15]
	v_mov_b64_e32 v[4:5], s[12:13]
	v_mov_b64_e32 v[2:3], s[14:15]
	v_mov_b64_e32 v[124:125], s[12:13]
	v_mov_b64_e32 v[120:121], s[12:13]
	v_mov_b64_e32 v[108:109], s[12:13]
	v_mov_b64_e32 v[104:105], s[12:13]
	v_mov_b64_e32 v[92:93], s[12:13]
	v_mov_b64_e32 v[88:89], s[12:13]
	v_mov_b64_e32 v[76:77], s[12:13]
	v_mov_b64_e32 v[72:73], s[12:13]
	v_mov_b64_e32 v[116:117], s[12:13]
	v_mov_b64_e32 v[112:113], s[12:13]
	v_mov_b64_e32 v[100:101], s[12:13]
	v_mov_b64_e32 v[96:97], s[12:13]
	v_mov_b64_e32 v[84:85], s[12:13]
	v_mov_b64_e32 v[80:81], s[12:13]
	v_mov_b64_e32 v[68:69], s[12:13]
	v_mov_b64_e32 v[64:65], s[12:13]
	v_mov_b64_e32 v[60:61], s[12:13]
	v_mov_b64_e32 v[56:57], s[12:13]
	v_mov_b64_e32 v[44:45], s[12:13]
	v_mov_b64_e32 v[40:41], s[12:13]
	v_mov_b64_e32 v[28:29], s[12:13]
	v_mov_b64_e32 v[24:25], s[12:13]
	v_mov_b64_e32 v[14:15], s[14:15]
	v_mov_b64_e32 v[10:11], s[14:15]
	v_mov_b64_e32 v[52:53], s[12:13]
	v_mov_b64_e32 v[48:49], s[12:13]
	v_mov_b64_e32 v[36:37], s[12:13]
	v_mov_b64_e32 v[32:33], s[12:13]
	v_mov_b64_e32 v[20:21], s[12:13]
	v_mov_b64_e32 v[16:17], s[12:13]
	v_mov_b64_e32 v[6:7], s[14:15]
	s_andn2_b64 vcc, exec, s[6:7]
	s_cbranch_vccnz .LBB0_97
	s_mov_b32 s100, 1
	s_branch .LBB0_97

; #define PG8_STAGE(bufoff, gbase, voff) do { _Pragma("unroll") for (int _i = 0; _i < 2; ++_i) { unsigned vo_ = (voff)[_i]; if constexpr (FP8) asm volatile("" : "+v"(vo_)); \
;         __builtin_amdgcn_global_load_lds((const unsigned*)((const char*)(gbase) + vo_), (PG8_LAS unsigned*)(lds + (bufoff) + ldsw + _i * 8192), 16, 0, 0); } } while (0)
; #define PG8_LDA(dst, b, h) do { _Pragma("unroll") for (int m = 0; m < 4; ++m) _Pragma("unroll") for (int k = 0; k < 2; ++k) dst[m][k] = *(const PG8_LAS bf16x8*)(lds + PG8_SA(b, h) + aoff + m * 2048 + k * 1024); } while (0)
; #define PG8_LDB(dst, b, h) do { _Pragma("unroll") for (int n = 0; n < 2; ++n) _Pragma("unroll") for (int k = 0; k < 2; ++k) dst[n][k] = *(const PG8_LAS bf16x8*)(lds + PG8_SB(b, h) + boff + n * 2048 + k * 1024); } while (0)
; #define PG8_WAIT_V(n) asm volatile("s_waitcnt vmcnt(" #n ")" ::: "memory")
; #define PG8_WAIT_L(n) asm volatile("s_waitcnt lgkmcnt(" #n ")" ::: "memory")
; #define PG8_BAR __builtin_amdgcn_s_barrier()
; #define PG8_SCHED __builtin_amdgcn_sched_barrier(0)
; template <class Epi, class Sched, bool ALIGN_EPI = false, bool SP2 = false, bool FP8 = false>
; __device__ __forceinline__ void gemm_phase(PG8_LAS unsigned char* lds, const Gemm g, const Sched& S, const Epi& E) {
;     ...
;             const bool last = (t == nt - 2);
;             const char* a1 = cA + (size_t)(t + 1) * kstep;
;             const char* a2 = last ? nA : cA + (size_t)(t + 2) * kstep; const char* b2 = last ? nB : cB + (size_t)(t + 2) * kstep;
;             const char* a3 = a2 + kstep; const char* b3 = b2 + kstep;
;             if (last && has_next) S.a_ready(nxt);
;             if constexpr (SP2) {
;             PG8_LDB(B0, 0, 0); PG8_LDB(B1, 0, 1); PG8_SCHED; PG8_LDA(At, 0, 0); PG8_STAGE(PG8_SA(1, 1), a1 + hstep, voffA);
;             PG8_WAIT_V(8); PG8_WAIT_L(0); PG8_BAR; PG8_MMA(0, 0, At, B0); PG8_MMA(0, 1, At, B1); PG8_BAR; PG8_SCHED;
;             PG8_LDA(At, 0, 1); PG8_STAGE(PG8_SB(0, 0), b2, voffB); PG8_STAGE(PG8_SB(0, 1), b2 + hstep, voffB); PG8_STAGE(PG8_SA(0, 0), a2, voffA);
;             PG8_WAIT_V(8); PG8_WAIT_L(0); PG8_BAR; PG8_MMA(1, 0, At, B0); PG8_MMA(1, 1, At, B1); PG8_BAR; PG8_SCHED;
.LBB0_304:
	s_lshl_b32 s88, s64, 8
	s_lshl_b32 s0, s9, 8
	s_or_b32 s9, s0, s74
	s_add_i32 s88, s88, s73
	s_add_u32 s10, s10, 0x18080
	s_addc_u32 s11, s11, 0
	s_add_u32 s89, s62, 0x100
	s_addc_u32 s90, s63, 0
	s_mov_b32 s91, -2
	s_cmp_eq_u32 s100, 0
	s_cbranch_scc1 .Lmy_nobar_P3
	s_barrier
	s_mov_b32 s100, 0
.Lmy_nobar_P3:
	s_branch .LBB0_306
.LBB0_305:
	s_add_u32 s52, s10, 0xfffe8080
	s_addc_u32 s53, s11, -1
	s_and_b64 s[0:1], s[62:63], exec
	s_cselect_b32 s65, s5, s53
	s_cselect_b32 s64, s4, s52
	s_add_i32 s52, 0, 0x10000
	v_add_u32_e32 v128, s52, v152
	ds_read_b128 v[134:137], v128
	ds_read_b128 v[138:141], v128 offset:1024
	ds_read_b128 v[156:159], v128 offset:2048
	ds_read_b128 v[160:163], v128 offset:3072
	v_add_u32_e32 v128, s84, v152
	ds_read_b128 v[164:167], v128
	ds_read_b128 v[168:171], v128 offset:1024
	ds_read_b128 v[178:181], v128 offset:2048
	ds_read_b128 v[182:185], v128 offset:3072
	s_and_b64 s[0:1], s[62:63], exec
	s_cselect_b32 s63, s61, s90
	s_cselect_b32 s62, s60, s89
	v_mov_b32_e32 v128, v146
	ds_read_b128 v[186:189], v153
	ds_read_b128 v[190:193], v153 offset:1024
	ds_read_b128 v[198:201], v153 offset:2048
	ds_read_b128 v[202:205], v153 offset:3072
	ds_read_b128 v[206:209], v153 offset:4096
	ds_read_b128 v[210:213], v153 offset:5120
	ds_read_b128 v[214:217], v153 offset:6144
	ds_read_b128 v[218:221], v153 offset:7168
	s_add_i32 m0, s68, 0xc000
	s_nop 0
	global_load_lds_dwordx4 v128, s[10:11]
	v_mov_b32_e32 v128, v148
	s_add_i32 m0, s68, 0xe000
	s_nop 0
	global_load_lds_dwordx4 v128, s[10:11]
	s_waitcnt vmcnt(8)
	s_waitcnt lgkmcnt(0)
	s_barrier
	s_setprio 1
	s_waitcnt lgkmcnt(0)
	v_mfma_scale_f32_16x16x128_f8f6f4 v[112:115], v[134:141], v[186:193], v[112:115], v154, v154 op_sel_hi:[0,0,0]
	v_mfma_scale_f32_16x16x128_f8f6f4 v[116:119], v[156:163], v[186:193], v[116:119], v154, v154 op_sel_hi:[0,0,0]
	v_mfma_scale_f32_16x16x128_f8f6f4 v[96:99], v[134:141], v[198:205], v[96:99], v154, v154 op_sel_hi:[0,0,0]
	v_mfma_scale_f32_16x16x128_f8f6f4 v[100:103], v[156:163], v[198:205], v[100:103], v154, v154 op_sel_hi:[0,0,0]
	v_mfma_scale_f32_16x16x128_f8f6f4 v[142:145], v[134:141], v[206:213], v[80:83], v154, v154 op_sel_hi:[0,0,0]
	v_mfma_scale_f32_16x16x128_f8f6f4 v[172:175], v[156:163], v[206:213], v[84:87], v154, v154 op_sel_hi:[0,0,0]
	v_mfma_scale_f32_16x16x128_f8f6f4 v[194:197], v[134:141], v[214:221], v[64:67], v154, v154 op_sel_hi:[0,0,0]
	v_mfma_scale_f32_16x16x128_f8f6f4 v[222:225], v[156:163], v[214:221], v[68:71], v154, v154 op_sel_hi:[0,0,0]
	s_setprio 0
	s_setprio 1
	v_mfma_scale_f32_16x16x128_f8f6f4 v[120:123], v[164:171], v[186:193], v[120:123], v154, v154 op_sel_hi:[0,0,0]
	v_mfma_scale_f32_16x16x128_f8f6f4 v[124:127], v[178:185], v[186:193], v[124:127], v154, v154 op_sel_hi:[0,0,0]
	v_mfma_scale_f32_16x16x128_f8f6f4 v[104:107], v[164:171], v[198:205], v[104:107], v154, v154 op_sel_hi:[0,0,0]
	v_mfma_scale_f32_16x16x128_f8f6f4 v[108:111], v[178:185], v[198:205], v[108:111], v154, v154 op_sel_hi:[0,0,0]
	v_mfma_scale_f32_16x16x128_f8f6f4 v[186:189], v[164:171], v[206:213], v[88:91], v154, v154 op_sel_hi:[0,0,0]
	v_mfma_scale_f32_16x16x128_f8f6f4 v[190:193], v[178:185], v[206:213], v[92:95], v154, v154 op_sel_hi:[0,0,0]
	v_mfma_scale_f32_16x16x128_f8f6f4 v[198:201], v[164:171], v[214:221], v[72:75], v154, v154 op_sel_hi:[0,0,0]
	v_mfma_scale_f32_16x16x128_f8f6f4 v[202:205], v[178:185], v[214:221], v[76:79], v154, v154 op_sel_hi:[0,0,0]
	s_setprio 0
	s_barrier
	v_mov_b32_e32 v128, v147
	s_add_i32 s0, s52, s66
	ds_read_b128 v[64:67], v153 offset:16384
	ds_read_b128 v[68:71], v153 offset:17408
	ds_read_b128 v[72:75], v153 offset:18432
	ds_read_b128 v[76:79], v153 offset:19456
	ds_read_b128 v[80:83], v153 offset:20480
	ds_read_b128 v[84:87], v153 offset:21504
	ds_read_b128 v[88:91], v153 offset:22528
	ds_read_b128 v[92:95], v153 offset:23552
	s_mov_b32 m0, s0
	s_nop 0
	global_load_lds_dwordx4 v128, s[62:63]
	v_mov_b32_e32 v128, v149
	s_add_i32 m0, s0, 0x2000
	s_add_u32 s0, s62, 0x18000
	global_load_lds_dwordx4 v128, s[62:63]
	s_addc_u32 s1, s63, 0
	v_mov_b32_e32 v128, v147
	s_add_i32 s52, s84, s66
	s_mov_b32 m0, s52
	s_nop 0
	global_load_lds_dwordx4 v128, s[0:1]
	v_mov_b32_e32 v128, v149
	s_add_i32 m0, s52, 0x2000
	s_nop 0
	global_load_lds_dwordx4 v128, s[0:1]
	v_mov_b32_e32 v128, v146
	s_mov_b32 m0, s68
	s_nop 0
	global_load_lds_dwordx4 v128, s[64:65]
	v_mov_b32_e32 v128, v148
	s_mov_b32 m0, s69
	s_nop 0
	global_load_lds_dwordx4 v128, s[64:65]
	s_waitcnt vmcnt(8)
	s_waitcnt lgkmcnt(0)
	s_barrier
	s_setprio 1
	s_waitcnt lgkmcnt(0)
	v_mfma_scale_f32_16x16x128_f8f6f4 v[48:51], v[134:141], v[64:71], v[48:51], v154, v154 op_sel_hi:[0,0,0]
	v_mfma_scale_f32_16x16x128_f8f6f4 v[52:55], v[156:163], v[64:71], v[52:55], v154, v154 op_sel_hi:[0,0,0]
	v_mfma_scale_f32_16x16x128_f8f6f4 v[206:209], v[134:141], v[72:79], v[32:35], v154, v154 op_sel_hi:[0,0,0]
	v_mfma_scale_f32_16x16x128_f8f6f4 v[210:213], v[156:163], v[72:79], v[36:39], v154, v154 op_sel_hi:[0,0,0]
	v_mfma_scale_f32_16x16x128_f8f6f4 v[214:217], v[134:141], v[80:87], v[16:19], v154, v154 op_sel_hi:[0,0,0]
	v_mfma_scale_f32_16x16x128_f8f6f4 v[218:221], v[156:163], v[80:87], v[20:23], v154, v154 op_sel_hi:[0,0,0]
	v_mfma_scale_f32_16x16x128_f8f6f4 v[226:229], v[134:141], v[88:95], v[4:7], v154, v154 op_sel_hi:[0,0,0]
	v_mfma_scale_f32_16x16x128_f8f6f4 v[230:233], v[156:163], v[88:95], v[8:11], v154, v154 op_sel_hi:[0,0,0]
	s_setprio 0
	s_setprio 1
	v_mfma_scale_f32_16x16x128_f8f6f4 v[56:59], v[164:171], v[64:71], v[56:59], v154, v154 op_sel_hi:[0,0,0]
	v_mfma_scale_f32_16x16x128_f8f6f4 v[60:63], v[178:185], v[64:71], v[60:63], v154, v154 op_sel_hi:[0,0,0]
	v_mfma_scale_f32_16x16x128_f8f6f4 v[234:237], v[164:171], v[72:79], v[40:43], v154, v154 op_sel_hi:[0,0,0]
	v_mfma_scale_f32_16x16x128_f8f6f4 v[238:241], v[178:185], v[72:79], v[44:47], v154, v154 op_sel_hi:[0,0,0]
	v_mfma_scale_f32_16x16x128_f8f6f4 v[242:245], v[164:171], v[80:87], v[24:27], v154, v154 op_sel_hi:[0,0,0]
	v_mfma_scale_f32_16x16x128_f8f6f4 v[246:249], v[178:185], v[80:87], v[28:31], v154, v154 op_sel_hi:[0,0,0]
	v_mfma_scale_f32_16x16x128_f8f6f4 v[250:253], v[164:171], v[88:95], v[12:15], v154, v154 op_sel_hi:[0,0,0]
	v_mfma_scale_f32_16x16x128_f8f6f4 v[130:133], v[178:185], v[88:95], v[0:3], v154, v154 op_sel_hi:[0,0,0]
	s_setprio 0
	s_barrier
; #define PG8_STAGE(bufoff, gbase, voff) do { _Pragma("unroll") for (int _i = 0; _i < 2; ++_i) { unsigned vo_ = (voff)[_i]; if constexpr (FP8) asm volatile("" : "+v"(vo_)); \
;         __builtin_amdgcn_global_load_lds((const unsigned*)((const char*)(gbase) + vo_), (PG8_LAS unsigned*)(lds + (bufoff) + ldsw + _i * 8192), 16, 0, 0); } } while (0)
; #define PG8_LDA(dst, b, h) do { _Pragma("unroll") for (int m = 0; m < 4; ++m) _Pragma("unroll") for (int k = 0; k < 2; ++k) dst[m][k] = *(const PG8_LAS bf16x8*)(lds + PG8_SA(b, h) + aoff + m * 2048 + k * 1024); } while (0)
; #define PG8_LDB(dst, b, h) do { _Pragma("unroll") for (int n = 0; n < 2; ++n) _Pragma("unroll") for (int k = 0; k < 2; ++k) dst[n][k] = *(const PG8_LAS bf16x8*)(lds + PG8_SB(b, h) + boff + n * 2048 + k * 1024); } while (0)
; #define PG8_WAIT_V(n) asm volatile("s_waitcnt vmcnt(" #n ")" ::: "memory")
; #define PG8_WAIT_L(n) asm volatile("s_waitcnt lgkmcnt(" #n ")" ::: "memory")
; #define PG8_BAR __builtin_amdgcn_s_barrier()
; #define PG8_SCHED __builtin_amdgcn_sched_barrier(0)
; template <class Epi, class Sched, bool ALIGN_EPI = false, bool SP2 = false, bool FP8 = false>
; __device__ __forceinline__ void gemm_phase(PG8_LAS unsigned char* lds, const Gemm g, const Sched& S, const Epi& E) {
;     ...
;             PG8_LDB(B0, 1, 0); PG8_LDB(B1, 1, 1); PG8_SCHED; PG8_LDA(At, 1, 0); PG8_STAGE(PG8_SA(0, 1), a2 + hstep, voffA);
;             PG8_WAIT_V(8); PG8_WAIT_L(0); PG8_BAR; PG8_MMA(0, 0, At, B0); PG8_MMA(0, 1, At, B1); PG8_BAR; PG8_SCHED;
;             PG8_LDA(At, 1, 1); PG8_STAGE(PG8_SB(1, 0), b3, voffB); PG8_STAGE(PG8_SB(1, 1), b3 + hstep, voffB); PG8_STAGE(PG8_SA(1, 0), a3, voffA);
;             PG8_WAIT_V(8); PG8_WAIT_L(0); PG8_BAR; PG8_MMA(1, 0, At, B0); PG8_MMA(1, 1, At, B1); PG8_BAR; PG8_SCHED;
	s_add_i32 s52, 0, 0x18000
	s_add_i32 s53, 0, 0x1c000
	s_nop 1
	v_add_u32_e32 v12, s52, v152
	v_add_u32_e32 v16, s53, v152
	ds_read_b128 v[0:3], v12
	ds_read_b128 v[4:7], v12 offset:1024
	ds_read_b128 v[8:11], v12 offset:2048
	ds_read_b128 v[12:15], v12 offset:3072
	ds_read_b128 v[134:137], v16
	ds_read_b128 v[138:141], v16 offset:1024
	ds_read_b128 v[156:159], v16 offset:2048
	ds_read_b128 v[160:163], v16 offset:3072
	s_add_u32 s0, s64, 0x18000
	v_mov_b32_e32 v64, v146
	s_mov_b32 m0, s70
	ds_read_b128 v[16:19], v153 offset:32768
	ds_read_b128 v[20:23], v153 offset:33792
	ds_read_b128 v[24:27], v153 offset:34816
	ds_read_b128 v[28:31], v153 offset:35840
	ds_read_b128 v[32:35], v153 offset:36864
	ds_read_b128 v[36:39], v153 offset:37888
	ds_read_b128 v[40:43], v153 offset:38912
	ds_read_b128 v[44:47], v153 offset:39936
	s_addc_u32 s1, s65, 0
	s_nop 0
	global_load_lds_dwordx4 v64, s[0:1]
	v_mov_b32_e32 v64, v148
	s_mov_b32 m0, s71
	s_nop 0
	global_load_lds_dwordx4 v64, s[0:1]
	s_waitcnt vmcnt(8)
	s_waitcnt lgkmcnt(0)
	s_barrier
	s_setprio 1
	s_waitcnt lgkmcnt(0)
	v_mfma_scale_f32_16x16x128_f8f6f4 v[112:115], v[0:7], v[16:23], v[112:115], v154, v154 op_sel_hi:[0,0,0]
	v_mfma_scale_f32_16x16x128_f8f6f4 v[116:119], v[8:15], v[16:23], v[116:119], v154, v154 op_sel_hi:[0,0,0]
	v_mfma_scale_f32_16x16x128_f8f6f4 v[96:99], v[0:7], v[24:31], v[96:99], v154, v154 op_sel_hi:[0,0,0]
	v_mfma_scale_f32_16x16x128_f8f6f4 v[100:103], v[8:15], v[24:31], v[100:103], v154, v154 op_sel_hi:[0,0,0]
	v_mfma_scale_f32_16x16x128_f8f6f4 v[80:83], v[0:7], v[32:39], v[142:145], v154, v154 op_sel_hi:[0,0,0]
	v_mfma_scale_f32_16x16x128_f8f6f4 v[84:87], v[8:15], v[32:39], v[172:175], v154, v154 op_sel_hi:[0,0,0]
	v_mfma_scale_f32_16x16x128_f8f6f4 v[64:67], v[0:7], v[40:47], v[194:197], v154, v154 op_sel_hi:[0,0,0]
	v_mfma_scale_f32_16x16x128_f8f6f4 v[68:71], v[8:15], v[40:47], v[222:225], v154, v154 op_sel_hi:[0,0,0]
	s_setprio 0
	s_setprio 1
	v_mfma_scale_f32_16x16x128_f8f6f4 v[120:123], v[134:141], v[16:23], v[120:123], v154, v154 op_sel_hi:[0,0,0]
	v_mfma_scale_f32_16x16x128_f8f6f4 v[124:127], v[156:163], v[16:23], v[124:127], v154, v154 op_sel_hi:[0,0,0]
	v_mfma_scale_f32_16x16x128_f8f6f4 v[104:107], v[134:141], v[24:31], v[104:107], v154, v154 op_sel_hi:[0,0,0]
	v_mfma_scale_f32_16x16x128_f8f6f4 v[108:111], v[156:163], v[24:31], v[108:111], v154, v154 op_sel_hi:[0,0,0]
	v_mfma_scale_f32_16x16x128_f8f6f4 v[88:91], v[134:141], v[32:39], v[186:189], v154, v154 op_sel_hi:[0,0,0]
	v_mfma_scale_f32_16x16x128_f8f6f4 v[92:95], v[156:163], v[32:39], v[190:193], v154, v154 op_sel_hi:[0,0,0]
	v_mfma_scale_f32_16x16x128_f8f6f4 v[72:75], v[134:141], v[40:47], v[198:201], v154, v154 op_sel_hi:[0,0,0]
	v_mfma_scale_f32_16x16x128_f8f6f4 v[76:79], v[156:163], v[40:47], v[202:205], v154, v154 op_sel_hi:[0,0,0]
	s_setprio 0
	s_barrier
	v_mov_b32_e32 v128, v147
	ds_read_b128 v[24:27], v153 offset:49152
	ds_read_b128 v[28:31], v153 offset:50176
	ds_read_b128 v[164:167], v153 offset:51200
	ds_read_b128 v[168:171], v153 offset:52224
	ds_read_b128 v[178:181], v153 offset:53248
	ds_read_b128 v[182:185], v153 offset:54272
	ds_read_b128 v[186:189], v153 offset:55296
	ds_read_b128 v[190:193], v153 offset:56320
	s_add_i32 s0, s52, s66
	v_lshl_add_u64 v[16:17], s[62:63], 0, v[128:129]
	v_lshl_add_u64 v[16:17], v[16:17], 0, s[40:41]
	s_mov_b32 m0, s0
	v_mov_b32_e32 v128, v149
	global_load_lds_dwordx4 v[16:17], off
	s_add_i32 m0, s0, 0x2000
	v_lshl_add_u64 v[16:17], s[62:63], 0, v[128:129]
	v_lshl_add_u64 v[16:17], v[16:17], 0, s[40:41]
	s_add_u32 s0, s62, 0x18080
	global_load_lds_dwordx4 v[16:17], off
	s_addc_u32 s1, s63, 0
	v_mov_b32_e32 v16, v147
	s_add_i32 s52, s53, s66
	s_mov_b32 m0, s52
	v_mov_b32_e32 v128, v146
	global_load_lds_dwordx4 v16, s[0:1]
	v_mov_b32_e32 v16, v149
	s_add_i32 m0, s52, 0x2000
	s_nop 0
	global_load_lds_dwordx4 v16, s[0:1]
	s_mov_b32 m0, s75
	v_lshl_add_u64 v[16:17], s[64:65], 0, v[128:129]
	v_lshl_add_u64 v[16:17], v[16:17], 0, s[40:41]
	v_mov_b32_e32 v128, v148
	global_load_lds_dwordx4 v[16:17], off
	s_mov_b32 m0, s77
	v_lshl_add_u64 v[16:17], s[64:65], 0, v[128:129]
	v_lshl_add_u64 v[16:17], v[16:17], 0, s[40:41]
	global_load_lds_dwordx4 v[16:17], off
	s_waitcnt vmcnt(8)
	s_waitcnt lgkmcnt(0)
	s_barrier
	s_setprio 1
	s_waitcnt lgkmcnt(0)
	v_mfma_scale_f32_16x16x128_f8f6f4 v[48:51], v[0:7], v[24:31], v[48:51], v154, v154 op_sel_hi:[0,0,0]
	v_mfma_scale_f32_16x16x128_f8f6f4 v[52:55], v[8:15], v[24:31], v[52:55], v154, v154 op_sel_hi:[0,0,0]
	v_mfma_scale_f32_16x16x128_f8f6f4 v[32:35], v[0:7], v[164:171], v[206:209], v154, v154 op_sel_hi:[0,0,0]
	v_mfma_scale_f32_16x16x128_f8f6f4 v[36:39], v[8:15], v[164:171], v[210:213], v154, v154 op_sel_hi:[0,0,0]
	v_mfma_scale_f32_16x16x128_f8f6f4 v[16:19], v[0:7], v[178:185], v[214:217], v154, v154 op_sel_hi:[0,0,0]
	v_mfma_scale_f32_16x16x128_f8f6f4 v[20:23], v[8:15], v[178:185], v[218:221], v154, v154 op_sel_hi:[0,0,0]
	v_mfma_scale_f32_16x16x128_f8f6f4 v[4:7], v[0:7], v[186:193], v[226:229], v154, v154 op_sel_hi:[0,0,0]
	v_mfma_scale_f32_16x16x128_f8f6f4 v[8:11], v[8:15], v[186:193], v[230:233], v154, v154 op_sel_hi:[0,0,0]
	s_setprio 0
	s_setprio 1
	v_mfma_scale_f32_16x16x128_f8f6f4 v[56:59], v[134:141], v[24:31], v[56:59], v154, v154 op_sel_hi:[0,0,0]
	v_mfma_scale_f32_16x16x128_f8f6f4 v[60:63], v[156:163], v[24:31], v[60:63], v154, v154 op_sel_hi:[0,0,0]
	v_mfma_scale_f32_16x16x128_f8f6f4 v[40:43], v[134:141], v[164:171], v[234:237], v154, v154 op_sel_hi:[0,0,0]
	v_mfma_scale_f32_16x16x128_f8f6f4 v[44:47], v[156:163], v[164:171], v[238:241], v154, v154 op_sel_hi:[0,0,0]
	v_mfma_scale_f32_16x16x128_f8f6f4 v[24:27], v[134:141], v[178:185], v[242:245], v154, v154 op_sel_hi:[0,0,0]
	v_mfma_scale_f32_16x16x128_f8f6f4 v[28:31], v[156:163], v[178:185], v[246:249], v154, v154 op_sel_hi:[0,0,0]
	v_mfma_scale_f32_16x16x128_f8f6f4 v[12:15], v[134:141], v[186:193], v[250:253], v154, v154 op_sel_hi:[0,0,0]
	v_mfma_scale_f32_16x16x128_f8f6f4 v[0:3], v[156:163], v[186:193], v[130:133], v154, v154 op_sel_hi:[0,0,0]
	s_setprio 0
	s_barrier
	s_add_i32 s91, s91, 2
	s_add_u32 s10, s10, 0x100
	s_addc_u32 s11, s11, 0
	s_add_u32 s89, s89, 0x100
	s_addc_u32 s90, s90, 0
	s_cmp_gt_u32 s91, 3
	s_cbranch_scc1 .LBB0_308

; __device__ __forceinline__ unsigned pk4_fp8g(float a, float b, float c, float d) { int r = __builtin_amdgcn_cvt_pk_fp8_f32(a, b, 0, false); r = __builtin_amdgcn_cvt_pk_fp8_f32(c, d, r, true); return (unsigned)r; }
; #define G2B(bw, sh) (fmaxf((float)(((bw) >> (sh)) & 0xffu), 0.5f) * (1.f / 2040.f))
;     __device__ __forceinline__ void operator()(const f32x4 (&acc)[2][2][4][2], const Unit& u, int wr, int wc, int fr, int fq) const {
;         asm volatile("" : "+v"(fr), "+v"(fq));
;         const int row0 = u.pm * BM + wr * 64 + fr, col0 = u.pn * BM + wc * 32 + 8 * fq;
; #pragma unroll
;         for (int ai = 0; ai < 2; ++ai)
; #pragma unroll
;             for (int m = 0; m < 4; ++m) { const size_t r = (size_t)(row0 + ai * HALF + m * 16);
; #pragma unroll
;                 for (int bj = 0; bj < 2; ++bj) {
;                     const u32x2g b = *(const u32x2g*)(Gt + r * GC + DM + col0 + bj * HALF);
;                     f32x4 v0 = acc[ai][bj][m][0], v1 = acc[ai][bj][m][1];
;     ...
;                     v0[0] *= G2B(b.x, 0); v0[1] *= G2B(b.x, 8); v0[2] *= G2B(b.x, 16); v0[3] *= G2B(b.x, 24);
;                     v1[0] *= G2B(b.y, 0); v1[1] *= G2B(b.y, 8); v1[2] *= G2B(b.y, 16); v1[3] *= G2B(b.y, 24);
;     ...
;                     u32x2g w; w.x = pk4_fp8g(v0[0], v0[1], v0[2], v0[3]); w.y = pk4_fp8g(v1[0], v1[1], v1[2], v1[3]);
;                     *(u32x2g*)((unsigned char*)O + r * DM + col0 + bj * HALF) = w; }
;                 asm volatile("" ::: "memory"); }
.LBB0_310:
	v_mov_b32_e32 v128, v151
	v_mov_b32_e32 v130, v150
	v_mov_b32_e32 v138, v129
	v_add_u32_e32 v136, s88, v130
	v_ashrrev_i32_e32 v137, 31, v136
	v_lshl_add_u32 v134, v128, 3, s9
	v_lshlrev_b64 v[130:131], 11, v[136:137]
	v_ashrrev_i32_e32 v135, 31, v134
	v_lshl_add_u64 v[130:131], s[42:43], 0, v[130:131]
	v_lshl_add_u64 v[130:131], v[130:131], 0, v[134:135]
	global_load_dwordx2 v[132:133], v[130:131], off offset:1024
	s_nop 0
	global_load_dwordx2 v[130:131], v[130:131], off offset:1152
	v_lshlrev_b64 v[144:145], 10, v[136:137]
	v_mov_b32_e32 v139, v129
	v_mov_b32_e32 v140, v129
	v_mov_b32_e32 v141, v129
	v_add_u32_e32 v142, 16, v136
	v_ashrrev_i32_e32 v143, 31, v142
	v_lshl_add_u64 v[144:145], s[28:29], 0, v[144:145]
	v_lshlrev_b64 v[156:157], 11, v[142:143]
	v_lshl_add_u64 v[144:145], v[144:145], 0, v[134:135]
	s_and_b64 vcc, exec, s[2:3]
	s_mov_b64 s[2:3], -1
	s_waitcnt vmcnt(0)
	v_cvt_f32_ubyte0_e32 v128, v132
	v_cvt_f32_ubyte1_e32 v137, v132
	v_cvt_f32_ubyte0_e32 v158, v133
	v_cvt_f32_ubyte1_e32 v159, v133
	v_cvt_f32_ubyte0_e32 v161, v130
	v_cvt_f32_ubyte1_e32 v162, v130
	v_cvt_f32_ubyte0_e32 v164, v131
	v_cvt_f32_ubyte1_e32 v165, v131
	v_max_f32_e32 v128, 0.5, v128
	v_max_f32_e32 v137, 0.5, v137
	v_max_f32_e32 v158, 0.5, v158
	v_max_f32_e32 v159, 0.5, v159
	v_max_f32_e32 v161, 0.5, v161
	v_max_f32_e32 v162, 0.5, v162
	v_max_f32_e32 v164, 0.5, v164
	v_max_f32_e32 v165, 0.5, v165
	v_mul_f32_e32 v128, 0x3a008081, v128
	v_mul_f32_e32 v137, 0x3a008081, v137
	v_mul_f32_e32 v158, 0x3a008081, v158
	v_mul_f32_e32 v159, 0x3a008081, v159
	v_mul_f32_e32 v161, 0x3a008081, v161
	v_mul_f32_e32 v162, 0x3a008081, v162
	v_mul_f32_e32 v164, 0x3a008081, v164
	v_mul_f32_e32 v165, 0x3a008081, v165
	v_mul_f32_e32 v112, v112, v128
	v_mul_f32_e32 v113, v113, v137
	v_mul_f32_e32 v116, v116, v158
	v_mul_f32_e32 v117, v117, v159
	v_cvt_f32_ubyte2_e32 v155, v132
	v_cvt_f32_ubyte3_e32 v132, v132
	v_cvt_f32_ubyte2_e32 v160, v133
	v_cvt_f32_ubyte3_e32 v133, v133
	v_mul_f32_e32 v120, v120, v161
	v_mul_f32_e32 v121, v121, v162
	v_mul_f32_e32 v124, v124, v164
	v_mul_f32_e32 v125, v125, v165
	v_cvt_pk_fp8_f32 v138, v112, v113
	v_cvt_pk_fp8_f32 v139, v116, v117
	v_cvt_f32_ubyte2_e32 v163, v130
	v_cvt_f32_ubyte3_e32 v130, v130
	v_cvt_f32_ubyte2_e32 v166, v131
	v_cvt_f32_ubyte3_e32 v131, v131
	v_max_f32_e32 v155, 0.5, v155
	v_max_f32_e32 v132, 0.5, v132
	v_max_f32_e32 v160, 0.5, v160
	v_max_f32_e32 v133, 0.5, v133
	v_cvt_pk_fp8_f32 v140, v120, v121
	v_cvt_pk_fp8_f32 v141, v124, v125
	v_max_f32_e32 v163, 0.5, v163
	v_max_f32_e32 v130, 0.5, v130
	v_max_f32_e32 v166, 0.5, v166
	v_max_f32_e32 v131, 0.5, v131
	v_mul_f32_e32 v155, 0x3a008081, v155
	v_mul_f32_e32 v132, 0x3a008081, v132
	v_mul_f32_e32 v160, 0x3a008081, v160
	v_mul_f32_e32 v133, 0x3a008081, v133
	v_mul_f32_e32 v163, 0x3a008081, v163
	v_mul_f32_e32 v130, 0x3a008081, v130
	v_mul_f32_e32 v166, 0x3a008081, v166
	v_mul_f32_e32 v131, 0x3a008081, v131
	v_mul_f32_e32 v114, v114, v155
	v_mul_f32_e32 v115, v115, v132
	v_mul_f32_e32 v118, v118, v160
	v_mul_f32_e32 v119, v119, v133
	v_mul_f32_e32 v122, v122, v163
	v_mul_f32_e32 v123, v123, v130
	v_mul_f32_e32 v126, v126, v166
	v_mul_f32_e32 v127, v127, v131
	v_cvt_pk_fp8_f32 v138, v114, v115 op_sel:[0,0,1]
	v_cvt_pk_fp8_f32 v139, v118, v119 op_sel:[0,0,1]
	v_cvt_pk_fp8_f32 v140, v122, v123 op_sel:[0,0,1]
	v_cvt_pk_fp8_f32 v141, v126, v127 op_sel:[0,0,1]
	v_lshl_add_u64 v[112:113], s[42:43], 0, v[156:157]
	global_store_dwordx2 v[144:145], v[138:139], off
	global_store_dwordx2 v[144:145], v[140:141], off offset:128
	v_lshl_add_u64 v[112:113], v[112:113], 0, v[134:135]
	global_load_dwordx2 v[114:115], v[112:113], off offset:1024
	s_nop 0
	global_load_dwordx2 v[112:113], v[112:113], off offset:1152
	v_mov_b32_e32 v116, v129
	v_mov_b32_e32 v117, v129
	v_mov_b32_e32 v118, v129
	v_mov_b32_e32 v119, v129
	v_add_u32_e32 v120, 32, v136
	v_lshlrev_b64 v[122:123], 10, v[142:143]
	v_ashrrev_i32_e32 v121, 31, v120
	v_lshl_add_u64 v[122:123], s[28:29], 0, v[122:123]
	v_lshlrev_b64 v[124:125], 11, v[120:121]
	v_lshl_add_u64 v[124:125], s[42:43], 0, v[124:125]
	s_waitcnt vmcnt(1)
	v_cvt_f32_ubyte0_e32 v126, v114
	v_cvt_f32_ubyte1_e32 v127, v114
	v_cvt_f32_ubyte0_e32 v130, v115
	v_cvt_f32_ubyte1_e32 v131, v115
	s_waitcnt vmcnt(0)
; __device__ __forceinline__ unsigned pk4_fp8g(float a, float b, float c, float d) { int r = __builtin_amdgcn_cvt_pk_fp8_f32(a, b, 0, false); r = __builtin_amdgcn_cvt_pk_fp8_f32(c, d, r, true); return (unsigned)r; }
; #define G2B(bw, sh) (fmaxf((float)(((bw) >> (sh)) & 0xffu), 0.5f) * (1.f / 2040.f))
;     __device__ __forceinline__ void operator()(const f32x4 (&acc)[2][2][4][2], const Unit& u, int wr, int wc, int fr, int fq) const {
;     ...
;             for (int m = 0; m < 4; ++m) { const size_t r = (size_t)(row0 + ai * HALF + m * 16);
; #pragma unroll
;                 for (int bj = 0; bj < 2; ++bj) {
;                     const u32x2g b = *(const u32x2g*)(Gt + r * GC + DM + col0 + bj * HALF);
;                     f32x4 v0 = acc[ai][bj][m][0], v1 = acc[ai][bj][m][1];
;     ...
;                     v0[0] *= G2B(b.x, 0); v0[1] *= G2B(b.x, 8); v0[2] *= G2B(b.x, 16); v0[3] *= G2B(b.x, 24);
;                     v1[0] *= G2B(b.y, 0); v1[1] *= G2B(b.y, 8); v1[2] *= G2B(b.y, 16); v1[3] *= G2B(b.y, 24);
;     ...
;                     u32x2g w; w.x = pk4_fp8g(v0[0], v0[1], v0[2], v0[3]); w.y = pk4_fp8g(v1[0], v1[1], v1[2], v1[3]);
;                     *(u32x2g*)((unsigned char*)O + r * DM + col0 + bj * HALF) = w; }
	v_cvt_f32_ubyte0_e32 v133, v112
	v_cvt_f32_ubyte1_e32 v137, v112
	v_cvt_f32_ubyte0_e32 v139, v113
	v_cvt_f32_ubyte1_e32 v140, v113
	v_max_f32_e32 v126, 0.5, v126
	v_max_f32_e32 v127, 0.5, v127
	v_max_f32_e32 v130, 0.5, v130
	v_max_f32_e32 v131, 0.5, v131
	v_max_f32_e32 v133, 0.5, v133
	v_max_f32_e32 v137, 0.5, v137
	v_max_f32_e32 v139, 0.5, v139
	v_max_f32_e32 v140, 0.5, v140
	v_mul_f32_e32 v126, 0x3a008081, v126
	v_mul_f32_e32 v127, 0x3a008081, v127
	v_mul_f32_e32 v130, 0x3a008081, v130
	v_mul_f32_e32 v131, 0x3a008081, v131
	v_mul_f32_e32 v133, 0x3a008081, v133
	v_mul_f32_e32 v137, 0x3a008081, v137
	v_mul_f32_e32 v139, 0x3a008081, v139
	v_mul_f32_e32 v140, 0x3a008081, v140
	v_mul_f32_e32 v96, v96, v126
	v_mul_f32_e32 v97, v97, v127
	v_mul_f32_e32 v100, v100, v130
	v_mul_f32_e32 v101, v101, v131
	v_cvt_f32_ubyte2_e32 v128, v114
	v_cvt_f32_ubyte3_e32 v114, v114
	v_cvt_f32_ubyte2_e32 v132, v115
	v_cvt_f32_ubyte3_e32 v115, v115
	v_mul_f32_e32 v104, v104, v133
	v_mul_f32_e32 v105, v105, v137
	v_mul_f32_e32 v108, v108, v139
	v_mul_f32_e32 v109, v109, v140
	v_cvt_pk_fp8_f32 v116, v96, v97
	v_cvt_pk_fp8_f32 v117, v100, v101
	v_cvt_f32_ubyte2_e32 v138, v112
	v_cvt_f32_ubyte3_e32 v112, v112
	v_cvt_f32_ubyte2_e32 v141, v113
	v_cvt_f32_ubyte3_e32 v113, v113
	v_max_f32_e32 v128, 0.5, v128
	v_max_f32_e32 v114, 0.5, v114
	v_max_f32_e32 v132, 0.5, v132
	v_max_f32_e32 v115, 0.5, v115
	v_cvt_pk_fp8_f32 v118, v104, v105
	v_cvt_pk_fp8_f32 v119, v108, v109
	v_max_f32_e32 v138, 0.5, v138
	v_max_f32_e32 v112, 0.5, v112
	v_max_f32_e32 v141, 0.5, v141
	v_max_f32_e32 v113, 0.5, v113
	v_mul_f32_e32 v128, 0x3a008081, v128
	v_mul_f32_e32 v114, 0x3a008081, v114
	v_mul_f32_e32 v132, 0x3a008081, v132
	v_mul_f32_e32 v115, 0x3a008081, v115
	v_mul_f32_e32 v138, 0x3a008081, v138
	v_mul_f32_e32 v112, 0x3a008081, v112
	v_mul_f32_e32 v141, 0x3a008081, v141
	v_mul_f32_e32 v113, 0x3a008081, v113
	v_mul_f32_e32 v98, v98, v128
	v_mul_f32_e32 v99, v99, v114
	v_mul_f32_e32 v102, v102, v132
	v_mul_f32_e32 v103, v103, v115
	v_mul_f32_e32 v106, v106, v138
	v_mul_f32_e32 v107, v107, v112
	v_mul_f32_e32 v110, v110, v141
	v_mul_f32_e32 v111, v111, v113
	v_cvt_pk_fp8_f32 v116, v98, v99 op_sel:[0,0,1]
	v_cvt_pk_fp8_f32 v117, v102, v103 op_sel:[0,0,1]
	v_cvt_pk_fp8_f32 v118, v106, v107 op_sel:[0,0,1]
	v_cvt_pk_fp8_f32 v119, v110, v111 op_sel:[0,0,1]
	v_lshl_add_u64 v[96:97], v[122:123], 0, v[134:135]
	global_store_dwordx2 v[96:97], v[116:117], off
	global_store_dwordx2 v[96:97], v[118:119], off offset:128
	v_lshl_add_u64 v[98:99], v[124:125], 0, v[134:135]
	global_load_dwordx2 v[96:97], v[98:99], off offset:1024
	s_nop 0
	global_load_dwordx2 v[98:99], v[98:99], off offset:1152
	v_lshlrev_b64 v[106:107], 10, v[120:121]
	v_mov_b32_e32 v100, v129
	v_mov_b32_e32 v101, v129
	v_mov_b32_e32 v102, v129
	v_mov_b32_e32 v103, v129
	v_add_u32_e32 v104, 48, v136
	v_ashrrev_i32_e32 v105, 31, v104
	v_lshl_add_u64 v[106:107], s[28:29], 0, v[106:107]
	v_lshlrev_b64 v[108:109], 11, v[104:105]
	v_lshl_add_u64 v[108:109], s[42:43], 0, v[108:109]
	s_waitcnt vmcnt(1)
	v_cvt_f32_ubyte0_e32 v110, v96
	v_cvt_f32_ubyte1_e32 v111, v96
	v_cvt_f32_ubyte0_e32 v113, v97
	v_cvt_f32_ubyte1_e32 v114, v97
	s_waitcnt vmcnt(0)
	v_cvt_f32_ubyte0_e32 v116, v98
	v_cvt_f32_ubyte1_e32 v117, v98
	v_cvt_f32_ubyte0_e32 v119, v99
	v_cvt_f32_ubyte1_e32 v120, v99
	v_max_f32_e32 v110, 0.5, v110
	v_max_f32_e32 v111, 0.5, v111
	v_max_f32_e32 v113, 0.5, v113
	v_max_f32_e32 v114, 0.5, v114
	v_max_f32_e32 v116, 0.5, v116
	v_max_f32_e32 v117, 0.5, v117
	v_max_f32_e32 v119, 0.5, v119
	v_max_f32_e32 v120, 0.5, v120
	v_mul_f32_e32 v110, 0x3a008081, v110
	v_mul_f32_e32 v111, 0x3a008081, v111
	v_mul_f32_e32 v113, 0x3a008081, v113
	v_mul_f32_e32 v114, 0x3a008081, v114
	v_mul_f32_e32 v116, 0x3a008081, v116
	v_mul_f32_e32 v117, 0x3a008081, v117
	v_mul_f32_e32 v119, 0x3a008081, v119
	v_mul_f32_e32 v120, 0x3a008081, v120
	v_mul_f32_e32 v80, v80, v110
	v_mul_f32_e32 v81, v81, v111
	v_mul_f32_e32 v84, v84, v113
	v_mul_f32_e32 v85, v85, v114
	v_cvt_f32_ubyte2_e32 v112, v96
	v_cvt_f32_ubyte3_e32 v96, v96
	v_cvt_f32_ubyte2_e32 v115, v97
	v_cvt_f32_ubyte3_e32 v97, v97
	v_mul_f32_e32 v88, v88, v116
	v_mul_f32_e32 v89, v89, v117
	v_mul_f32_e32 v92, v92, v119
	v_mul_f32_e32 v93, v93, v120
	v_cvt_pk_fp8_f32 v100, v80, v81
	v_cvt_pk_fp8_f32 v101, v84, v85
	v_cvt_f32_ubyte2_e32 v118, v98
	v_cvt_f32_ubyte3_e32 v98, v98
	v_cvt_f32_ubyte2_e32 v121, v99
	v_cvt_f32_ubyte3_e32 v99, v99
	v_max_f32_e32 v112, 0.5, v112
	v_max_f32_e32 v96, 0.5, v96
	v_max_f32_e32 v115, 0.5, v115
	v_max_f32_e32 v97, 0.5, v97
	v_cvt_pk_fp8_f32 v102, v88, v89
	v_cvt_pk_fp8_f32 v103, v92, v93
	v_max_f32_e32 v118, 0.5, v118
	v_max_f32_e32 v98, 0.5, v98
	v_max_f32_e32 v121, 0.5, v121
	v_max_f32_e32 v99, 0.5, v99
	v_mul_f32_e32 v112, 0x3a008081, v112
	v_mul_f32_e32 v96, 0x3a008081, v96
	v_mul_f32_e32 v115, 0x3a008081, v115
	v_mul_f32_e32 v97, 0x3a008081, v97
	v_mul_f32_e32 v118, 0x3a008081, v118
	v_mul_f32_e32 v98, 0x3a008081, v98
	v_mul_f32_e32 v121, 0x3a008081, v121
	v_mul_f32_e32 v99, 0x3a008081, v99
	v_mul_f32_e32 v82, v82, v112
	v_mul_f32_e32 v83, v83, v96
	v_mul_f32_e32 v86, v86, v115
	v_mul_f32_e32 v87, v87, v97
	v_mul_f32_e32 v90, v90, v118
	v_mul_f32_e32 v91, v91, v98
	v_mul_f32_e32 v94, v94, v121
	v_mul_f32_e32 v95, v95, v99
	v_cvt_pk_fp8_f32 v100, v82, v83 op_sel:[0,0,1]
	v_cvt_pk_fp8_f32 v101, v86, v87 op_sel:[0,0,1]
	v_cvt_pk_fp8_f32 v102, v90, v91 op_sel:[0,0,1]
	v_cvt_pk_fp8_f32 v103, v94, v95 op_sel:[0,0,1]
	v_lshl_add_u64 v[80:81], v[106:107], 0, v[134:135]
	global_store_dwordx2 v[80:81], v[100:101], off
	global_store_dwordx2 v[80:81], v[102:103], off offset:128
	v_lshl_add_u64 v[82:83], v[108:109], 0, v[134:135]
	global_load_dwordx2 v[80:81], v[82:83], off offset:1024
	s_nop 0
	global_load_dwordx2 v[82:83], v[82:83], off offset:1152
	v_lshlrev_b64 v[90:91], 10, v[104:105]
	v_mov_b32_e32 v84, v129
	v_mov_b32_e32 v85, v129
	v_mov_b32_e32 v86, v129
	v_mov_b32_e32 v87, v129
	v_add_u32_e32 v88, 0x80, v136
	v_ashrrev_i32_e32 v89, 31, v88
	v_lshl_add_u64 v[90:91], s[28:29], 0, v[90:91]
	v_lshlrev_b64 v[92:93], 11, v[88:89]
	v_lshl_add_u64 v[92:93], s[42:43], 0, v[92:93]
	s_waitcnt vmcnt(1)
; __device__ __forceinline__ unsigned pk4_fp8g(float a, float b, float c, float d) { int r = __builtin_amdgcn_cvt_pk_fp8_f32(a, b, 0, false); r = __builtin_amdgcn_cvt_pk_fp8_f32(c, d, r, true); return (unsigned)r; }
; #define G2B(bw, sh) (fmaxf((float)(((bw) >> (sh)) & 0xffu), 0.5f) * (1.f / 2040.f))
;     __device__ __forceinline__ void operator()(const f32x4 (&acc)[2][2][4][2], const Unit& u, int wr, int wc, int fr, int fq) const {
;     ...
;             for (int m = 0; m < 4; ++m) { const size_t r = (size_t)(row0 + ai * HALF + m * 16);
; #pragma unroll
;                 for (int bj = 0; bj < 2; ++bj) {
;                     const u32x2g b = *(const u32x2g*)(Gt + r * GC + DM + col0 + bj * HALF);
;                     f32x4 v0 = acc[ai][bj][m][0], v1 = acc[ai][bj][m][1];
;     ...
;                     v0[0] *= G2B(b.x, 0); v0[1] *= G2B(b.x, 8); v0[2] *= G2B(b.x, 16); v0[3] *= G2B(b.x, 24);
;                     v1[0] *= G2B(b.y, 0); v1[1] *= G2B(b.y, 8); v1[2] *= G2B(b.y, 16); v1[3] *= G2B(b.y, 24);
;     ...
;                     u32x2g w; w.x = pk4_fp8g(v0[0], v0[1], v0[2], v0[3]); w.y = pk4_fp8g(v1[0], v1[1], v1[2], v1[3]);
;                     *(u32x2g*)((unsigned char*)O + r * DM + col0 + bj * HALF) = w; }
	v_cvt_f32_ubyte0_e32 v94, v80
	v_cvt_f32_ubyte1_e32 v95, v80
	v_cvt_f32_ubyte0_e32 v97, v81
	v_cvt_f32_ubyte1_e32 v98, v81
	s_waitcnt vmcnt(0)
	v_cvt_f32_ubyte0_e32 v100, v82
	v_cvt_f32_ubyte1_e32 v101, v82
	v_cvt_f32_ubyte0_e32 v103, v83
	v_cvt_f32_ubyte1_e32 v104, v83
	v_max_f32_e32 v94, 0.5, v94
	v_max_f32_e32 v95, 0.5, v95
	v_max_f32_e32 v97, 0.5, v97
	v_max_f32_e32 v98, 0.5, v98
	v_max_f32_e32 v100, 0.5, v100
	v_max_f32_e32 v101, 0.5, v101
	v_max_f32_e32 v103, 0.5, v103
	v_max_f32_e32 v104, 0.5, v104
	v_mul_f32_e32 v94, 0x3a008081, v94
	v_mul_f32_e32 v95, 0x3a008081, v95
	v_mul_f32_e32 v97, 0x3a008081, v97
	v_mul_f32_e32 v98, 0x3a008081, v98
	v_mul_f32_e32 v100, 0x3a008081, v100
	v_mul_f32_e32 v101, 0x3a008081, v101
	v_mul_f32_e32 v103, 0x3a008081, v103
	v_mul_f32_e32 v104, 0x3a008081, v104
	v_mul_f32_e32 v64, v64, v94
	v_mul_f32_e32 v65, v65, v95
	v_mul_f32_e32 v68, v68, v97
	v_mul_f32_e32 v69, v69, v98
	v_cvt_f32_ubyte2_e32 v96, v80
	v_cvt_f32_ubyte3_e32 v80, v80
	v_cvt_f32_ubyte2_e32 v99, v81
	v_cvt_f32_ubyte3_e32 v81, v81
	v_mul_f32_e32 v72, v72, v100
	v_mul_f32_e32 v73, v73, v101
	v_mul_f32_e32 v76, v76, v103
	v_mul_f32_e32 v77, v77, v104
	v_cvt_pk_fp8_f32 v84, v64, v65
	v_cvt_pk_fp8_f32 v85, v68, v69
	v_cvt_f32_ubyte2_e32 v102, v82
	v_cvt_f32_ubyte3_e32 v82, v82
	v_cvt_f32_ubyte2_e32 v105, v83
	v_cvt_f32_ubyte3_e32 v83, v83
	v_max_f32_e32 v96, 0.5, v96
	v_max_f32_e32 v80, 0.5, v80
	v_max_f32_e32 v99, 0.5, v99
	v_max_f32_e32 v81, 0.5, v81
	v_cvt_pk_fp8_f32 v86, v72, v73
	v_cvt_pk_fp8_f32 v87, v76, v77
	v_max_f32_e32 v102, 0.5, v102
	v_max_f32_e32 v82, 0.5, v82
	v_max_f32_e32 v105, 0.5, v105
	v_max_f32_e32 v83, 0.5, v83
	v_mul_f32_e32 v96, 0x3a008081, v96
	v_mul_f32_e32 v80, 0x3a008081, v80
	v_mul_f32_e32 v99, 0x3a008081, v99
	v_mul_f32_e32 v81, 0x3a008081, v81
	v_mul_f32_e32 v102, 0x3a008081, v102
	v_mul_f32_e32 v82, 0x3a008081, v82
	v_mul_f32_e32 v105, 0x3a008081, v105
	v_mul_f32_e32 v83, 0x3a008081, v83
	v_mul_f32_e32 v66, v66, v96
	v_mul_f32_e32 v67, v67, v80
	v_mul_f32_e32 v70, v70, v99
	v_mul_f32_e32 v71, v71, v81
	v_mul_f32_e32 v74, v74, v102
	v_mul_f32_e32 v75, v75, v82
	v_mul_f32_e32 v78, v78, v105
	v_mul_f32_e32 v79, v79, v83
	v_cvt_pk_fp8_f32 v84, v66, v67 op_sel:[0,0,1]
	v_cvt_pk_fp8_f32 v85, v70, v71 op_sel:[0,0,1]
	v_cvt_pk_fp8_f32 v86, v74, v75 op_sel:[0,0,1]
	v_cvt_pk_fp8_f32 v87, v78, v79 op_sel:[0,0,1]
	v_lshl_add_u64 v[64:65], v[90:91], 0, v[134:135]
	global_store_dwordx2 v[64:65], v[84:85], off
	global_store_dwordx2 v[64:65], v[86:87], off offset:128
	v_lshl_add_u64 v[66:67], v[92:93], 0, v[134:135]
	global_load_dwordx2 v[64:65], v[66:67], off offset:1024
	s_nop 0
	global_load_dwordx2 v[66:67], v[66:67], off offset:1152
	v_lshlrev_b64 v[74:75], 10, v[88:89]
	v_mov_b32_e32 v68, v129
	v_mov_b32_e32 v69, v129
	v_mov_b32_e32 v70, v129
	v_mov_b32_e32 v71, v129
	v_add_u32_e32 v72, 0x90, v136
	v_ashrrev_i32_e32 v73, 31, v72
	v_lshl_add_u64 v[74:75], s[28:29], 0, v[74:75]
	v_lshlrev_b64 v[76:77], 11, v[72:73]
	v_lshl_add_u64 v[76:77], s[42:43], 0, v[76:77]
	s_waitcnt vmcnt(1)
	v_cvt_f32_ubyte0_e32 v78, v64
	v_cvt_f32_ubyte1_e32 v79, v64
	v_cvt_f32_ubyte0_e32 v81, v65
	v_cvt_f32_ubyte1_e32 v82, v65
	s_waitcnt vmcnt(0)
	v_cvt_f32_ubyte0_e32 v84, v66
	v_cvt_f32_ubyte1_e32 v85, v66
	v_cvt_f32_ubyte0_e32 v87, v67
	v_cvt_f32_ubyte1_e32 v88, v67
	v_max_f32_e32 v78, 0.5, v78
	v_max_f32_e32 v79, 0.5, v79
	v_max_f32_e32 v81, 0.5, v81
	v_max_f32_e32 v82, 0.5, v82
	v_max_f32_e32 v84, 0.5, v84
	v_max_f32_e32 v85, 0.5, v85
	v_max_f32_e32 v87, 0.5, v87
	v_max_f32_e32 v88, 0.5, v88
	v_mul_f32_e32 v78, 0x3a008081, v78
	v_mul_f32_e32 v79, 0x3a008081, v79
	v_mul_f32_e32 v81, 0x3a008081, v81
	v_mul_f32_e32 v82, 0x3a008081, v82
	v_mul_f32_e32 v84, 0x3a008081, v84
	v_mul_f32_e32 v85, 0x3a008081, v85
	v_mul_f32_e32 v87, 0x3a008081, v87
	v_mul_f32_e32 v88, 0x3a008081, v88
	v_mul_f32_e32 v48, v48, v78
	v_mul_f32_e32 v49, v49, v79
	v_mul_f32_e32 v52, v52, v81
	v_mul_f32_e32 v53, v53, v82
	v_cvt_f32_ubyte2_e32 v80, v64
	v_cvt_f32_ubyte3_e32 v64, v64
	v_cvt_f32_ubyte2_e32 v83, v65
	v_cvt_f32_ubyte3_e32 v65, v65
	v_mul_f32_e32 v56, v56, v84
	v_mul_f32_e32 v57, v57, v85
	v_mul_f32_e32 v60, v60, v87
	v_mul_f32_e32 v61, v61, v88
	v_cvt_pk_fp8_f32 v68, v48, v49
	v_cvt_pk_fp8_f32 v69, v52, v53
	v_cvt_f32_ubyte2_e32 v86, v66
	v_cvt_f32_ubyte3_e32 v66, v66
	v_cvt_f32_ubyte2_e32 v89, v67
	v_cvt_f32_ubyte3_e32 v67, v67
	v_max_f32_e32 v80, 0.5, v80
	v_max_f32_e32 v64, 0.5, v64
	v_max_f32_e32 v83, 0.5, v83
	v_max_f32_e32 v65, 0.5, v65
	v_cvt_pk_fp8_f32 v70, v56, v57
	v_cvt_pk_fp8_f32 v71, v60, v61
	v_max_f32_e32 v86, 0.5, v86
	v_max_f32_e32 v66, 0.5, v66
	v_max_f32_e32 v89, 0.5, v89
	v_max_f32_e32 v67, 0.5, v67
	v_mul_f32_e32 v80, 0x3a008081, v80
	v_mul_f32_e32 v64, 0x3a008081, v64
	v_mul_f32_e32 v83, 0x3a008081, v83
	v_mul_f32_e32 v65, 0x3a008081, v65
	v_mul_f32_e32 v86, 0x3a008081, v86
	v_mul_f32_e32 v66, 0x3a008081, v66
	v_mul_f32_e32 v89, 0x3a008081, v89
	v_mul_f32_e32 v67, 0x3a008081, v67
	v_mul_f32_e32 v50, v50, v80
	v_mul_f32_e32 v51, v51, v64
	v_mul_f32_e32 v54, v54, v83
	v_mul_f32_e32 v55, v55, v65
	v_mul_f32_e32 v58, v58, v86
	v_mul_f32_e32 v59, v59, v66
	v_mul_f32_e32 v62, v62, v89
	v_mul_f32_e32 v63, v63, v67
	v_cvt_pk_fp8_f32 v68, v50, v51 op_sel:[0,0,1]
	v_cvt_pk_fp8_f32 v69, v54, v55 op_sel:[0,0,1]
	v_cvt_pk_fp8_f32 v70, v58, v59 op_sel:[0,0,1]
	v_cvt_pk_fp8_f32 v71, v62, v63 op_sel:[0,0,1]
	v_lshl_add_u64 v[48:49], v[74:75], 0, v[134:135]
	global_store_dwordx2 v[48:49], v[68:69], off
	global_store_dwordx2 v[48:49], v[70:71], off offset:128
	v_lshl_add_u64 v[50:51], v[76:77], 0, v[134:135]
	global_load_dwordx2 v[48:49], v[50:51], off offset:1024
	s_nop 0
	global_load_dwordx2 v[50:51], v[50:51], off offset:1152
	v_lshlrev_b64 v[58:59], 10, v[72:73]
	v_mov_b32_e32 v52, v129
	v_mov_b32_e32 v53, v129
	v_mov_b32_e32 v54, v129
	v_mov_b32_e32 v55, v129
	v_add_u32_e32 v56, 0xa0, v136
	v_ashrrev_i32_e32 v57, 31, v56
	v_lshl_add_u64 v[58:59], s[28:29], 0, v[58:59]
	v_lshlrev_b64 v[60:61], 11, v[56:57]
	v_lshl_add_u64 v[60:61], s[42:43], 0, v[60:61]
	s_waitcnt vmcnt(1)
; __device__ __forceinline__ unsigned pk4_fp8g(float a, float b, float c, float d) { int r = __builtin_amdgcn_cvt_pk_fp8_f32(a, b, 0, false); r = __builtin_amdgcn_cvt_pk_fp8_f32(c, d, r, true); return (unsigned)r; }
; #define G2B(bw, sh) (fmaxf((float)(((bw) >> (sh)) & 0xffu), 0.5f) * (1.f / 2040.f))
;     __device__ __forceinline__ void operator()(const f32x4 (&acc)[2][2][4][2], const Unit& u, int wr, int wc, int fr, int fq) const {
;     ...
;             for (int m = 0; m < 4; ++m) { const size_t r = (size_t)(row0 + ai * HALF + m * 16);
; #pragma unroll
;                 for (int bj = 0; bj < 2; ++bj) {
;                     const u32x2g b = *(const u32x2g*)(Gt + r * GC + DM + col0 + bj * HALF);
;                     f32x4 v0 = acc[ai][bj][m][0], v1 = acc[ai][bj][m][1];
;     ...
;                     v0[0] *= G2B(b.x, 0); v0[1] *= G2B(b.x, 8); v0[2] *= G2B(b.x, 16); v0[3] *= G2B(b.x, 24);
;                     v1[0] *= G2B(b.y, 0); v1[1] *= G2B(b.y, 8); v1[2] *= G2B(b.y, 16); v1[3] *= G2B(b.y, 24);
;     ...
;                     u32x2g w; w.x = pk4_fp8g(v0[0], v0[1], v0[2], v0[3]); w.y = pk4_fp8g(v1[0], v1[1], v1[2], v1[3]);
;                     *(u32x2g*)((unsigned char*)O + r * DM + col0 + bj * HALF) = w; }
	v_cvt_f32_ubyte0_e32 v62, v48
	v_cvt_f32_ubyte1_e32 v63, v48
	v_cvt_f32_ubyte0_e32 v65, v49
	v_cvt_f32_ubyte1_e32 v66, v49
	s_waitcnt vmcnt(0)
	v_cvt_f32_ubyte0_e32 v68, v50
	v_cvt_f32_ubyte1_e32 v69, v50
	v_cvt_f32_ubyte0_e32 v71, v51
	v_cvt_f32_ubyte1_e32 v72, v51
	v_max_f32_e32 v62, 0.5, v62
	v_max_f32_e32 v63, 0.5, v63
	v_max_f32_e32 v65, 0.5, v65
	v_max_f32_e32 v66, 0.5, v66
	v_max_f32_e32 v68, 0.5, v68
	v_max_f32_e32 v69, 0.5, v69
	v_max_f32_e32 v71, 0.5, v71
	v_max_f32_e32 v72, 0.5, v72
	v_mul_f32_e32 v62, 0x3a008081, v62
	v_mul_f32_e32 v63, 0x3a008081, v63
	v_mul_f32_e32 v65, 0x3a008081, v65
	v_mul_f32_e32 v66, 0x3a008081, v66
	v_mul_f32_e32 v68, 0x3a008081, v68
	v_mul_f32_e32 v69, 0x3a008081, v69
	v_mul_f32_e32 v71, 0x3a008081, v71
	v_mul_f32_e32 v72, 0x3a008081, v72
	v_mul_f32_e32 v32, v32, v62
	v_mul_f32_e32 v33, v33, v63
	v_mul_f32_e32 v36, v36, v65
	v_mul_f32_e32 v37, v37, v66
	v_cvt_f32_ubyte2_e32 v64, v48
	v_cvt_f32_ubyte3_e32 v48, v48
	v_cvt_f32_ubyte2_e32 v67, v49
	v_cvt_f32_ubyte3_e32 v49, v49
	v_mul_f32_e32 v40, v40, v68
	v_mul_f32_e32 v41, v41, v69
	v_mul_f32_e32 v44, v44, v71
	v_mul_f32_e32 v45, v45, v72
	v_cvt_pk_fp8_f32 v52, v32, v33
	v_cvt_pk_fp8_f32 v53, v36, v37
	v_cvt_f32_ubyte2_e32 v70, v50
	v_cvt_f32_ubyte3_e32 v50, v50
	v_cvt_f32_ubyte2_e32 v73, v51
	v_cvt_f32_ubyte3_e32 v51, v51
	v_max_f32_e32 v64, 0.5, v64
	v_max_f32_e32 v48, 0.5, v48
	v_max_f32_e32 v67, 0.5, v67
	v_max_f32_e32 v49, 0.5, v49
	v_cvt_pk_fp8_f32 v54, v40, v41
	v_cvt_pk_fp8_f32 v55, v44, v45
	v_max_f32_e32 v70, 0.5, v70
	v_max_f32_e32 v50, 0.5, v50
	v_max_f32_e32 v73, 0.5, v73
	v_max_f32_e32 v51, 0.5, v51
	v_mul_f32_e32 v64, 0x3a008081, v64
	v_mul_f32_e32 v48, 0x3a008081, v48
	v_mul_f32_e32 v67, 0x3a008081, v67
	v_mul_f32_e32 v49, 0x3a008081, v49
	v_mul_f32_e32 v70, 0x3a008081, v70
	v_mul_f32_e32 v50, 0x3a008081, v50
	v_mul_f32_e32 v73, 0x3a008081, v73
	v_mul_f32_e32 v51, 0x3a008081, v51
	v_mul_f32_e32 v34, v34, v64
	v_mul_f32_e32 v35, v35, v48
	v_mul_f32_e32 v38, v38, v67
	v_mul_f32_e32 v39, v39, v49
	v_mul_f32_e32 v42, v42, v70
	v_mul_f32_e32 v43, v43, v50
	v_mul_f32_e32 v46, v46, v73
	v_mul_f32_e32 v47, v47, v51
	v_cvt_pk_fp8_f32 v52, v34, v35 op_sel:[0,0,1]
	v_cvt_pk_fp8_f32 v53, v38, v39 op_sel:[0,0,1]
	v_cvt_pk_fp8_f32 v54, v42, v43 op_sel:[0,0,1]
	v_cvt_pk_fp8_f32 v55, v46, v47 op_sel:[0,0,1]
	v_lshl_add_u64 v[32:33], v[58:59], 0, v[134:135]
	global_store_dwordx2 v[32:33], v[52:53], off
	global_store_dwordx2 v[32:33], v[54:55], off offset:128
	v_lshl_add_u64 v[34:35], v[60:61], 0, v[134:135]
	global_load_dwordx2 v[32:33], v[34:35], off offset:1024
	s_nop 0
	global_load_dwordx2 v[34:35], v[34:35], off offset:1152
	v_lshlrev_b64 v[42:43], 10, v[56:57]
	v_mov_b32_e32 v36, v129
	v_mov_b32_e32 v37, v129
	v_mov_b32_e32 v38, v129
	v_mov_b32_e32 v39, v129
	v_add_u32_e32 v40, 0xb0, v136
	v_ashrrev_i32_e32 v41, 31, v40
	v_lshl_add_u64 v[42:43], s[28:29], 0, v[42:43]
	v_lshlrev_b64 v[44:45], 11, v[40:41]
	v_lshl_add_u64 v[44:45], s[42:43], 0, v[44:45]
	s_waitcnt vmcnt(1)
	v_cvt_f32_ubyte0_e32 v46, v32
	v_cvt_f32_ubyte1_e32 v47, v32
	v_cvt_f32_ubyte0_e32 v49, v33
	v_cvt_f32_ubyte1_e32 v50, v33
	s_waitcnt vmcnt(0)
	v_cvt_f32_ubyte0_e32 v52, v34
	v_cvt_f32_ubyte1_e32 v53, v34
	v_cvt_f32_ubyte0_e32 v55, v35
	v_cvt_f32_ubyte1_e32 v56, v35
	v_max_f32_e32 v46, 0.5, v46
	v_max_f32_e32 v47, 0.5, v47
	v_max_f32_e32 v49, 0.5, v49
	v_max_f32_e32 v50, 0.5, v50
	v_max_f32_e32 v52, 0.5, v52
	v_max_f32_e32 v53, 0.5, v53
	v_max_f32_e32 v55, 0.5, v55
	v_max_f32_e32 v56, 0.5, v56
	v_mul_f32_e32 v46, 0x3a008081, v46
	v_mul_f32_e32 v47, 0x3a008081, v47
	v_mul_f32_e32 v49, 0x3a008081, v49
	v_mul_f32_e32 v50, 0x3a008081, v50
	v_mul_f32_e32 v52, 0x3a008081, v52
	v_mul_f32_e32 v53, 0x3a008081, v53
	v_mul_f32_e32 v55, 0x3a008081, v55
	v_mul_f32_e32 v56, 0x3a008081, v56
	v_mul_f32_e32 v16, v16, v46
	v_mul_f32_e32 v17, v17, v47
	v_mul_f32_e32 v20, v20, v49
	v_mul_f32_e32 v21, v21, v50
	v_cvt_f32_ubyte2_e32 v48, v32
	v_cvt_f32_ubyte3_e32 v32, v32
	v_cvt_f32_ubyte2_e32 v51, v33
	v_cvt_f32_ubyte3_e32 v33, v33
	v_mul_f32_e32 v24, v24, v52
	v_mul_f32_e32 v25, v25, v53
	v_mul_f32_e32 v28, v28, v55
	v_mul_f32_e32 v29, v29, v56
	v_cvt_pk_fp8_f32 v36, v16, v17
	v_cvt_pk_fp8_f32 v37, v20, v21
	v_cvt_f32_ubyte2_e32 v54, v34
	v_cvt_f32_ubyte3_e32 v34, v34
	v_cvt_f32_ubyte2_e32 v57, v35
	v_cvt_f32_ubyte3_e32 v35, v35
	v_max_f32_e32 v48, 0.5, v48
	v_max_f32_e32 v32, 0.5, v32
	v_max_f32_e32 v51, 0.5, v51
	v_max_f32_e32 v33, 0.5, v33
	v_cvt_pk_fp8_f32 v38, v24, v25
	v_cvt_pk_fp8_f32 v39, v28, v29
	v_max_f32_e32 v54, 0.5, v54
	v_max_f32_e32 v34, 0.5, v34
	v_max_f32_e32 v57, 0.5, v57
	v_max_f32_e32 v35, 0.5, v35
	v_mul_f32_e32 v48, 0x3a008081, v48
	v_mul_f32_e32 v32, 0x3a008081, v32
	v_mul_f32_e32 v51, 0x3a008081, v51
	v_mul_f32_e32 v33, 0x3a008081, v33
	v_mul_f32_e32 v54, 0x3a008081, v54
	v_mul_f32_e32 v34, 0x3a008081, v34
	v_mul_f32_e32 v57, 0x3a008081, v57
	v_mul_f32_e32 v35, 0x3a008081, v35
	v_mul_f32_e32 v18, v18, v48
	v_mul_f32_e32 v19, v19, v32
	v_mul_f32_e32 v22, v22, v51
	v_mul_f32_e32 v23, v23, v33
	v_mul_f32_e32 v26, v26, v54
	v_mul_f32_e32 v27, v27, v34
	v_mul_f32_e32 v30, v30, v57
	v_mul_f32_e32 v31, v31, v35
	v_cvt_pk_fp8_f32 v36, v18, v19 op_sel:[0,0,1]
	v_cvt_pk_fp8_f32 v37, v22, v23 op_sel:[0,0,1]
	v_cvt_pk_fp8_f32 v38, v26, v27 op_sel:[0,0,1]
	v_cvt_pk_fp8_f32 v39, v30, v31 op_sel:[0,0,1]
	v_lshl_add_u64 v[16:17], v[42:43], 0, v[134:135]
	global_store_dwordx2 v[16:17], v[36:37], off
	global_store_dwordx2 v[16:17], v[38:39], off offset:128
	v_lshl_add_u64 v[18:19], v[44:45], 0, v[134:135]
	global_load_dwordx2 v[16:17], v[18:19], off offset:1024
	s_nop 0
	global_load_dwordx2 v[18:19], v[18:19], off offset:1152
	v_mov_b32_e32 v20, v129
	v_mov_b32_e32 v21, v129
	v_mov_b32_e32 v22, v129
	v_mov_b32_e32 v23, v129
	v_lshlrev_b64 v[24:25], 10, v[40:41]
	s_waitcnt vmcnt(1)
; #define PG8_BAR __builtin_amdgcn_s_barrier()
; __device__ __forceinline__ unsigned pk4_fp8g(float a, float b, float c, float d) { int r = __builtin_amdgcn_cvt_pk_fp8_f32(a, b, 0, false); r = __builtin_amdgcn_cvt_pk_fp8_f32(c, d, r, true); return (unsigned)r; }
; #define G2B(bw, sh) (fmaxf((float)(((bw) >> (sh)) & 0xffu), 0.5f) * (1.f / 2040.f))
; template <class Epi, class Sched, bool ALIGN_EPI = false, bool SP2 = false, bool FP8 = false>
; __device__ __forceinline__ void gemm_phase(PG8_LAS unsigned char* lds, const Gemm g, const Sched& S, const Epi& E) {
;     ...
;         if (!has_next) break;
; #pragma unroll
;         for (int a = 0; a < 2; ++a)
; #pragma unroll
;             for (int b = 0; b < 2; ++b)
; #pragma unroll
;                 for (int m = 0; m < 4; ++m)
; #pragma unroll
;                     for (int n = 0; n < 2; ++n) { acc[a][b][m][n] = (f32x4){0.f, 0.f, 0.f, 0.f}; if constexpr (FP8) asm volatile("" : "+v"(acc[a][b][m][n])); }
;         cur = nxt; cA = nA; cB = nB; ++ui;
;         if constexpr (ALIGN_EPI) { if (wr == 1) PG8_BAR; }
;     __device__ __forceinline__ void operator()(const f32x4 (&acc)[2][2][4][2], const Unit& u, int wr, int wc, int fr, int fq) const {
;     ...
;             for (int m = 0; m < 4; ++m) { const size_t r = (size_t)(row0 + ai * HALF + m * 16);
; #pragma unroll
;                 for (int bj = 0; bj < 2; ++bj) {
;                     const u32x2g b = *(const u32x2g*)(Gt + r * GC + DM + col0 + bj * HALF);
;                     f32x4 v0 = acc[ai][bj][m][0], v1 = acc[ai][bj][m][1];
;     ...
;                     v0[0] *= G2B(b.x, 0); v0[1] *= G2B(b.x, 8); v0[2] *= G2B(b.x, 16); v0[3] *= G2B(b.x, 24);
;                     v1[0] *= G2B(b.y, 0); v1[1] *= G2B(b.y, 8); v1[2] *= G2B(b.y, 16); v1[3] *= G2B(b.y, 24);
;     ...
;                     u32x2g w; w.x = pk4_fp8g(v0[0], v0[1], v0[2], v0[3]); w.y = pk4_fp8g(v1[0], v1[1], v1[2], v1[3]);
;                     *(u32x2g*)((unsigned char*)O + r * DM + col0 + bj * HALF) = w; }
	v_cvt_f32_ubyte0_e32 v26, v16
	v_cvt_f32_ubyte1_e32 v27, v16
	v_cvt_f32_ubyte0_e32 v29, v17
	v_cvt_f32_ubyte1_e32 v30, v17
	s_waitcnt vmcnt(0)
	v_cvt_f32_ubyte0_e32 v32, v18
	v_cvt_f32_ubyte1_e32 v33, v18
	v_cvt_f32_ubyte0_e32 v35, v19
	v_cvt_f32_ubyte1_e32 v36, v19
	v_max_f32_e32 v26, 0.5, v26
	v_max_f32_e32 v27, 0.5, v27
	v_max_f32_e32 v29, 0.5, v29
	v_max_f32_e32 v30, 0.5, v30
	v_max_f32_e32 v32, 0.5, v32
	v_max_f32_e32 v33, 0.5, v33
	v_max_f32_e32 v35, 0.5, v35
	v_max_f32_e32 v36, 0.5, v36
	v_mul_f32_e32 v26, 0x3a008081, v26
	v_mul_f32_e32 v27, 0x3a008081, v27
	v_mul_f32_e32 v29, 0x3a008081, v29
	v_mul_f32_e32 v30, 0x3a008081, v30
	v_mul_f32_e32 v32, 0x3a008081, v32
	v_mul_f32_e32 v33, 0x3a008081, v33
	v_mul_f32_e32 v35, 0x3a008081, v35
	v_mul_f32_e32 v36, 0x3a008081, v36
	v_mul_f32_e32 v4, v4, v26
	v_mul_f32_e32 v5, v5, v27
	v_mul_f32_e32 v8, v8, v29
	v_mul_f32_e32 v9, v9, v30
	v_cvt_f32_ubyte2_e32 v28, v16
	v_cvt_f32_ubyte3_e32 v16, v16
	v_cvt_f32_ubyte2_e32 v31, v17
	v_cvt_f32_ubyte3_e32 v17, v17
	v_mul_f32_e32 v12, v12, v32
	v_mul_f32_e32 v13, v13, v33
	v_mul_f32_e32 v0, v0, v35
	v_mul_f32_e32 v1, v1, v36
	v_cvt_pk_fp8_f32 v20, v4, v5
	v_cvt_pk_fp8_f32 v21, v8, v9
	v_cvt_f32_ubyte2_e32 v34, v18
	v_cvt_f32_ubyte3_e32 v18, v18
	v_cvt_f32_ubyte2_e32 v37, v19
	v_cvt_f32_ubyte3_e32 v19, v19
	v_max_f32_e32 v28, 0.5, v28
	v_max_f32_e32 v16, 0.5, v16
	v_max_f32_e32 v31, 0.5, v31
	v_max_f32_e32 v17, 0.5, v17
	v_cvt_pk_fp8_f32 v22, v12, v13
	v_cvt_pk_fp8_f32 v23, v0, v1
	v_max_f32_e32 v34, 0.5, v34
	v_max_f32_e32 v18, 0.5, v18
	v_max_f32_e32 v37, 0.5, v37
	v_max_f32_e32 v19, 0.5, v19
	v_mul_f32_e32 v28, 0x3a008081, v28
	v_mul_f32_e32 v16, 0x3a008081, v16
	v_mul_f32_e32 v31, 0x3a008081, v31
	v_mul_f32_e32 v17, 0x3a008081, v17
	v_mul_f32_e32 v34, 0x3a008081, v34
	v_mul_f32_e32 v18, 0x3a008081, v18
	v_mul_f32_e32 v37, 0x3a008081, v37
	v_mul_f32_e32 v19, 0x3a008081, v19
	v_mul_f32_e32 v6, v6, v28
	v_mul_f32_e32 v7, v7, v16
	v_mul_f32_e32 v10, v10, v31
	v_mul_f32_e32 v11, v11, v17
	v_mul_f32_e32 v14, v14, v34
	v_mul_f32_e32 v15, v15, v18
	v_mul_f32_e32 v2, v2, v37
	v_mul_f32_e32 v3, v3, v19
	v_cvt_pk_fp8_f32 v20, v6, v7 op_sel:[0,0,1]
	v_cvt_pk_fp8_f32 v21, v10, v11 op_sel:[0,0,1]
	v_cvt_pk_fp8_f32 v22, v14, v15 op_sel:[0,0,1]
	v_cvt_pk_fp8_f32 v23, v2, v3 op_sel:[0,0,1]
	v_lshl_add_u64 v[0:1], s[28:29], 0, v[24:25]
	v_lshl_add_u64 v[0:1], v[0:1], 0, v[134:135]
	global_store_dwordx2 v[0:1], v[20:21], off
	global_store_dwordx2 v[0:1], v[22:23], off offset:128
	s_cbranch_vccnz .LBB0_297
	s_mov_b32 s9, s8
	s_mov_b32 s10, s8
	s_mov_b32 s11, s8
	v_mov_b64_e32 v[0:1], s[8:9]
	v_mov_b64_e32 v[114:115], s[10:11]
	v_mov_b64_e32 v[118:119], s[10:11]
	v_mov_b64_e32 v[98:99], s[10:11]
	v_mov_b64_e32 v[102:103], s[10:11]
	v_mov_b64_e32 v[82:83], s[10:11]
	v_mov_b64_e32 v[86:87], s[10:11]
	v_mov_b64_e32 v[66:67], s[10:11]
	v_mov_b64_e32 v[70:71], s[10:11]
	v_mov_b64_e32 v[122:123], s[10:11]
	v_mov_b64_e32 v[126:127], s[10:11]
	v_mov_b64_e32 v[106:107], s[10:11]
	v_mov_b64_e32 v[110:111], s[10:11]
	v_mov_b64_e32 v[90:91], s[10:11]
	v_mov_b64_e32 v[94:95], s[10:11]
	v_mov_b64_e32 v[74:75], s[10:11]
	v_mov_b64_e32 v[78:79], s[10:11]
	v_mov_b64_e32 v[50:51], s[10:11]
	v_mov_b64_e32 v[54:55], s[10:11]
	v_mov_b64_e32 v[34:35], s[10:11]
	v_mov_b64_e32 v[38:39], s[10:11]
	v_mov_b64_e32 v[18:19], s[10:11]
	v_mov_b64_e32 v[22:23], s[10:11]
	v_mov_b64_e32 v[4:5], s[8:9]
	v_mov_b64_e32 v[8:9], s[8:9]
	v_mov_b64_e32 v[58:59], s[10:11]
	v_mov_b64_e32 v[62:63], s[10:11]
	v_mov_b64_e32 v[42:43], s[10:11]
	v_mov_b64_e32 v[46:47], s[10:11]
	v_mov_b64_e32 v[26:27], s[10:11]
	v_mov_b64_e32 v[30:31], s[10:11]
	v_mov_b64_e32 v[14:15], s[10:11]
	v_mov_b64_e32 v[2:3], s[10:11]
	v_mov_b64_e32 v[112:113], s[8:9]
	v_mov_b64_e32 v[116:117], s[8:9]
	v_mov_b64_e32 v[96:97], s[8:9]
	v_mov_b64_e32 v[100:101], s[8:9]
	v_mov_b64_e32 v[80:81], s[8:9]
	v_mov_b64_e32 v[84:85], s[8:9]
	v_mov_b64_e32 v[64:65], s[8:9]
	v_mov_b64_e32 v[68:69], s[8:9]
	v_mov_b64_e32 v[120:121], s[8:9]
	v_mov_b64_e32 v[124:125], s[8:9]
	v_mov_b64_e32 v[104:105], s[8:9]
	v_mov_b64_e32 v[108:109], s[8:9]
	v_mov_b64_e32 v[88:89], s[8:9]
	v_mov_b64_e32 v[92:93], s[8:9]
	v_mov_b64_e32 v[72:73], s[8:9]
	v_mov_b64_e32 v[76:77], s[8:9]
	v_mov_b64_e32 v[48:49], s[8:9]
	v_mov_b64_e32 v[52:53], s[8:9]
	v_mov_b64_e32 v[32:33], s[8:9]
	v_mov_b64_e32 v[36:37], s[8:9]
	v_mov_b64_e32 v[16:17], s[8:9]
	v_mov_b64_e32 v[20:21], s[8:9]
	v_mov_b64_e32 v[6:7], s[10:11]
	v_mov_b64_e32 v[10:11], s[10:11]
	v_mov_b64_e32 v[56:57], s[8:9]
	v_mov_b64_e32 v[60:61], s[8:9]
	v_mov_b64_e32 v[40:41], s[8:9]
	v_mov_b64_e32 v[44:45], s[8:9]
	v_mov_b64_e32 v[24:25], s[8:9]
	v_mov_b64_e32 v[28:29], s[8:9]
	v_mov_b64_e32 v[12:13], s[8:9]
	s_andn2_b64 vcc, exec, s[12:13]
	s_cbranch_vccnz .LBB0_296
	s_mov_b32 s100, 1
	s_branch .LBB0_296

; #define PG8_STAGE(bufoff, gbase, voff) do { _Pragma("unroll") for (int _i = 0; _i < 2; ++_i) { unsigned vo_ = (voff)[_i]; if constexpr (FP8) asm volatile("" : "+v"(vo_)); \
;         __builtin_amdgcn_global_load_lds((const unsigned*)((const char*)(gbase) + vo_), (PG8_LAS unsigned*)(lds + (bufoff) + ldsw + _i * 8192), 16, 0, 0); } } while (0)
; #define PG8_LDA(dst, b, h) do { _Pragma("unroll") for (int m = 0; m < 4; ++m) _Pragma("unroll") for (int k = 0; k < 2; ++k) dst[m][k] = *(const PG8_LAS bf16x8*)(lds + PG8_SA(b, h) + aoff + m * 2048 + k * 1024); } while (0)
; #define PG8_LDB(dst, b, h) do { _Pragma("unroll") for (int n = 0; n < 2; ++n) _Pragma("unroll") for (int k = 0; k < 2; ++k) dst[n][k] = *(const PG8_LAS bf16x8*)(lds + PG8_SB(b, h) + boff + n * 2048 + k * 1024); } while (0)
; #define PG8_WAIT_V(n) asm volatile("s_waitcnt vmcnt(" #n ")" ::: "memory")
; #define PG8_WAIT_L(n) asm volatile("s_waitcnt lgkmcnt(" #n ")" ::: "memory")
; #define PG8_BAR __builtin_amdgcn_s_barrier()
; #define PG8_SCHED __builtin_amdgcn_sched_barrier(0)
; template <class Epi, class Sched, bool ALIGN_EPI = false, bool SP2 = false, bool FP8 = false>
; __device__ __forceinline__ void gemm_phase(PG8_LAS unsigned char* lds, const Gemm g, const Sched& S, const Epi& E) {
;     ...
;             const bool last = (t == nt - 2);
;             const char* a1 = cA + (size_t)(t + 1) * kstep;
;             const char* a2 = last ? nA : cA + (size_t)(t + 2) * kstep; const char* b2 = last ? nB : cB + (size_t)(t + 2) * kstep;
;             const char* a3 = a2 + kstep; const char* b3 = b2 + kstep;
;             if (last && has_next) S.a_ready(nxt);
;             if constexpr (SP2) {
;             PG8_LDB(B0, 0, 0); PG8_LDB(B1, 0, 1); PG8_SCHED; PG8_LDA(At, 0, 0); PG8_STAGE(PG8_SA(1, 1), a1 + hstep, voffA);
;             PG8_WAIT_V(8); PG8_WAIT_L(0); PG8_BAR; PG8_MMA(0, 0, At, B0); PG8_MMA(0, 1, At, B1); PG8_BAR; PG8_SCHED;
;             PG8_LDA(At, 0, 1); PG8_STAGE(PG8_SB(0, 0), b2, voffB); PG8_STAGE(PG8_SB(0, 1), b2 + hstep, voffB); PG8_STAGE(PG8_SA(0, 0), a2, voffA);
;             PG8_WAIT_V(8); PG8_WAIT_L(0); PG8_BAR; PG8_MMA(1, 0, At, B0); PG8_MMA(1, 1, At, B1); PG8_BAR; PG8_SCHED;
.LBB0_341:
	s_ashr_i32 s45, s44, 31
	s_lshl_b64 s[0:1], s[44:45], 18
	s_add_u32 s46, s28, s0
	s_addc_u32 s47, s29, s1
	s_and_b64 s[0:1], s[4:5], exec
	s_cselect_b32 s9, s47, s11
	s_cselect_b32 s45, s46, s10
	s_ashr_i32 s43, s42, 31
	s_lshl_b64 s[0:1], s[42:43], 18
	s_add_u32 s48, s34, s0
	s_addc_u32 s49, s35, s1
	s_and_b64 s[0:1], s[4:5], exec
	s_cselect_b32 s43, s49, s55
	s_cselect_b32 s51, s48, s54
	s_add_u32 s10, s10, 0x20080
	s_addc_u32 s11, s11, 0
	s_add_u32 s72, s54, 0x100
	s_addc_u32 s73, s55, 0
	s_mov_b32 s74, -2
	s_cmp_eq_u32 s100, 0
	s_cbranch_scc1 .Lmy_nobar_P4
	s_barrier
	s_mov_b32 s100, 0
.Lmy_nobar_P4:
.LBB0_342:
	v_add_u32_e32 v140, s69, v201
	v_add_u32_e32 v156, s70, v201
	ds_read_b128 v[128:131], v140
	ds_read_b128 v[132:135], v140 offset:1024
	ds_read_b128 v[136:139], v140 offset:2048
	ds_read_b128 v[140:143], v140 offset:3072
	ds_read_b128 v[144:147], v156
	ds_read_b128 v[148:151], v156 offset:1024
	ds_read_b128 v[152:155], v156 offset:2048
	ds_read_b128 v[156:159], v156 offset:3072
	s_add_u32 s0, s10, 0xfffe0080
	s_addc_u32 s1, s11, -1
	s_cmp_eq_u32 s74, 4
	s_cselect_b32 s55, s9, s1
	s_cselect_b32 s54, s45, s0
	s_cselect_b32 s57, s43, s73
	s_cselect_b32 s56, s51, s72
	v_mov_b32_e32 v178, v197
	ds_read_b128 v[160:163], v202
	ds_read_b128 v[164:167], v202 offset:1024
	ds_read_b128 v[168:171], v202 offset:2048
	ds_read_b128 v[172:175], v202 offset:3072
	ds_read_b128 v[184:187], v202 offset:4096
	ds_read_b128 v[188:191], v202 offset:5120
	ds_read_b128 v[206:209], v202 offset:6144
	ds_read_b128 v[210:213], v202 offset:7168
	s_add_i32 m0, s53, 0xc000
	s_nop 0
	global_load_lds_dwordx4 v178, s[10:11]
	v_mov_b32_e32 v178, v199
	s_add_i32 m0, s53, 0xe000
	s_nop 0
	global_load_lds_dwordx4 v178, s[10:11]
	s_waitcnt vmcnt(8)
	s_waitcnt lgkmcnt(0)
	s_barrier
	s_setprio 1
	s_waitcnt lgkmcnt(0)
	v_mfma_scale_f32_16x16x128_f8f6f4 v[116:119], v[128:135], v[160:167], v[116:119], v203, v203 op_sel_hi:[0,0,0]
	v_mfma_scale_f32_16x16x128_f8f6f4 v[112:115], v[136:143], v[160:167], v[112:115], v203, v203 op_sel_hi:[0,0,0]
	v_mfma_scale_f32_16x16x128_f8f6f4 v[108:111], v[128:135], v[168:175], v[108:111], v203, v203 op_sel_hi:[0,0,0]
	v_mfma_scale_f32_16x16x128_f8f6f4 v[100:103], v[136:143], v[168:175], v[100:103], v203, v203 op_sel_hi:[0,0,0]
	v_mfma_scale_f32_16x16x128_f8f6f4 v[192:195], v[128:135], v[184:191], v[92:95], v203, v203 op_sel_hi:[0,0,0]
	v_mfma_scale_f32_16x16x128_f8f6f4 v[214:217], v[136:143], v[184:191], v[84:87], v203, v203 op_sel_hi:[0,0,0]
	v_mfma_scale_f32_16x16x128_f8f6f4 v[218:221], v[128:135], v[206:213], v[76:79], v203, v203 op_sel_hi:[0,0,0]
	v_mfma_scale_f32_16x16x128_f8f6f4 v[222:225], v[136:143], v[206:213], v[68:71], v203, v203 op_sel_hi:[0,0,0]
	s_setprio 0
	s_setprio 1
	v_mfma_scale_f32_16x16x128_f8f6f4 v[124:127], v[144:151], v[160:167], v[124:127], v203, v203 op_sel_hi:[0,0,0]
	v_mfma_scale_f32_16x16x128_f8f6f4 v[120:123], v[152:159], v[160:167], v[120:123], v203, v203 op_sel_hi:[0,0,0]
	v_mfma_scale_f32_16x16x128_f8f6f4 v[104:107], v[144:151], v[168:175], v[104:107], v203, v203 op_sel_hi:[0,0,0]
	v_mfma_scale_f32_16x16x128_f8f6f4 v[96:99], v[152:159], v[168:175], v[96:99], v203, v203 op_sel_hi:[0,0,0]
	v_mfma_scale_f32_16x16x128_f8f6f4 v[160:163], v[144:151], v[184:191], v[88:91], v203, v203 op_sel_hi:[0,0,0]
	v_mfma_scale_f32_16x16x128_f8f6f4 v[164:167], v[152:159], v[184:191], v[80:83], v203, v203 op_sel_hi:[0,0,0]
	v_mfma_scale_f32_16x16x128_f8f6f4 v[168:171], v[144:151], v[206:213], v[72:75], v203, v203 op_sel_hi:[0,0,0]
	v_mfma_scale_f32_16x16x128_f8f6f4 v[172:175], v[152:159], v[206:213], v[64:67], v203, v203 op_sel_hi:[0,0,0]
	s_setprio 0
	s_barrier
	v_mov_b32_e32 v178, v198
	s_add_i32 s0, s69, s41
	s_nop 2
	ds_read_b128 v[64:67], v202 offset:16384
	ds_read_b128 v[68:71], v202 offset:17408
	ds_read_b128 v[72:75], v202 offset:18432
	ds_read_b128 v[76:79], v202 offset:19456
	ds_read_b128 v[80:83], v202 offset:20480
	ds_read_b128 v[84:87], v202 offset:21504
	ds_read_b128 v[88:91], v202 offset:22528
	ds_read_b128 v[92:95], v202 offset:23552
	s_mov_b32 m0, s0
	s_nop 0
	global_load_lds_dwordx4 v178, s[56:57]
	v_mov_b32_e32 v178, v200
	s_add_i32 m0, s0, 0x2000
	s_add_u32 s0, s56, 0x20000
	global_load_lds_dwordx4 v178, s[56:57]
	s_addc_u32 s1, s57, 0
	v_mov_b32_e32 v178, v198
	s_add_i32 s75, s70, s41
	s_mov_b32 m0, s75
	s_nop 0
	global_load_lds_dwordx4 v178, s[0:1]
	v_mov_b32_e32 v178, v200
	s_add_i32 m0, s75, 0x2000
	s_nop 0
	global_load_lds_dwordx4 v178, s[0:1]
	v_mov_b32_e32 v178, v197
	s_mov_b32 m0, s53
	s_nop 0
	global_load_lds_dwordx4 v178, s[54:55]
	v_mov_b32_e32 v178, v199
	s_mov_b32 m0, s58
	s_nop 0
	global_load_lds_dwordx4 v178, s[54:55]
	s_waitcnt vmcnt(8)
	s_waitcnt lgkmcnt(0)
	s_barrier
	s_setprio 1
	s_waitcnt lgkmcnt(0)
	v_mfma_scale_f32_16x16x128_f8f6f4 v[52:55], v[128:135], v[64:71], v[52:55], v203, v203 op_sel_hi:[0,0,0]
	v_mfma_scale_f32_16x16x128_f8f6f4 v[48:51], v[136:143], v[64:71], v[48:51], v203, v203 op_sel_hi:[0,0,0]
	v_mfma_scale_f32_16x16x128_f8f6f4 v[44:47], v[128:135], v[72:79], v[44:47], v203, v203 op_sel_hi:[0,0,0]
	v_mfma_scale_f32_16x16x128_f8f6f4 v[184:187], v[136:143], v[72:79], v[36:39], v203, v203 op_sel_hi:[0,0,0]
	v_mfma_scale_f32_16x16x128_f8f6f4 v[188:191], v[128:135], v[80:87], v[28:31], v203, v203 op_sel_hi:[0,0,0]
	v_mfma_scale_f32_16x16x128_f8f6f4 v[206:209], v[136:143], v[80:87], v[20:23], v203, v203 op_sel_hi:[0,0,0]
	v_mfma_scale_f32_16x16x128_f8f6f4 v[210:213], v[128:135], v[88:95], v[12:15], v203, v203 op_sel_hi:[0,0,0]
	v_mfma_scale_f32_16x16x128_f8f6f4 v[226:229], v[136:143], v[88:95], v[4:7], v203, v203 op_sel_hi:[0,0,0]
	s_setprio 0
	s_setprio 1
	v_mfma_scale_f32_16x16x128_f8f6f4 v[40:43], v[144:151], v[72:79], v[40:43], v203, v203 op_sel_hi:[0,0,0]
	v_mfma_scale_f32_16x16x128_f8f6f4 v[230:233], v[144:151], v[64:71], v[60:63], v203, v203 op_sel_hi:[0,0,0]
	v_mfma_scale_f32_16x16x128_f8f6f4 v[234:237], v[152:159], v[64:71], v[56:59], v203, v203 op_sel_hi:[0,0,0]
	v_mfma_scale_f32_16x16x128_f8f6f4 v[238:241], v[152:159], v[72:79], v[32:35], v203, v203 op_sel_hi:[0,0,0]
	v_mfma_scale_f32_16x16x128_f8f6f4 v[242:245], v[144:151], v[80:87], v[24:27], v203, v203 op_sel_hi:[0,0,0]
	v_mfma_scale_f32_16x16x128_f8f6f4 v[246:249], v[152:159], v[80:87], v[16:19], v203, v203 op_sel_hi:[0,0,0]
	v_mfma_scale_f32_16x16x128_f8f6f4 v[250:253], v[144:151], v[88:95], v[8:11], v203, v203 op_sel_hi:[0,0,0]
	v_mfma_scale_f32_16x16x128_f8f6f4 v[180:183], v[152:159], v[88:95], v[0:3], v203, v203 op_sel_hi:[0,0,0]
	s_setprio 0
	s_barrier
; #define PG8_LDA(dst, b, h) do { _Pragma("unroll") for (int m = 0; m < 4; ++m) _Pragma("unroll") for (int k = 0; k < 2; ++k) dst[m][k] = *(const PG8_LAS bf16x8*)(lds + PG8_SA(b, h) + aoff + m * 2048 + k * 1024); } while (0)
; #define PG8_WAIT_V(n) asm volatile("s_waitcnt vmcnt(" #n ")" ::: "memory")
; template <class Epi, class Sched, bool ALIGN_EPI = false, bool SP2 = false, bool FP8 = false>
; __device__ __forceinline__ void gemm_phase(PG8_LAS unsigned char* lds, const Gemm g, const Sched& S, const Epi& E) {
;     ...
;             PG8_LDB(B0, 1, 0); PG8_LDB(B1, 1, 1); PG8_SCHED; PG8_LDA(At, 1, 0); PG8_STAGE(PG8_SA(0, 1), a2 + hstep, voffA);
;             PG8_WAIT_V(8); PG8_WAIT_L(0); PG8_BAR; PG8_MMA(0, 0, At, B0); PG8_MMA(0, 1, At, B1); PG8_BAR; PG8_SCHED;
;             PG8_LDA(At, 1, 1); PG8_STAGE(PG8_SB(1, 0), b3, voffB); PG8_STAGE(PG8_SB(1, 1), b3 + hstep, voffB); PG8_STAGE(PG8_SA(1, 0), a3, voffA);
;             PG8_WAIT_V(8); PG8_WAIT_L(0); PG8_BAR; PG8_MMA(1, 0, At, B0); PG8_MMA(1, 1, At, B1); PG8_BAR; PG8_SCHED;
;             } else {
;             PG8_LDB(B0, 0, 0); PG8_SCHED; PG8_LDA(At, 0, 0); PG8_STAGE(PG8_SA(1, 1), a1 + hstep, voffA);
;             PG8_WAIT_L(8); PG8_BAR; PG8_WAIT_L(0); PG8_MMA(0, 0, At, B0); PG8_BAR; PG8_SCHED;
;             PG8_LDB(B1, 0, 1); PG8_STAGE(PG8_SB(0, 0), b2, voffB);
;             PG8_BAR; PG8_WAIT_L(0); PG8_MMA(0, 1, At, B1); PG8_BAR;
;             PG8_LDA(At, 0, 1); PG8_STAGE(PG8_SA(0, 0), a2, voffA);
;             PG8_BAR; PG8_WAIT_L(0); PG8_MMA(1, 0, At, B0); PG8_BAR; PG8_SCHED;
;             PG8_STAGE(PG8_SB(0, 1), b2 + hstep, voffB);
;             PG8_WAIT_V(6); PG8_BAR; PG8_MMA(1, 1, At, B1); PG8_BAR;
;             PG8_LDB(B0, 1, 0); PG8_SCHED; PG8_LDA(At, 1, 0); PG8_STAGE(PG8_SA(0, 1), a2 + hstep, voffA);
;             PG8_WAIT_L(8); PG8_BAR; PG8_WAIT_L(0); PG8_MMA(0, 0, At, B0); PG8_BAR; PG8_SCHED;
;             PG8_LDB(B1, 1, 1); PG8_STAGE(PG8_SB(1, 0), b3, voffB);
;             PG8_BAR; PG8_WAIT_L(0); PG8_MMA(0, 1, At, B1); PG8_BAR;
;             PG8_LDA(At, 1, 1); PG8_STAGE(PG8_SA(1, 0), a3, voffA);
;             PG8_BAR; PG8_WAIT_L(0); PG8_MMA(1, 0, At, B0); PG8_BAR; PG8_SCHED;
;             PG8_STAGE(PG8_SB(1, 1), b3 + hstep, voffB);
;             PG8_WAIT_V(6); PG8_BAR; PG8_MMA(1, 1, At, B1); PG8_BAR;
;             }
;         }
;         if constexpr (ALIGN_EPI) { if (wr == 0) PG8_BAR; }
	s_add_i32 s75, 0, 0x18000
	s_nop 2
	v_add_u32_e32 v8, s75, v201
	s_add_i32 s77, 0, 0x1c000
	ds_read_b128 v[0:3], v8
	ds_read_b128 v[4:7], v8 offset:1024
	ds_read_b128 v[56:59], v8 offset:2048
	ds_read_b128 v[60:63], v8 offset:3072
	v_add_u32_e32 v8, s77, v201
	ds_read_b128 v[128:131], v8
	ds_read_b128 v[132:135], v8 offset:1024
	ds_read_b128 v[136:139], v8 offset:2048
	ds_read_b128 v[140:143], v8 offset:3072
	s_add_u32 s0, s54, 0x20000
	v_mov_b32_e32 v64, v197
	s_mov_b32 m0, s59
	ds_read_b128 v[8:11], v202 offset:32768
	ds_read_b128 v[12:15], v202 offset:33792
	ds_read_b128 v[16:19], v202 offset:34816
	ds_read_b128 v[20:23], v202 offset:35840
	ds_read_b128 v[24:27], v202 offset:36864
	ds_read_b128 v[28:31], v202 offset:37888
	ds_read_b128 v[32:35], v202 offset:38912
	ds_read_b128 v[36:39], v202 offset:39936
	s_addc_u32 s1, s55, 0
	s_nop 0
	global_load_lds_dwordx4 v64, s[0:1]
	v_mov_b32_e32 v64, v199
	s_mov_b32 m0, s60
	s_nop 0
	global_load_lds_dwordx4 v64, s[0:1]
	s_waitcnt vmcnt(8)
	s_waitcnt lgkmcnt(0)
	s_barrier
	s_setprio 1
	s_waitcnt lgkmcnt(0)
	v_mfma_scale_f32_16x16x128_f8f6f4 v[116:119], v[0:7], v[8:15], v[116:119], v203, v203 op_sel_hi:[0,0,0]
	v_mfma_scale_f32_16x16x128_f8f6f4 v[112:115], v[56:63], v[8:15], v[112:115], v203, v203 op_sel_hi:[0,0,0]
	v_mfma_scale_f32_16x16x128_f8f6f4 v[108:111], v[0:7], v[16:23], v[108:111], v203, v203 op_sel_hi:[0,0,0]
	v_mfma_scale_f32_16x16x128_f8f6f4 v[100:103], v[56:63], v[16:23], v[100:103], v203, v203 op_sel_hi:[0,0,0]
	v_mfma_scale_f32_16x16x128_f8f6f4 v[92:95], v[0:7], v[24:31], v[192:195], v203, v203 op_sel_hi:[0,0,0]
	v_mfma_scale_f32_16x16x128_f8f6f4 v[84:87], v[56:63], v[24:31], v[214:217], v203, v203 op_sel_hi:[0,0,0]
	v_mfma_scale_f32_16x16x128_f8f6f4 v[76:79], v[0:7], v[32:39], v[218:221], v203, v203 op_sel_hi:[0,0,0]
	v_mfma_scale_f32_16x16x128_f8f6f4 v[68:71], v[56:63], v[32:39], v[222:225], v203, v203 op_sel_hi:[0,0,0]
	s_setprio 0
	s_setprio 1
	v_mfma_scale_f32_16x16x128_f8f6f4 v[124:127], v[128:135], v[8:15], v[124:127], v203, v203 op_sel_hi:[0,0,0]
	v_mfma_scale_f32_16x16x128_f8f6f4 v[120:123], v[136:143], v[8:15], v[120:123], v203, v203 op_sel_hi:[0,0,0]
	v_mfma_scale_f32_16x16x128_f8f6f4 v[104:107], v[128:135], v[16:23], v[104:107], v203, v203 op_sel_hi:[0,0,0]
	v_mfma_scale_f32_16x16x128_f8f6f4 v[96:99], v[136:143], v[16:23], v[96:99], v203, v203 op_sel_hi:[0,0,0]
	v_mfma_scale_f32_16x16x128_f8f6f4 v[88:91], v[128:135], v[24:31], v[160:163], v203, v203 op_sel_hi:[0,0,0]
	v_mfma_scale_f32_16x16x128_f8f6f4 v[80:83], v[136:143], v[24:31], v[164:167], v203, v203 op_sel_hi:[0,0,0]
	v_mfma_scale_f32_16x16x128_f8f6f4 v[72:75], v[128:135], v[32:39], v[168:171], v203, v203 op_sel_hi:[0,0,0]
	v_mfma_scale_f32_16x16x128_f8f6f4 v[64:67], v[136:143], v[32:39], v[172:175], v203, v203 op_sel_hi:[0,0,0]
	s_setprio 0
	s_barrier
	v_mov_b32_e32 v178, v198
	ds_read_b128 v[144:147], v202 offset:49152
	ds_read_b128 v[148:151], v202 offset:50176
	ds_read_b128 v[152:155], v202 offset:51200
	ds_read_b128 v[156:159], v202 offset:52224
	ds_read_b128 v[160:163], v202 offset:53248
	ds_read_b128 v[164:167], v202 offset:54272
	ds_read_b128 v[168:171], v202 offset:55296
	ds_read_b128 v[172:175], v202 offset:56320
	s_add_i32 s0, s75, s41
	v_lshl_add_u64 v[8:9], s[56:57], 0, v[178:179]
	v_lshl_add_u64 v[8:9], v[8:9], 0, s[14:15]
	s_mov_b32 m0, s0
	v_mov_b32_e32 v178, v200
	global_load_lds_dwordx4 v[8:9], off
	s_add_i32 m0, s0, 0x2000
	v_lshl_add_u64 v[8:9], s[56:57], 0, v[178:179]
	v_lshl_add_u64 v[8:9], v[8:9], 0, s[14:15]
	s_add_u32 s0, s56, 0x20080
	global_load_lds_dwordx4 v[8:9], off
	s_addc_u32 s1, s57, 0
	v_mov_b32_e32 v8, v198
	s_add_i32 s56, s77, s41
	s_mov_b32 m0, s56
	v_mov_b32_e32 v178, v197
	global_load_lds_dwordx4 v8, s[0:1]
	v_mov_b32_e32 v8, v200
	s_add_i32 m0, s56, 0x2000
	s_nop 0
	global_load_lds_dwordx4 v8, s[0:1]
	s_mov_b32 m0, s66
	v_lshl_add_u64 v[8:9], s[54:55], 0, v[178:179]
	v_lshl_add_u64 v[8:9], v[8:9], 0, s[14:15]
	v_mov_b32_e32 v178, v199
	global_load_lds_dwordx4 v[8:9], off
	s_mov_b32 m0, s67
	v_lshl_add_u64 v[8:9], s[54:55], 0, v[178:179]
	v_lshl_add_u64 v[8:9], v[8:9], 0, s[14:15]
	global_load_lds_dwordx4 v[8:9], off
	s_waitcnt vmcnt(8)
	s_waitcnt lgkmcnt(0)
	s_barrier
	s_setprio 1
	s_waitcnt lgkmcnt(0)
	v_mfma_scale_f32_16x16x128_f8f6f4 v[52:55], v[0:7], v[144:151], v[52:55], v203, v203 op_sel_hi:[0,0,0]
	v_mfma_scale_f32_16x16x128_f8f6f4 v[48:51], v[56:63], v[144:151], v[48:51], v203, v203 op_sel_hi:[0,0,0]
	v_mfma_scale_f32_16x16x128_f8f6f4 v[44:47], v[0:7], v[152:159], v[44:47], v203, v203 op_sel_hi:[0,0,0]
	v_mfma_scale_f32_16x16x128_f8f6f4 v[36:39], v[56:63], v[152:159], v[184:187], v203, v203 op_sel_hi:[0,0,0]
	v_mfma_scale_f32_16x16x128_f8f6f4 v[28:31], v[0:7], v[160:167], v[188:191], v203, v203 op_sel_hi:[0,0,0]
	v_mfma_scale_f32_16x16x128_f8f6f4 v[20:23], v[56:63], v[160:167], v[206:209], v203, v203 op_sel_hi:[0,0,0]
	v_mfma_scale_f32_16x16x128_f8f6f4 v[12:15], v[0:7], v[168:175], v[210:213], v203, v203 op_sel_hi:[0,0,0]
	v_mfma_scale_f32_16x16x128_f8f6f4 v[4:7], v[56:63], v[168:175], v[226:229], v203, v203 op_sel_hi:[0,0,0]
	s_setprio 0
	s_setprio 1
	v_mfma_scale_f32_16x16x128_f8f6f4 v[60:63], v[128:135], v[144:151], v[230:233], v203, v203 op_sel_hi:[0,0,0]
	v_mfma_scale_f32_16x16x128_f8f6f4 v[56:59], v[136:143], v[144:151], v[234:237], v203, v203 op_sel_hi:[0,0,0]
	v_mfma_scale_f32_16x16x128_f8f6f4 v[40:43], v[128:135], v[152:159], v[40:43], v203, v203 op_sel_hi:[0,0,0]
	v_mfma_scale_f32_16x16x128_f8f6f4 v[32:35], v[136:143], v[152:159], v[238:241], v203, v203 op_sel_hi:[0,0,0]
	v_mfma_scale_f32_16x16x128_f8f6f4 v[24:27], v[128:135], v[160:167], v[242:245], v203, v203 op_sel_hi:[0,0,0]
	v_mfma_scale_f32_16x16x128_f8f6f4 v[16:19], v[136:143], v[160:167], v[246:249], v203, v203 op_sel_hi:[0,0,0]
	v_mfma_scale_f32_16x16x128_f8f6f4 v[8:11], v[128:135], v[168:175], v[250:253], v203, v203 op_sel_hi:[0,0,0]
	v_mfma_scale_f32_16x16x128_f8f6f4 v[0:3], v[136:143], v[168:175], v[180:183], v203, v203 op_sel_hi:[0,0,0]
	s_setprio 0
	s_barrier
	s_add_i32 s74, s74, 2
	s_add_u32 s10, s10, 0x100
	s_addc_u32 s11, s11, 0
	s_add_u32 s72, s72, 0x100
	s_addc_u32 s73, s73, 0
	s_cmp_gt_u32 s74, 5
	s_cbranch_scc0 .LBB0_342
	s_and_b64 vcc, exec, s[38:39]
	s_cbranch_vccz .LBB0_345
	s_barrier

; #define PG8_BAR __builtin_amdgcn_s_barrier()
; template <class Epi, class Sched, bool ALIGN_EPI = false, bool SP2 = false, bool FP8 = false>
; __device__ __forceinline__ void gemm_phase(PG8_LAS unsigned char* lds, const Gemm g, const Sched& S, const Epi& E) {
;     ...
;         if (!has_next) break;
; #pragma unroll
;         for (int a = 0; a < 2; ++a)
; #pragma unroll
;             for (int b = 0; b < 2; ++b)
; #pragma unroll
;                 for (int m = 0; m < 4; ++m)
; #pragma unroll
;                     for (int n = 0; n < 2; ++n) { acc[a][b][m][n] = (f32x4){0.f, 0.f, 0.f, 0.f}; if constexpr (FP8) asm volatile("" : "+v"(acc[a][b][m][n])); }
;         cur = nxt; cA = nA; cB = nB; ++ui;
;         if constexpr (ALIGN_EPI) { if (wr == 1) PG8_BAR; }
.LBB0_361:
	s_or_b64 exec, exec, s[50:51]
	s_andn2_b64 vcc, exec, s[4:5]
	s_mov_b64 s[4:5], -1
	s_cbranch_vccnz .LBB0_338
	s_mov_b32 s9, s8
	s_mov_b32 s10, s8
	s_mov_b32 s11, s8
	s_waitcnt lgkmcnt(0)
	v_mov_b64_e32 v[0:1], s[8:9]
	v_mov_b64_e32 v[118:119], s[10:11]
	v_mov_b64_e32 v[114:115], s[10:11]
	v_mov_b64_e32 v[110:111], s[10:11]
	v_mov_b64_e32 v[102:103], s[10:11]
	v_mov_b64_e32 v[94:95], s[10:11]
	v_mov_b64_e32 v[86:87], s[10:11]
	v_mov_b64_e32 v[78:79], s[10:11]
	v_mov_b64_e32 v[70:71], s[10:11]
	v_mov_b64_e32 v[126:127], s[10:11]
	v_mov_b64_e32 v[122:123], s[10:11]
	v_mov_b64_e32 v[106:107], s[10:11]
	v_mov_b64_e32 v[98:99], s[10:11]
	v_mov_b64_e32 v[90:91], s[10:11]
	v_mov_b64_e32 v[82:83], s[10:11]
	v_mov_b64_e32 v[74:75], s[10:11]
	v_mov_b64_e32 v[66:67], s[10:11]
	v_mov_b64_e32 v[54:55], s[10:11]
	v_mov_b64_e32 v[50:51], s[10:11]
	v_mov_b64_e32 v[46:47], s[10:11]
	v_mov_b64_e32 v[38:39], s[10:11]
	v_mov_b64_e32 v[30:31], s[10:11]
	v_mov_b64_e32 v[22:23], s[10:11]
	v_mov_b64_e32 v[14:15], s[10:11]
	v_mov_b64_e32 v[4:5], s[8:9]
	v_mov_b64_e32 v[62:63], s[10:11]
	v_mov_b64_e32 v[58:59], s[10:11]
	v_mov_b64_e32 v[42:43], s[10:11]
	v_mov_b64_e32 v[34:35], s[10:11]
	v_mov_b64_e32 v[26:27], s[10:11]
	v_mov_b64_e32 v[18:19], s[10:11]
	v_mov_b64_e32 v[8:9], s[8:9]
	v_mov_b64_e32 v[2:3], s[10:11]
	v_mov_b64_e32 v[116:117], s[8:9]
	v_mov_b64_e32 v[112:113], s[8:9]
	v_mov_b64_e32 v[108:109], s[8:9]
	v_mov_b64_e32 v[100:101], s[8:9]
	v_mov_b64_e32 v[92:93], s[8:9]
	v_mov_b64_e32 v[84:85], s[8:9]
	v_mov_b64_e32 v[76:77], s[8:9]
	v_mov_b64_e32 v[68:69], s[8:9]
	v_mov_b64_e32 v[124:125], s[8:9]
	v_mov_b64_e32 v[120:121], s[8:9]
	v_mov_b64_e32 v[104:105], s[8:9]
	v_mov_b64_e32 v[96:97], s[8:9]
	v_mov_b64_e32 v[88:89], s[8:9]
	v_mov_b64_e32 v[80:81], s[8:9]
	v_mov_b64_e32 v[72:73], s[8:9]
	v_mov_b64_e32 v[64:65], s[8:9]
	v_mov_b64_e32 v[52:53], s[8:9]
	v_mov_b64_e32 v[48:49], s[8:9]
	v_mov_b64_e32 v[44:45], s[8:9]
	v_mov_b64_e32 v[36:37], s[8:9]
	v_mov_b64_e32 v[28:29], s[8:9]
	v_mov_b64_e32 v[20:21], s[8:9]
	v_mov_b64_e32 v[12:13], s[8:9]
	v_mov_b64_e32 v[6:7], s[10:11]
	v_mov_b64_e32 v[60:61], s[8:9]
	v_mov_b64_e32 v[56:57], s[8:9]
	v_mov_b64_e32 v[40:41], s[8:9]
	v_mov_b64_e32 v[32:33], s[8:9]
	v_mov_b64_e32 v[24:25], s[8:9]
	v_mov_b64_e32 v[16:17], s[8:9]
	v_mov_b64_e32 v[10:11], s[10:11]
	s_andn2_b64 vcc, exec, s[6:7]
	s_cbranch_vccnz .LBB0_337
	s_mov_b32 s100, 1
	s_branch .LBB0_337

; #define PG8_STAGE(bufoff, gbase, voff) do { _Pragma("unroll") for (int _i = 0; _i < 2; ++_i) { unsigned vo_ = (voff)[_i]; if constexpr (FP8) asm volatile("" : "+v"(vo_)); \
;         __builtin_amdgcn_global_load_lds((const unsigned*)((const char*)(gbase) + vo_), (PG8_LAS unsigned*)(lds + (bufoff) + ldsw + _i * 8192), 16, 0, 0); } } while (0)
; #define PG8_LDA(dst, b, h) do { _Pragma("unroll") for (int m = 0; m < 4; ++m) _Pragma("unroll") for (int k = 0; k < 2; ++k) dst[m][k] = *(const PG8_LAS bf16x8*)(lds + PG8_SA(b, h) + aoff + m * 2048 + k * 1024); } while (0)
; #define PG8_LDB(dst, b, h) do { _Pragma("unroll") for (int n = 0; n < 2; ++n) _Pragma("unroll") for (int k = 0; k < 2; ++k) dst[n][k] = *(const PG8_LAS bf16x8*)(lds + PG8_SB(b, h) + boff + n * 2048 + k * 1024); } while (0)
; template <class Epi, class Sched, bool ALIGN_EPI = false, bool SP2 = false, bool FP8 = false>
; __device__ __forceinline__ void gemm_phase(PG8_LAS unsigned char* lds, const Gemm g, const Sched& S, const Epi& E) {
;     ...
;     for (;;) {
;         const bool has_next = S.next(ui + 1, nxt);
;         const char* nA = has_next ? (const char*)g.A + (size_t)nxt.pm * tstep : cA; const char* nB = has_next ? (const char*)g.Bt + (size_t)nxt.pn * tstep : cB;
; #pragma unroll 1
;         for (int t = 0; t < nt; t += 2) {
;             if constexpr (Epi::MID_T > 0) { if (t == Epi::MID_T) E.mid(acc, cur, wr, wc, fr, fq); }
;             const bool last = (t == nt - 2);
;             const char* a1 = cA + (size_t)(t + 1) * kstep;
;             const char* a2 = last ? nA : cA + (size_t)(t + 2) * kstep; const char* b2 = last ? nB : cB + (size_t)(t + 2) * kstep;
;             const char* a3 = a2 + kstep; const char* b3 = b2 + kstep;
;             if (last && has_next) S.a_ready(nxt);
;             if constexpr (SP2) {
;             PG8_LDB(B0, 0, 0); PG8_LDB(B1, 0, 1); PG8_SCHED; PG8_LDA(At, 0, 0); PG8_STAGE(PG8_SA(1, 1), a1 + hstep, voffA);
;     ...
; #pragma unroll
;         for (int a = 0; a < 2; ++a)
; #pragma unroll
;             for (int b = 0; b < 2; ++b)
; #pragma unroll
;                 for (int m = 0; m < 4; ++m)
; #pragma unroll
;                     for (int n = 0; n < 2; ++n) { acc[a][b][m][n] = (f32x4){0.f, 0.f, 0.f, 0.f}; if constexpr (FP8) asm volatile("" : "+v"(acc[a][b][m][n])); }
;         cur = nxt; cA = nA; cB = nB; ++ui;
;         if constexpr (ALIGN_EPI) { if (wr == 1) PG8_BAR; }
.LBB0_390:
	s_ashr_i32 s15, s14, 31
	s_lshl_b64 s[0:1], s[14:15], 19
	s_add_u32 s34, s16, s0
	s_addc_u32 s35, s17, s1
	s_and_b64 s[0:1], s[4:5], exec
	s_cselect_b32 s15, s35, s41
	s_cselect_b32 s57, s34, s40
	s_ashr_i32 s13, s12, 31
	s_lshl_b64 s[0:1], s[12:13], 19
	s_add_u32 s36, s30, s0
	s_addc_u32 s37, s31, s1
	s_and_b64 s[0:1], s[4:5], exec
	s_cselect_b32 s13, s37, s43
	s_cselect_b32 s58, s36, s42
	s_add_u32 s40, s40, 0x40080
	s_addc_u32 s41, s41, 0
	s_add_u32 s59, s42, 0x100
	v_mov_b32_e32 v0, 0
	s_addc_u32 s60, s43, 0
	s_mov_b32 s61, -2
	v_mov_b32_e32 v1, v0
	v_mov_b32_e32 v2, v0
	v_mov_b32_e32 v3, v0
	v_mov_b32_e32 v4, v0
	v_mov_b32_e32 v5, v0
	v_mov_b32_e32 v6, v0
	v_mov_b32_e32 v7, v0
	v_mov_b32_e32 v16, v0
	v_mov_b32_e32 v17, v0
	v_mov_b32_e32 v18, v0
	v_mov_b32_e32 v19, v0
	v_mov_b32_e32 v20, v0
	v_mov_b32_e32 v21, v0
	v_mov_b32_e32 v22, v0
	v_mov_b32_e32 v23, v0
	v_mov_b32_e32 v32, v0
	v_mov_b32_e32 v33, v0
	v_mov_b32_e32 v34, v0
	v_mov_b32_e32 v35, v0
	v_mov_b32_e32 v36, v0
	v_mov_b32_e32 v37, v0
	v_mov_b32_e32 v38, v0
	v_mov_b32_e32 v39, v0
	v_mov_b32_e32 v48, v0
	v_mov_b32_e32 v49, v0
	v_mov_b32_e32 v50, v0
	v_mov_b32_e32 v51, v0
	v_mov_b32_e32 v52, v0
	v_mov_b32_e32 v53, v0
	v_mov_b32_e32 v54, v0
	v_mov_b32_e32 v55, v0
	v_mov_b32_e32 v8, v0
	v_mov_b32_e32 v9, v0
	v_mov_b32_e32 v10, v0
	v_mov_b32_e32 v11, v0
	v_mov_b32_e32 v12, v0
	v_mov_b32_e32 v13, v0
	v_mov_b32_e32 v14, v0
	v_mov_b32_e32 v15, v0
	v_mov_b32_e32 v24, v0
	v_mov_b32_e32 v25, v0
	v_mov_b32_e32 v26, v0
	v_mov_b32_e32 v27, v0
	v_mov_b32_e32 v28, v0
	v_mov_b32_e32 v29, v0
	v_mov_b32_e32 v30, v0
	v_mov_b32_e32 v31, v0
	v_mov_b32_e32 v40, v0
	v_mov_b32_e32 v41, v0
	v_mov_b32_e32 v42, v0
	v_mov_b32_e32 v43, v0
	v_mov_b32_e32 v44, v0
	v_mov_b32_e32 v45, v0
	v_mov_b32_e32 v46, v0
	v_mov_b32_e32 v47, v0
	v_mov_b32_e32 v56, v0
	v_mov_b32_e32 v57, v0
	v_mov_b32_e32 v58, v0
	v_mov_b32_e32 v59, v0
	v_mov_b32_e32 v60, v0
	v_mov_b32_e32 v61, v0
	v_mov_b32_e32 v62, v0
	v_mov_b32_e32 v63, v0
	v_mov_b32_e32 v64, v0
	v_mov_b32_e32 v65, v0
	v_mov_b32_e32 v66, v0
	v_mov_b32_e32 v67, v0
	v_mov_b32_e32 v68, v0
	v_mov_b32_e32 v69, v0
	v_mov_b32_e32 v70, v0
	v_mov_b32_e32 v71, v0
	v_mov_b32_e32 v80, v0
	v_mov_b32_e32 v81, v0
	v_mov_b32_e32 v82, v0
	v_mov_b32_e32 v83, v0
	v_mov_b32_e32 v84, v0
	v_mov_b32_e32 v85, v0
	v_mov_b32_e32 v86, v0
	v_mov_b32_e32 v87, v0
	v_mov_b32_e32 v96, v0
	v_mov_b32_e32 v97, v0
	v_mov_b32_e32 v98, v0
	v_mov_b32_e32 v99, v0
	v_mov_b32_e32 v100, v0
	v_mov_b32_e32 v101, v0
	v_mov_b32_e32 v102, v0
	v_mov_b32_e32 v103, v0
	v_mov_b32_e32 v112, v0
	v_mov_b32_e32 v113, v0
	v_mov_b32_e32 v114, v0
	v_mov_b32_e32 v115, v0
	v_mov_b32_e32 v116, v0
	v_mov_b32_e32 v117, v0
	v_mov_b32_e32 v118, v0
	v_mov_b32_e32 v119, v0
	v_mov_b32_e32 v72, v0
	v_mov_b32_e32 v73, v0
	v_mov_b32_e32 v74, v0
	v_mov_b32_e32 v75, v0
	v_mov_b32_e32 v76, v0
	v_mov_b32_e32 v77, v0
	v_mov_b32_e32 v78, v0
	v_mov_b32_e32 v79, v0
	v_mov_b32_e32 v88, v0
	v_mov_b32_e32 v89, v0
	v_mov_b32_e32 v90, v0
	v_mov_b32_e32 v91, v0
	v_mov_b32_e32 v92, v0
	v_mov_b32_e32 v93, v0
	v_mov_b32_e32 v94, v0
	v_mov_b32_e32 v95, v0
	v_mov_b32_e32 v104, v0
	v_mov_b32_e32 v105, v0
	v_mov_b32_e32 v106, v0
	v_mov_b32_e32 v107, v0
	v_mov_b32_e32 v108, v0
	v_mov_b32_e32 v109, v0
	v_mov_b32_e32 v110, v0
	v_mov_b32_e32 v111, v0
	v_mov_b32_e32 v120, v0
	v_mov_b32_e32 v121, v0
	v_mov_b32_e32 v122, v0
	v_mov_b32_e32 v123, v0
	v_mov_b32_e32 v124, v0
	v_mov_b32_e32 v125, v0
	v_mov_b32_e32 v126, v0
	v_mov_b32_e32 v127, v0
	s_cmp_eq_u32 s100, 0
	s_cbranch_scc1 .Lmy_nobar_P5
	s_barrier
	s_mov_b32 s100, 0
.Lmy_nobar_P5:
.LBB0_391:
	ds_read_b128 v[146:149], v153
	ds_read_b128 v[158:161], v153 offset:1024
	ds_read_b128 v[162:165], v153 offset:2048
	ds_read_b128 v[166:169], v153 offset:3072
	ds_read_b128 v[170:173], v154
	ds_read_b128 v[174:177], v154 offset:1024
	ds_read_b128 v[178:181], v154 offset:2048
	ds_read_b128 v[182:185], v154 offset:3072
	s_add_u32 s0, s40, 0xfffc0080
	s_addc_u32 s1, s41, -1
	s_cmp_eq_u32 s61, 12
	s_cselect_b32 s45, s15, s1
	s_cselect_b32 s44, s57, s0
	s_cselect_b32 s43, s13, s60
	s_cselect_b32 s42, s58, s59
	v_lshl_add_u64 v[218:219], s[40:41], 0, v[138:139]
	s_add_i32 m0, s39, 0xc000
	ds_read_b128 v[186:189], v155
	ds_read_b128 v[190:193], v155 offset:1024
	ds_read_b128 v[194:197], v155 offset:2048
	ds_read_b128 v[198:201], v155 offset:3072
	ds_read_b128 v[202:205], v155 offset:4096
	ds_read_b128 v[206:209], v155 offset:5120
	ds_read_b128 v[210:213], v155 offset:6144
	ds_read_b128 v[214:217], v155 offset:7168
	global_load_lds_dwordx4 v[218:219], off
	v_lshl_add_u64 v[218:219], s[40:41], 0, v[140:141]
	s_add_i32 m0, s39, 0xe000
	s_nop 0
	global_load_lds_dwordx4 v[218:219], off
	s_waitcnt vmcnt(8)
	s_waitcnt lgkmcnt(0)
	s_barrier
; #define PG8_STAGE(bufoff, gbase, voff) do { _Pragma("unroll") for (int _i = 0; _i < 2; ++_i) { unsigned vo_ = (voff)[_i]; if constexpr (FP8) asm volatile("" : "+v"(vo_)); \
;         __builtin_amdgcn_global_load_lds((const unsigned*)((const char*)(gbase) + vo_), (PG8_LAS unsigned*)(lds + (bufoff) + ldsw + _i * 8192), 16, 0, 0); } } while (0)
; #define PG8_LDA(dst, b, h) do { _Pragma("unroll") for (int m = 0; m < 4; ++m) _Pragma("unroll") for (int k = 0; k < 2; ++k) dst[m][k] = *(const PG8_LAS bf16x8*)(lds + PG8_SA(b, h) + aoff + m * 2048 + k * 1024); } while (0)
; #define PG8_LDB(dst, b, h) do { _Pragma("unroll") for (int n = 0; n < 2; ++n) _Pragma("unroll") for (int k = 0; k < 2; ++k) dst[n][k] = *(const PG8_LAS bf16x8*)(lds + PG8_SB(b, h) + boff + n * 2048 + k * 1024); } while (0)
; #define PG8_WAIT_V(n) asm volatile("s_waitcnt vmcnt(" #n ")" ::: "memory")
; #define PG8_WAIT_L(n) asm volatile("s_waitcnt lgkmcnt(" #n ")" ::: "memory")
; #define PG8_BAR __builtin_amdgcn_s_barrier()
; #define PG8_SCHED __builtin_amdgcn_sched_barrier(0)
; template <class Epi, class Sched, bool ALIGN_EPI = false, bool SP2 = false, bool FP8 = false>
; __device__ __forceinline__ void gemm_phase(PG8_LAS unsigned char* lds, const Gemm g, const Sched& S, const Epi& E) {
;     ...
;             PG8_LDB(B0, 0, 0); PG8_LDB(B1, 0, 1); PG8_SCHED; PG8_LDA(At, 0, 0); PG8_STAGE(PG8_SA(1, 1), a1 + hstep, voffA);
;             PG8_WAIT_V(8); PG8_WAIT_L(0); PG8_BAR; PG8_MMA(0, 0, At, B0); PG8_MMA(0, 1, At, B1); PG8_BAR; PG8_SCHED;
;             PG8_LDA(At, 0, 1); PG8_STAGE(PG8_SB(0, 0), b2, voffB); PG8_STAGE(PG8_SB(0, 1), b2 + hstep, voffB); PG8_STAGE(PG8_SA(0, 0), a2, voffA);
;             PG8_WAIT_V(8); PG8_WAIT_L(0); PG8_BAR; PG8_MMA(1, 0, At, B0); PG8_MMA(1, 1, At, B1); PG8_BAR; PG8_SCHED;
	s_setprio 1
	s_waitcnt lgkmcnt(0)
	v_mfma_f32_16x16x32_bf16 v[124:127], v[146:149], v[186:189], v[124:127]
	v_mfma_f32_16x16x32_bf16 v[120:123], v[162:165], v[186:189], v[120:123]
	v_mfma_f32_16x16x32_bf16 v[108:111], v[146:149], v[194:197], v[108:111]
	v_mfma_f32_16x16x32_bf16 v[104:107], v[162:165], v[194:197], v[104:107]
	v_mfma_f32_16x16x32_bf16 v[92:95], v[146:149], v[202:205], v[92:95]
	v_mfma_f32_16x16x32_bf16 v[88:91], v[162:165], v[202:205], v[88:91]
	v_mfma_f32_16x16x32_bf16 v[76:79], v[146:149], v[210:213], v[76:79]
	v_mfma_f32_16x16x32_bf16 v[72:75], v[162:165], v[210:213], v[72:75]
	v_mfma_f32_16x16x32_bf16 v[124:127], v[158:161], v[190:193], v[124:127]
	v_mfma_f32_16x16x32_bf16 v[120:123], v[166:169], v[190:193], v[120:123]
	v_mfma_f32_16x16x32_bf16 v[108:111], v[158:161], v[198:201], v[108:111]
	v_mfma_f32_16x16x32_bf16 v[104:107], v[166:169], v[198:201], v[104:107]
	v_mfma_f32_16x16x32_bf16 v[92:95], v[158:161], v[206:209], v[92:95]
	v_mfma_f32_16x16x32_bf16 v[88:91], v[166:169], v[206:209], v[88:91]
	v_mfma_f32_16x16x32_bf16 v[76:79], v[158:161], v[214:217], v[76:79]
	v_mfma_f32_16x16x32_bf16 v[72:75], v[166:169], v[214:217], v[72:75]
	s_setprio 0
	s_setprio 1
	v_mfma_f32_16x16x32_bf16 v[116:119], v[170:173], v[186:189], v[116:119]
	v_mfma_f32_16x16x32_bf16 v[112:115], v[178:181], v[186:189], v[112:115]
	v_mfma_f32_16x16x32_bf16 v[100:103], v[170:173], v[194:197], v[100:103]
	v_mfma_f32_16x16x32_bf16 v[96:99], v[178:181], v[194:197], v[96:99]
	v_mfma_f32_16x16x32_bf16 v[84:87], v[170:173], v[202:205], v[84:87]
	v_mfma_f32_16x16x32_bf16 v[80:83], v[178:181], v[202:205], v[80:83]
	v_mfma_f32_16x16x32_bf16 v[68:71], v[170:173], v[210:213], v[68:71]
	v_mfma_f32_16x16x32_bf16 v[64:67], v[178:181], v[210:213], v[64:67]
	v_mfma_f32_16x16x32_bf16 v[116:119], v[174:177], v[190:193], v[116:119]
	v_mfma_f32_16x16x32_bf16 v[112:115], v[182:185], v[190:193], v[112:115]
	v_mfma_f32_16x16x32_bf16 v[100:103], v[174:177], v[198:201], v[100:103]
	v_mfma_f32_16x16x32_bf16 v[96:99], v[182:185], v[198:201], v[96:99]
	v_mfma_f32_16x16x32_bf16 v[84:87], v[174:177], v[206:209], v[84:87]
	v_mfma_f32_16x16x32_bf16 v[80:83], v[182:185], v[206:209], v[80:83]
	v_mfma_f32_16x16x32_bf16 v[68:71], v[174:177], v[214:217], v[68:71]
	v_mfma_f32_16x16x32_bf16 v[64:67], v[182:185], v[214:217], v[64:67]
	s_setprio 0
	s_barrier
	s_add_i32 s0, s54, s46
	v_lshl_add_u64 v[218:219], s[42:43], 0, v[132:133]
	s_mov_b32 m0, s0
	ds_read_b128 v[186:189], v155 offset:16384
	ds_read_b128 v[190:193], v155 offset:17408
	ds_read_b128 v[194:197], v155 offset:18432
	ds_read_b128 v[198:201], v155 offset:19456
	ds_read_b128 v[202:205], v155 offset:20480
	ds_read_b128 v[206:209], v155 offset:21504
	ds_read_b128 v[210:213], v155 offset:22528
	ds_read_b128 v[214:217], v155 offset:23552
	global_load_lds_dwordx4 v[218:219], off
	s_add_i32 m0, s0, 0x2000
	s_add_u32 s0, s42, 0x40000
	v_lshl_add_u64 v[220:221], s[42:43], 0, v[128:129]
	s_addc_u32 s1, s43, 0
	s_add_i32 s62, s55, s46
	global_load_lds_dwordx4 v[220:221], off
	v_lshl_add_u64 v[222:223], s[0:1], 0, v[132:133]
	s_mov_b32 m0, s62
	v_lshl_add_u64 v[224:225], s[44:45], 0, v[130:131]
	global_load_lds_dwordx4 v[222:223], off
	v_lshl_add_u64 v[222:223], s[0:1], 0, v[128:129]
	s_add_i32 m0, s62, 0x2000
	s_nop 0
	global_load_lds_dwordx4 v[222:223], off
	v_lshl_add_u64 v[222:223], s[44:45], 0, v[134:135]
	s_mov_b32 m0, s39
	s_nop 0
	global_load_lds_dwordx4 v[222:223], off
	s_mov_b32 m0, s48
	s_nop 0
	global_load_lds_dwordx4 v[224:225], off
	s_waitcnt vmcnt(8)
	s_waitcnt lgkmcnt(0)
	s_barrier
	s_setprio 1
	s_waitcnt lgkmcnt(0)
	v_mfma_f32_16x16x32_bf16 v[60:63], v[146:149], v[186:189], v[60:63]
	v_mfma_f32_16x16x32_bf16 v[56:59], v[162:165], v[186:189], v[56:59]
	v_mfma_f32_16x16x32_bf16 v[44:47], v[146:149], v[194:197], v[44:47]
	v_mfma_f32_16x16x32_bf16 v[40:43], v[162:165], v[194:197], v[40:43]
	v_mfma_f32_16x16x32_bf16 v[28:31], v[146:149], v[202:205], v[28:31]
	v_mfma_f32_16x16x32_bf16 v[24:27], v[162:165], v[202:205], v[24:27]
	v_mfma_f32_16x16x32_bf16 v[12:15], v[146:149], v[210:213], v[12:15]
	v_mfma_f32_16x16x32_bf16 v[8:11], v[162:165], v[210:213], v[8:11]
	v_mfma_f32_16x16x32_bf16 v[60:63], v[158:161], v[190:193], v[60:63]
	v_mfma_f32_16x16x32_bf16 v[56:59], v[166:169], v[190:193], v[56:59]
	v_mfma_f32_16x16x32_bf16 v[44:47], v[158:161], v[198:201], v[44:47]
	v_mfma_f32_16x16x32_bf16 v[40:43], v[166:169], v[198:201], v[40:43]
	v_mfma_f32_16x16x32_bf16 v[28:31], v[158:161], v[206:209], v[28:31]
	v_mfma_f32_16x16x32_bf16 v[24:27], v[166:169], v[206:209], v[24:27]
	v_mfma_f32_16x16x32_bf16 v[12:15], v[158:161], v[214:217], v[12:15]
	v_mfma_f32_16x16x32_bf16 v[8:11], v[166:169], v[214:217], v[8:11]
	s_setprio 0
	s_setprio 1
	v_mfma_f32_16x16x32_bf16 v[52:55], v[170:173], v[186:189], v[52:55]
	v_mfma_f32_16x16x32_bf16 v[48:51], v[178:181], v[186:189], v[48:51]
	v_mfma_f32_16x16x32_bf16 v[36:39], v[170:173], v[194:197], v[36:39]
	v_mfma_f32_16x16x32_bf16 v[32:35], v[178:181], v[194:197], v[32:35]
	v_mfma_f32_16x16x32_bf16 v[20:23], v[170:173], v[202:205], v[20:23]
	v_mfma_f32_16x16x32_bf16 v[16:19], v[178:181], v[202:205], v[16:19]
	v_mfma_f32_16x16x32_bf16 v[4:7], v[170:173], v[210:213], v[4:7]
	v_mfma_f32_16x16x32_bf16 v[0:3], v[178:181], v[210:213], v[0:3]
	v_mfma_f32_16x16x32_bf16 v[52:55], v[174:177], v[190:193], v[52:55]
	v_mfma_f32_16x16x32_bf16 v[48:51], v[182:185], v[190:193], v[48:51]
	v_mfma_f32_16x16x32_bf16 v[36:39], v[174:177], v[198:201], v[36:39]
	v_mfma_f32_16x16x32_bf16 v[32:35], v[182:185], v[198:201], v[32:35]
	v_mfma_f32_16x16x32_bf16 v[20:23], v[174:177], v[206:209], v[20:23]
	v_mfma_f32_16x16x32_bf16 v[16:19], v[182:185], v[206:209], v[16:19]
	v_mfma_f32_16x16x32_bf16 v[4:7], v[174:177], v[214:217], v[4:7]
	v_mfma_f32_16x16x32_bf16 v[0:3], v[182:185], v[214:217], v[0:3]
	s_setprio 0
	s_barrier
; #define PG8_STAGE(bufoff, gbase, voff) do { _Pragma("unroll") for (int _i = 0; _i < 2; ++_i) { unsigned vo_ = (voff)[_i]; if constexpr (FP8) asm volatile("" : "+v"(vo_)); \
;         __builtin_amdgcn_global_load_lds((const unsigned*)((const char*)(gbase) + vo_), (PG8_LAS unsigned*)(lds + (bufoff) + ldsw + _i * 8192), 16, 0, 0); } } while (0)
; #define PG8_LDA(dst, b, h) do { _Pragma("unroll") for (int m = 0; m < 4; ++m) _Pragma("unroll") for (int k = 0; k < 2; ++k) dst[m][k] = *(const PG8_LAS bf16x8*)(lds + PG8_SA(b, h) + aoff + m * 2048 + k * 1024); } while (0)
; #define PG8_LDB(dst, b, h) do { _Pragma("unroll") for (int n = 0; n < 2; ++n) _Pragma("unroll") for (int k = 0; k < 2; ++k) dst[n][k] = *(const PG8_LAS bf16x8*)(lds + PG8_SB(b, h) + boff + n * 2048 + k * 1024); } while (0)
; #define PG8_WAIT_V(n) asm volatile("s_waitcnt vmcnt(" #n ")" ::: "memory")
; #define PG8_WAIT_L(n) asm volatile("s_waitcnt lgkmcnt(" #n ")" ::: "memory")
; #define PG8_BAR __builtin_amdgcn_s_barrier()
; #define PG8_SCHED __builtin_amdgcn_sched_barrier(0)
; template <class Epi, class Sched, bool ALIGN_EPI = false, bool SP2 = false, bool FP8 = false>
; __device__ __forceinline__ void gemm_phase(PG8_LAS unsigned char* lds, const Gemm g, const Sched& S, const Epi& E) {
;     ...
;             PG8_LDB(B0, 1, 0); PG8_LDB(B1, 1, 1); PG8_SCHED; PG8_LDA(At, 1, 0); PG8_STAGE(PG8_SA(0, 1), a2 + hstep, voffA);
;             PG8_WAIT_V(8); PG8_WAIT_L(0); PG8_BAR; PG8_MMA(0, 0, At, B0); PG8_MMA(0, 1, At, B1); PG8_BAR; PG8_SCHED;
;             PG8_LDA(At, 1, 1); PG8_STAGE(PG8_SB(1, 0), b3, voffB); PG8_STAGE(PG8_SB(1, 1), b3 + hstep, voffB); PG8_STAGE(PG8_SA(1, 0), a3, voffA);
	s_add_i32 s62, 0, 0x18000
	s_add_i32 s63, 0, 0x1c000
	v_add_u32_e32 v166, s62, v151
	v_add_u32_e32 v182, s63, v151
	ds_read_b128 v[146:149], v166
	ds_read_b128 v[158:161], v166 offset:1024
	ds_read_b128 v[162:165], v166 offset:2048
	ds_read_b128 v[166:169], v166 offset:3072
	ds_read_b128 v[170:173], v182
	ds_read_b128 v[174:177], v182 offset:1024
	ds_read_b128 v[178:181], v182 offset:2048
	ds_read_b128 v[182:185], v182 offset:3072
	s_add_u32 s0, s44, 0x40000
	s_addc_u32 s1, s45, 0
	s_mov_b32 m0, s49
	v_lshl_add_u64 v[226:227], s[0:1], 0, v[134:135]
	ds_read_b128 v[186:189], v155 offset:32768
	ds_read_b128 v[190:193], v155 offset:33792
	ds_read_b128 v[194:197], v155 offset:34816
	ds_read_b128 v[198:201], v155 offset:35840
	ds_read_b128 v[202:205], v155 offset:36864
	ds_read_b128 v[206:209], v155 offset:37888
	ds_read_b128 v[210:213], v155 offset:38912
	ds_read_b128 v[214:217], v155 offset:39936
	global_load_lds_dwordx4 v[226:227], off
	v_lshl_add_u64 v[226:227], s[0:1], 0, v[130:131]
	s_mov_b32 m0, s50
	s_nop 0
	global_load_lds_dwordx4 v[226:227], off
	s_waitcnt vmcnt(8)
	s_waitcnt lgkmcnt(0)
	s_barrier
	s_setprio 1
	s_waitcnt lgkmcnt(0)
	v_mfma_f32_16x16x32_bf16 v[124:127], v[146:149], v[186:189], v[124:127]
	v_mfma_f32_16x16x32_bf16 v[120:123], v[162:165], v[186:189], v[120:123]
	v_mfma_f32_16x16x32_bf16 v[108:111], v[146:149], v[194:197], v[108:111]
	v_mfma_f32_16x16x32_bf16 v[104:107], v[162:165], v[194:197], v[104:107]
	v_mfma_f32_16x16x32_bf16 v[92:95], v[146:149], v[202:205], v[92:95]
	v_mfma_f32_16x16x32_bf16 v[88:91], v[162:165], v[202:205], v[88:91]
	v_mfma_f32_16x16x32_bf16 v[76:79], v[146:149], v[210:213], v[76:79]
	v_mfma_f32_16x16x32_bf16 v[72:75], v[162:165], v[210:213], v[72:75]
	v_mfma_f32_16x16x32_bf16 v[124:127], v[158:161], v[190:193], v[124:127]
	v_mfma_f32_16x16x32_bf16 v[120:123], v[166:169], v[190:193], v[120:123]
	v_mfma_f32_16x16x32_bf16 v[108:111], v[158:161], v[198:201], v[108:111]
	v_mfma_f32_16x16x32_bf16 v[104:107], v[166:169], v[198:201], v[104:107]
	v_mfma_f32_16x16x32_bf16 v[92:95], v[158:161], v[206:209], v[92:95]
	v_mfma_f32_16x16x32_bf16 v[88:91], v[166:169], v[206:209], v[88:91]
	v_mfma_f32_16x16x32_bf16 v[76:79], v[158:161], v[214:217], v[76:79]
	v_mfma_f32_16x16x32_bf16 v[72:75], v[166:169], v[214:217], v[72:75]
	s_setprio 0
	s_setprio 1
	v_mfma_f32_16x16x32_bf16 v[116:119], v[170:173], v[186:189], v[116:119]
	v_mfma_f32_16x16x32_bf16 v[112:115], v[178:181], v[186:189], v[112:115]
	v_mfma_f32_16x16x32_bf16 v[100:103], v[170:173], v[194:197], v[100:103]
	v_mfma_f32_16x16x32_bf16 v[96:99], v[178:181], v[194:197], v[96:99]
	v_mfma_f32_16x16x32_bf16 v[84:87], v[170:173], v[202:205], v[84:87]
	v_mfma_f32_16x16x32_bf16 v[80:83], v[178:181], v[202:205], v[80:83]
	v_mfma_f32_16x16x32_bf16 v[68:71], v[170:173], v[210:213], v[68:71]
	v_mfma_f32_16x16x32_bf16 v[64:67], v[178:181], v[210:213], v[64:67]
	v_mfma_f32_16x16x32_bf16 v[116:119], v[174:177], v[190:193], v[116:119]
	v_mfma_f32_16x16x32_bf16 v[112:115], v[182:185], v[190:193], v[112:115]
	v_mfma_f32_16x16x32_bf16 v[100:103], v[174:177], v[198:201], v[100:103]
	v_mfma_f32_16x16x32_bf16 v[96:99], v[182:185], v[198:201], v[96:99]
	v_mfma_f32_16x16x32_bf16 v[84:87], v[174:177], v[206:209], v[84:87]
	v_mfma_f32_16x16x32_bf16 v[80:83], v[182:185], v[206:209], v[80:83]
	v_mfma_f32_16x16x32_bf16 v[68:71], v[174:177], v[214:217], v[68:71]
	v_mfma_f32_16x16x32_bf16 v[64:67], v[182:185], v[214:217], v[64:67]
	s_setprio 0
	s_barrier
	s_add_i32 s0, s62, s46
	v_lshl_add_u64 v[218:219], v[218:219], 0, s[8:9]
	s_mov_b32 m0, s0
	ds_read_b128 v[186:189], v155 offset:49152
	ds_read_b128 v[190:193], v155 offset:50176
	ds_read_b128 v[194:197], v155 offset:51200
	ds_read_b128 v[198:201], v155 offset:52224
	ds_read_b128 v[202:205], v155 offset:53248
	ds_read_b128 v[206:209], v155 offset:54272
	ds_read_b128 v[210:213], v155 offset:55296
	ds_read_b128 v[214:217], v155 offset:56320
	global_load_lds_dwordx4 v[218:219], off
	s_add_i32 m0, s0, 0x2000
	s_add_u32 s0, s42, 0x40080
	v_lshl_add_u64 v[218:219], v[220:221], 0, s[8:9]
	s_addc_u32 s1, s43, 0
	s_add_i32 s42, s63, s46
	global_load_lds_dwordx4 v[218:219], off
	v_lshl_add_u64 v[218:219], s[0:1], 0, v[132:133]
	s_mov_b32 m0, s42
	s_nop 0
	global_load_lds_dwordx4 v[218:219], off
	v_lshl_add_u64 v[218:219], s[0:1], 0, v[128:129]
	s_add_i32 m0, s42, 0x2000
	s_nop 0
	global_load_lds_dwordx4 v[218:219], off
	v_lshl_add_u64 v[218:219], v[222:223], 0, s[8:9]
	s_mov_b32 m0, s52
	s_nop 0
	global_load_lds_dwordx4 v[218:219], off
	v_lshl_add_u64 v[218:219], v[224:225], 0, s[8:9]
	s_mov_b32 m0, s53
	s_nop 0
	global_load_lds_dwordx4 v[218:219], off
	s_waitcnt vmcnt(8)
	s_waitcnt lgkmcnt(0)
	s_barrier
; template <class Epi, class Sched, bool ALIGN_EPI = false, bool SP2 = false, bool FP8 = false>
; __device__ __forceinline__ void gemm_phase(PG8_LAS unsigned char* lds, const Gemm g, const Sched& S, const Epi& E) {
;     ...
;             PG8_WAIT_V(8); PG8_WAIT_L(0); PG8_BAR; PG8_MMA(1, 0, At, B0); PG8_MMA(1, 1, At, B1); PG8_BAR; PG8_SCHED;
;             } else {
;             PG8_LDB(B0, 0, 0); PG8_SCHED; PG8_LDA(At, 0, 0); PG8_STAGE(PG8_SA(1, 1), a1 + hstep, voffA);
;             PG8_WAIT_L(8); PG8_BAR; PG8_WAIT_L(0); PG8_MMA(0, 0, At, B0); PG8_BAR; PG8_SCHED;
;             PG8_LDB(B1, 0, 1); PG8_STAGE(PG8_SB(0, 0), b2, voffB);
;             PG8_BAR; PG8_WAIT_L(0); PG8_MMA(0, 1, At, B1); PG8_BAR;
;             PG8_LDA(At, 0, 1); PG8_STAGE(PG8_SA(0, 0), a2, voffA);
;             PG8_BAR; PG8_WAIT_L(0); PG8_MMA(1, 0, At, B0); PG8_BAR; PG8_SCHED;
;             PG8_STAGE(PG8_SB(0, 1), b2 + hstep, voffB);
;             PG8_WAIT_V(6); PG8_BAR; PG8_MMA(1, 1, At, B1); PG8_BAR;
;             PG8_LDB(B0, 1, 0); PG8_SCHED; PG8_LDA(At, 1, 0); PG8_STAGE(PG8_SA(0, 1), a2 + hstep, voffA);
;             PG8_WAIT_L(8); PG8_BAR; PG8_WAIT_L(0); PG8_MMA(0, 0, At, B0); PG8_BAR; PG8_SCHED;
;             PG8_LDB(B1, 1, 1); PG8_STAGE(PG8_SB(1, 0), b3, voffB);
;             PG8_BAR; PG8_WAIT_L(0); PG8_MMA(0, 1, At, B1); PG8_BAR;
;             PG8_LDA(At, 1, 1); PG8_STAGE(PG8_SA(1, 0), a3, voffA);
;             PG8_BAR; PG8_WAIT_L(0); PG8_MMA(1, 0, At, B0); PG8_BAR; PG8_SCHED;
;             PG8_STAGE(PG8_SB(1, 1), b3 + hstep, voffB);
;             PG8_WAIT_V(6); PG8_BAR; PG8_MMA(1, 1, At, B1); PG8_BAR;
;             }
;         }
;         if constexpr (ALIGN_EPI) { if (wr == 0) PG8_BAR; }
;     __device__ __forceinline__ void operator()(const f32x4 (&acc)[2][2][4][2], const Unit& u, int wr, int wc, int fr, int fq) const {
;     ...
;         for (int ai = 0; ai < 2; ++ai)
; #pragma unroll
;             for (int m = 0; m < 4; ++m) { const size_t r = (size_t)(row0 + ai * HALF + m * 16);
;                 const f32x4 pq = *(const f32x4*)(ssq + r * 16 + 4 * fq);
;                 float ss = (pq[0] + pq[1]) + (pq[2] + pq[3]); ss += __shfl_xor(ss, 16); ss += __shfl_xor(ss, 32);
;                 const float rs = __builtin_amdgcn_rsqf(ss * (1.f / DM) + RMS_EPS);
; #pragma unroll
;                 for (int bj = 0; bj < 2; ++bj) { f32x4 v0 = acc[ai][bj][m][0] * rs, v1 = acc[ai][bj][m][1] * rs;
	s_setprio 1
	s_waitcnt lgkmcnt(0)
	v_mfma_f32_16x16x32_bf16 v[60:63], v[146:149], v[186:189], v[60:63]
	v_mfma_f32_16x16x32_bf16 v[56:59], v[162:165], v[186:189], v[56:59]
	v_mfma_f32_16x16x32_bf16 v[44:47], v[146:149], v[194:197], v[44:47]
	v_mfma_f32_16x16x32_bf16 v[40:43], v[162:165], v[194:197], v[40:43]
	v_mfma_f32_16x16x32_bf16 v[28:31], v[146:149], v[202:205], v[28:31]
	v_mfma_f32_16x16x32_bf16 v[24:27], v[162:165], v[202:205], v[24:27]
	v_mfma_f32_16x16x32_bf16 v[12:15], v[146:149], v[210:213], v[12:15]
	v_mfma_f32_16x16x32_bf16 v[8:11], v[162:165], v[210:213], v[8:11]
	v_mfma_f32_16x16x32_bf16 v[60:63], v[158:161], v[190:193], v[60:63]
	v_mfma_f32_16x16x32_bf16 v[56:59], v[166:169], v[190:193], v[56:59]
	v_mfma_f32_16x16x32_bf16 v[44:47], v[158:161], v[198:201], v[44:47]
	v_mfma_f32_16x16x32_bf16 v[40:43], v[166:169], v[198:201], v[40:43]
	v_mfma_f32_16x16x32_bf16 v[28:31], v[158:161], v[206:209], v[28:31]
	v_mfma_f32_16x16x32_bf16 v[24:27], v[166:169], v[206:209], v[24:27]
	v_mfma_f32_16x16x32_bf16 v[12:15], v[158:161], v[214:217], v[12:15]
	v_mfma_f32_16x16x32_bf16 v[8:11], v[166:169], v[214:217], v[8:11]
	s_setprio 0
	s_setprio 1
	v_mfma_f32_16x16x32_bf16 v[52:55], v[170:173], v[186:189], v[52:55]
	v_mfma_f32_16x16x32_bf16 v[48:51], v[178:181], v[186:189], v[48:51]
	v_mfma_f32_16x16x32_bf16 v[36:39], v[170:173], v[194:197], v[36:39]
	v_mfma_f32_16x16x32_bf16 v[32:35], v[178:181], v[194:197], v[32:35]
	v_mfma_f32_16x16x32_bf16 v[20:23], v[170:173], v[202:205], v[20:23]
	v_mfma_f32_16x16x32_bf16 v[16:19], v[178:181], v[202:205], v[16:19]
	v_mfma_f32_16x16x32_bf16 v[4:7], v[170:173], v[210:213], v[4:7]
	v_mfma_f32_16x16x32_bf16 v[0:3], v[178:181], v[210:213], v[0:3]
	v_mfma_f32_16x16x32_bf16 v[52:55], v[174:177], v[190:193], v[52:55]
	v_mfma_f32_16x16x32_bf16 v[48:51], v[182:185], v[190:193], v[48:51]
	v_mfma_f32_16x16x32_bf16 v[36:39], v[174:177], v[198:201], v[36:39]
	v_mfma_f32_16x16x32_bf16 v[32:35], v[182:185], v[198:201], v[32:35]
	v_mfma_f32_16x16x32_bf16 v[20:23], v[174:177], v[206:209], v[20:23]
	v_mfma_f32_16x16x32_bf16 v[16:19], v[182:185], v[206:209], v[16:19]
	v_mfma_f32_16x16x32_bf16 v[4:7], v[174:177], v[214:217], v[4:7]
	v_mfma_f32_16x16x32_bf16 v[0:3], v[182:185], v[214:217], v[0:3]
	s_setprio 0
	s_barrier
	s_add_i32 s61, s61, 2
	s_add_u32 s40, s40, 0x100
	s_addc_u32 s41, s41, 0
	s_add_u32 s59, s59, 0x100
	s_addc_u32 s60, s60, 0
	s_cmp_gt_u32 s61, 13
	s_cbranch_scc0 .LBB0_391
	s_and_b64 vcc, exec, s[10:11]
	s_cbranch_vccz .LBB0_394
	s_barrier
.LBB0_394:
	v_lshl_add_u32 v148, s38, 8, v150
	v_ashrrev_i32_e32 v149, 31, v148
	v_lshlrev_b64 v[146:147], 6, v[148:149]
	v_lshl_add_u64 v[146:147], v[136:137], 0, v[146:147]
	s_mov_b64 s[0:1], 0x2000
	global_load_dwordx4 v[170:173], v[146:147], off
	global_load_dwordx4 v[174:177], v[146:147], off offset:1024
	global_load_dwordx4 v[178:181], v[146:147], off offset:2048
	global_load_dwordx4 v[182:185], v[146:147], off offset:3072
	v_lshl_add_u64 v[202:203], v[146:147], 0, s[0:1]
	global_load_dwordx4 v[186:189], v[202:203], off
	global_load_dwordx4 v[190:193], v[202:203], off offset:1024
	global_load_dwordx4 v[194:197], v[202:203], off offset:2048
	global_load_dwordx4 v[198:201], v[202:203], off offset:3072
	v_and_b32_e32 v147, 64, v156
	v_xor_b32_e32 v158, 16, v156
	v_add_u32_e32 v166, 64, v147
	v_cmp_lt_i32_e32 vcc, v158, v166
	v_xor_b32_e32 v159, 32, v156
	v_lshl_or_b32 v146, s56, 8, v152
	v_cndmask_b32_e32 v158, v156, v158, vcc
	v_lshlrev_b32_e32 v158, 2, v158
	v_cmp_lt_i32_e32 vcc, v159, v166
	v_ashrrev_i32_e32 v147, 31, v146
	v_lshlrev_b64 v[146:147], 1, v[146:147]
	v_cndmask_b32_e32 v159, v156, v159, vcc
	v_lshlrev_b32_e32 v159, 2, v159
	s_andn2_b64 vcc, exec, s[4:5]
	s_mov_b64 s[4:5], -1
	s_waitcnt vmcnt(7)
	s_nop 1
	v_add_f32_e32 v160, v170, v171
	v_add_f32_e32 v161, v172, v173
	s_nop 0
	v_add_f32_e32 v161, v160, v161
	ds_bpermute_b32 v162, v158, v161
	v_or_b32_e32 v160, 16, v148
	s_waitcnt lgkmcnt(0)
	v_add_f32_e32 v164, v161, v162
	ds_bpermute_b32 v165, v159, v164
	v_lshlrev_b64 v[162:163], 13, v[148:149]
	v_ashrrev_i32_e32 v161, 31, v160
	v_lshl_add_u64 v[162:163], s[28:29], 0, v[162:163]
	v_lshlrev_b64 v[166:167], 6, v[160:161]
	s_waitcnt lgkmcnt(0)
	v_add_f32_e32 v149, v164, v165
	v_fmamk_f32 v149, v149, 0x3a800000, v157
	v_rsq_f32_e32 v164, v149
	v_lshl_add_u64 v[162:163], v[162:163], 0, v[146:147]
	v_lshl_add_u64 v[166:167], v[136:137], 0, v[166:167]
	v_pk_mul_f32 v[126:127], v[126:127], v[164:165] op_sel_hi:[1,0]
	v_pk_mul_f32 v[124:125], v[124:125], v[164:165] op_sel_hi:[1,0]
	v_pk_mul_f32 v[122:123], v[122:123], v[164:165] op_sel_hi:[1,0]
	v_pk_mul_f32 v[120:121], v[120:121], v[164:165] op_sel_hi:[1,0]
	v_pk_mul_f32 v[118:119], v[118:119], v[164:165] op_sel_hi:[1,0]
	v_pk_mul_f32 v[116:117], v[116:117], v[164:165] op_sel_hi:[1,0]
	v_pk_mul_f32 v[114:115], v[114:115], v[164:165] op_sel_hi:[1,0]
	v_pk_mul_f32 v[112:113], v[112:113], v[164:165] op_sel_hi:[1,0]
	v_max_f32_e32 v124, 0, v124
	v_max_f32_e32 v120, 0, v120
	v_max_f32_e32 v125, 0, v125
	v_max_f32_e32 v121, 0, v121
	v_max_f32_e32 v126, 0, v126
	v_max_f32_e32 v122, 0, v122
	v_max_f32_e32 v127, 0, v127
	v_max_f32_e32 v123, 0, v123
	v_max_f32_e32 v116, 0, v116
	v_max_f32_e32 v112, 0, v112
	v_max_f32_e32 v117, 0, v117
	v_max_f32_e32 v113, 0, v113
	v_max_f32_e32 v118, 0, v118
	v_max_f32_e32 v114, 0, v114
	v_max_f32_e32 v119, 0, v119
	v_max_f32_e32 v115, 0, v115
	v_pk_mul_f32 v[124:125], v[124:125], v[124:125]
	v_pk_mul_f32 v[120:121], v[120:121], v[120:121]
	v_pk_mul_f32 v[126:127], v[126:127], v[126:127]
	v_pk_mul_f32 v[122:123], v[122:123], v[122:123]
	v_pk_mul_f32 v[116:117], v[116:117], v[116:117]
	v_pk_mul_f32 v[164:165], v[112:113], v[112:113]
	v_pk_mul_f32 v[118:119], v[118:119], v[118:119]
	v_pk_mul_f32 v[168:169], v[114:115], v[114:115]
	v_cvt_pk_bf16_f32 v112, v124, v125
	v_cvt_pk_bf16_f32 v113, v126, v127
	v_cvt_pk_bf16_f32 v114, v120, v121
	v_cvt_pk_bf16_f32 v115, v122, v123
	v_cvt_pk_bf16_f32 v116, v116, v117
	v_cvt_pk_bf16_f32 v117, v118, v119
	v_cvt_pk_bf16_f32 v118, v164, v165
	v_cvt_pk_bf16_f32 v119, v168, v169
	global_store_dwordx4 v[162:163], v[112:115], off
	global_store_dwordx4 v[162:163], v[116:119], off offset:256
	s_waitcnt vmcnt(8)
; __device__ __forceinline__ unsigned cvt_pk_bf16(float lo, float hi) { const f32x2c_t v = {lo, hi}; const bf16x2c_t b = __builtin_convertvector(v, bf16x2c_t); return __builtin_bit_cast(unsigned, b); }
;     __device__ __forceinline__ void operator()(const f32x4 (&acc)[2][2][4][2], const Unit& u, int wr, int wc, int fr, int fq) const {
;     ...
;             for (int m = 0; m < 4; ++m) { const size_t r = (size_t)(row0 + ai * HALF + m * 16);
;                 const f32x4 pq = *(const f32x4*)(ssq + r * 16 + 4 * fq);
;                 float ss = (pq[0] + pq[1]) + (pq[2] + pq[3]); ss += __shfl_xor(ss, 16); ss += __shfl_xor(ss, 32);
;                 const float rs = __builtin_amdgcn_rsqf(ss * (1.f / DM) + RMS_EPS);
; #pragma unroll
;                 for (int bj = 0; bj < 2; ++bj) { f32x4 v0 = acc[ai][bj][m][0] * rs, v1 = acc[ai][bj][m][1] * rs;
; #pragma unroll
;                     for (int e = 0; e < 4; ++e) { const float a = fmaxf(v0[e], 0.f), b = fmaxf(v1[e], 0.f); v0[e] = a * a; v1[e] = b * b; }
;                     u32x4 w; w.x = cvt_pk_bf16(v0[0], v0[1]); w.y = cvt_pk_bf16(v0[2], v0[3]); w.z = cvt_pk_bf16(v1[0], v1[1]); w.w = cvt_pk_bf16(v1[2], v1[3]);
;                     *(u32x4*)(O + r * DFF + col0 + bj * HALF) = w; } }
	s_nop 1
	v_add_f32_e32 v112, v174, v175
	v_add_f32_e32 v113, v176, v177
	v_lshlrev_b64 v[114:115], 13, v[160:161]
	v_add_f32_e32 v112, v112, v113
	ds_bpermute_b32 v113, v158, v112
	v_lshl_add_u64 v[114:115], s[28:29], 0, v[114:115]
	v_lshl_add_u64 v[114:115], v[114:115], 0, v[146:147]
	s_waitcnt lgkmcnt(0)
	v_add_f32_e32 v118, v112, v113
	ds_bpermute_b32 v119, v159, v118
	v_or_b32_e32 v112, 32, v148
	v_ashrrev_i32_e32 v113, 31, v112
	v_lshlrev_b64 v[116:117], 6, v[112:113]
	v_lshl_add_u64 v[116:117], v[136:137], 0, v[116:117]
	s_waitcnt lgkmcnt(0)
	v_add_f32_e32 v118, v118, v119
	v_fmamk_f32 v118, v118, 0x3a800000, v157
	v_rsq_f32_e32 v118, v118
	s_nop 0
	v_pk_mul_f32 v[110:111], v[110:111], v[118:119] op_sel_hi:[1,0]
	v_pk_mul_f32 v[108:109], v[108:109], v[118:119] op_sel_hi:[1,0]
	v_pk_mul_f32 v[106:107], v[106:107], v[118:119] op_sel_hi:[1,0]
	v_pk_mul_f32 v[104:105], v[104:105], v[118:119] op_sel_hi:[1,0]
	v_pk_mul_f32 v[102:103], v[102:103], v[118:119] op_sel_hi:[1,0]
	v_pk_mul_f32 v[100:101], v[100:101], v[118:119] op_sel_hi:[1,0]
	v_pk_mul_f32 v[98:99], v[98:99], v[118:119] op_sel_hi:[1,0]
	v_pk_mul_f32 v[96:97], v[96:97], v[118:119] op_sel_hi:[1,0]
	v_max_f32_e32 v108, 0, v108
	v_max_f32_e32 v104, 0, v104
	v_max_f32_e32 v109, 0, v109
	v_max_f32_e32 v105, 0, v105
	v_max_f32_e32 v110, 0, v110
	v_max_f32_e32 v106, 0, v106
	v_max_f32_e32 v111, 0, v111
	v_max_f32_e32 v107, 0, v107
	v_max_f32_e32 v100, 0, v100
	v_max_f32_e32 v96, 0, v96
	v_max_f32_e32 v101, 0, v101
	v_max_f32_e32 v97, 0, v97
	v_max_f32_e32 v102, 0, v102
	v_max_f32_e32 v98, 0, v98
	v_max_f32_e32 v103, 0, v103
	v_max_f32_e32 v99, 0, v99
	v_pk_mul_f32 v[108:109], v[108:109], v[108:109]
	v_pk_mul_f32 v[104:105], v[104:105], v[104:105]
	v_pk_mul_f32 v[110:111], v[110:111], v[110:111]
	v_pk_mul_f32 v[106:107], v[106:107], v[106:107]
	v_pk_mul_f32 v[100:101], v[100:101], v[100:101]
	v_pk_mul_f32 v[118:119], v[96:97], v[96:97]
	v_pk_mul_f32 v[102:103], v[102:103], v[102:103]
	v_pk_mul_f32 v[120:121], v[98:99], v[98:99]
	v_cvt_pk_bf16_f32 v96, v108, v109
	v_cvt_pk_bf16_f32 v97, v110, v111
	v_cvt_pk_bf16_f32 v98, v104, v105
	v_cvt_pk_bf16_f32 v99, v106, v107
	v_cvt_pk_bf16_f32 v100, v100, v101
	v_cvt_pk_bf16_f32 v101, v102, v103
	v_cvt_pk_bf16_f32 v102, v118, v119
	v_cvt_pk_bf16_f32 v103, v120, v121
	global_store_dwordx4 v[114:115], v[96:99], off
	global_store_dwordx4 v[114:115], v[100:103], off offset:256
	s_waitcnt vmcnt(9)
	s_nop 1
	v_add_f32_e32 v96, v178, v179
	v_add_f32_e32 v97, v180, v181
	v_lshlrev_b64 v[98:99], 13, v[112:113]
	v_add_f32_e32 v96, v96, v97
	ds_bpermute_b32 v97, v158, v96
	v_lshl_add_u64 v[98:99], s[28:29], 0, v[98:99]
	v_lshl_add_u64 v[98:99], v[98:99], 0, v[146:147]
	s_waitcnt lgkmcnt(0)
	v_add_f32_e32 v102, v96, v97
	ds_bpermute_b32 v103, v159, v102
	v_or_b32_e32 v96, 48, v148
	v_ashrrev_i32_e32 v97, 31, v96
	v_lshlrev_b64 v[100:101], 6, v[96:97]
	v_lshl_add_u64 v[100:101], v[136:137], 0, v[100:101]
	s_waitcnt lgkmcnt(0)
	v_add_f32_e32 v102, v102, v103
	v_fmamk_f32 v102, v102, 0x3a800000, v157
	v_rsq_f32_e32 v102, v102
	s_nop 0
	v_pk_mul_f32 v[94:95], v[94:95], v[102:103] op_sel_hi:[1,0]
	v_pk_mul_f32 v[92:93], v[92:93], v[102:103] op_sel_hi:[1,0]
	v_pk_mul_f32 v[90:91], v[90:91], v[102:103] op_sel_hi:[1,0]
	v_pk_mul_f32 v[88:89], v[88:89], v[102:103] op_sel_hi:[1,0]
	v_pk_mul_f32 v[86:87], v[86:87], v[102:103] op_sel_hi:[1,0]
	v_pk_mul_f32 v[84:85], v[84:85], v[102:103] op_sel_hi:[1,0]
	v_pk_mul_f32 v[82:83], v[82:83], v[102:103] op_sel_hi:[1,0]
	v_pk_mul_f32 v[80:81], v[80:81], v[102:103] op_sel_hi:[1,0]
	v_max_f32_e32 v92, 0, v92
	v_max_f32_e32 v88, 0, v88
	v_max_f32_e32 v93, 0, v93
	v_max_f32_e32 v89, 0, v89
	v_max_f32_e32 v94, 0, v94
	v_max_f32_e32 v90, 0, v90
	v_max_f32_e32 v95, 0, v95
	v_max_f32_e32 v91, 0, v91
	v_max_f32_e32 v84, 0, v84
	v_max_f32_e32 v80, 0, v80
	v_max_f32_e32 v85, 0, v85
	v_max_f32_e32 v81, 0, v81
	v_max_f32_e32 v86, 0, v86
	v_max_f32_e32 v82, 0, v82
	v_max_f32_e32 v87, 0, v87
	v_max_f32_e32 v83, 0, v83
	v_pk_mul_f32 v[92:93], v[92:93], v[92:93]
	v_pk_mul_f32 v[88:89], v[88:89], v[88:89]
	v_pk_mul_f32 v[94:95], v[94:95], v[94:95]
	v_pk_mul_f32 v[90:91], v[90:91], v[90:91]
	v_pk_mul_f32 v[84:85], v[84:85], v[84:85]
	v_pk_mul_f32 v[102:103], v[80:81], v[80:81]
	v_pk_mul_f32 v[86:87], v[86:87], v[86:87]
	v_pk_mul_f32 v[104:105], v[82:83], v[82:83]
	v_cvt_pk_bf16_f32 v80, v92, v93
	v_cvt_pk_bf16_f32 v81, v94, v95
	v_cvt_pk_bf16_f32 v82, v88, v89
	v_cvt_pk_bf16_f32 v83, v90, v91
	v_cvt_pk_bf16_f32 v84, v84, v85
	v_cvt_pk_bf16_f32 v85, v86, v87
	v_cvt_pk_bf16_f32 v86, v102, v103
	v_cvt_pk_bf16_f32 v87, v104, v105
	global_store_dwordx4 v[98:99], v[80:83], off
	global_store_dwordx4 v[98:99], v[84:87], off offset:256
	s_waitcnt vmcnt(10)
	s_nop 1
	v_add_f32_e32 v80, v182, v183
	v_add_f32_e32 v81, v184, v185
	v_lshlrev_b64 v[82:83], 13, v[96:97]
	v_add_f32_e32 v80, v80, v81
	ds_bpermute_b32 v81, v158, v80
	v_lshl_add_u64 v[82:83], s[28:29], 0, v[82:83]
	v_lshl_add_u64 v[82:83], v[82:83], 0, v[146:147]
	s_waitcnt lgkmcnt(0)
	v_add_f32_e32 v86, v80, v81
	ds_bpermute_b32 v87, v159, v86
	v_add_u32_e32 v80, 0x80, v148
	v_ashrrev_i32_e32 v81, 31, v80
	v_lshlrev_b64 v[84:85], 6, v[80:81]
	v_lshl_add_u64 v[84:85], v[136:137], 0, v[84:85]
	s_waitcnt lgkmcnt(0)
; __device__ __forceinline__ unsigned cvt_pk_bf16(float lo, float hi) { const f32x2c_t v = {lo, hi}; const bf16x2c_t b = __builtin_convertvector(v, bf16x2c_t); return __builtin_bit_cast(unsigned, b); }
;     __device__ __forceinline__ void operator()(const f32x4 (&acc)[2][2][4][2], const Unit& u, int wr, int wc, int fr, int fq) const {
;     ...
;             for (int m = 0; m < 4; ++m) { const size_t r = (size_t)(row0 + ai * HALF + m * 16);
;                 const f32x4 pq = *(const f32x4*)(ssq + r * 16 + 4 * fq);
;                 float ss = (pq[0] + pq[1]) + (pq[2] + pq[3]); ss += __shfl_xor(ss, 16); ss += __shfl_xor(ss, 32);
;                 const float rs = __builtin_amdgcn_rsqf(ss * (1.f / DM) + RMS_EPS);
; #pragma unroll
;                 for (int bj = 0; bj < 2; ++bj) { f32x4 v0 = acc[ai][bj][m][0] * rs, v1 = acc[ai][bj][m][1] * rs;
; #pragma unroll
;                     for (int e = 0; e < 4; ++e) { const float a = fmaxf(v0[e], 0.f), b = fmaxf(v1[e], 0.f); v0[e] = a * a; v1[e] = b * b; }
;                     u32x4 w; w.x = cvt_pk_bf16(v0[0], v0[1]); w.y = cvt_pk_bf16(v0[2], v0[3]); w.z = cvt_pk_bf16(v1[0], v1[1]); w.w = cvt_pk_bf16(v1[2], v1[3]);
;                     *(u32x4*)(O + r * DFF + col0 + bj * HALF) = w; } }
	v_add_f32_e32 v86, v86, v87
	v_fmamk_f32 v86, v86, 0x3a800000, v157
	v_rsq_f32_e32 v86, v86
	s_nop 0
	v_pk_mul_f32 v[78:79], v[78:79], v[86:87] op_sel_hi:[1,0]
	v_pk_mul_f32 v[76:77], v[76:77], v[86:87] op_sel_hi:[1,0]
	v_pk_mul_f32 v[74:75], v[74:75], v[86:87] op_sel_hi:[1,0]
	v_pk_mul_f32 v[72:73], v[72:73], v[86:87] op_sel_hi:[1,0]
	v_pk_mul_f32 v[70:71], v[70:71], v[86:87] op_sel_hi:[1,0]
	v_pk_mul_f32 v[68:69], v[68:69], v[86:87] op_sel_hi:[1,0]
	v_pk_mul_f32 v[66:67], v[66:67], v[86:87] op_sel_hi:[1,0]
	v_pk_mul_f32 v[64:65], v[64:65], v[86:87] op_sel_hi:[1,0]
	v_max_f32_e32 v76, 0, v76
	v_max_f32_e32 v72, 0, v72
	v_max_f32_e32 v77, 0, v77
	v_max_f32_e32 v73, 0, v73
	v_max_f32_e32 v78, 0, v78
	v_max_f32_e32 v74, 0, v74
	v_max_f32_e32 v79, 0, v79
	v_max_f32_e32 v75, 0, v75
	v_max_f32_e32 v68, 0, v68
	v_max_f32_e32 v64, 0, v64
	v_max_f32_e32 v69, 0, v69
	v_max_f32_e32 v65, 0, v65
	v_max_f32_e32 v70, 0, v70
	v_max_f32_e32 v66, 0, v66
	v_max_f32_e32 v71, 0, v71
	v_max_f32_e32 v67, 0, v67
	v_pk_mul_f32 v[76:77], v[76:77], v[76:77]
	v_pk_mul_f32 v[72:73], v[72:73], v[72:73]
	v_pk_mul_f32 v[78:79], v[78:79], v[78:79]
	v_pk_mul_f32 v[74:75], v[74:75], v[74:75]
	v_pk_mul_f32 v[68:69], v[68:69], v[68:69]
	v_pk_mul_f32 v[86:87], v[64:65], v[64:65]
	v_pk_mul_f32 v[70:71], v[70:71], v[70:71]
	v_pk_mul_f32 v[88:89], v[66:67], v[66:67]
	v_cvt_pk_bf16_f32 v64, v76, v77
	v_cvt_pk_bf16_f32 v65, v78, v79
	v_cvt_pk_bf16_f32 v66, v72, v73
	v_cvt_pk_bf16_f32 v67, v74, v75
	v_cvt_pk_bf16_f32 v68, v68, v69
	v_cvt_pk_bf16_f32 v69, v70, v71
	v_cvt_pk_bf16_f32 v70, v86, v87
	v_cvt_pk_bf16_f32 v71, v88, v89
	global_store_dwordx4 v[82:83], v[64:67], off
	global_store_dwordx4 v[82:83], v[68:71], off offset:256
	s_waitcnt vmcnt(11)
	s_nop 1
	v_add_f32_e32 v64, v186, v187
	v_add_f32_e32 v65, v188, v189
	v_lshlrev_b64 v[66:67], 13, v[80:81]
	v_add_f32_e32 v64, v64, v65
	ds_bpermute_b32 v65, v158, v64
	v_lshl_add_u64 v[66:67], s[28:29], 0, v[66:67]
	v_lshl_add_u64 v[66:67], v[66:67], 0, v[146:147]
	s_waitcnt lgkmcnt(0)
	v_add_f32_e32 v70, v64, v65
	ds_bpermute_b32 v71, v159, v70
	v_add_u32_e32 v64, 0x90, v148
	v_ashrrev_i32_e32 v65, 31, v64
	v_lshlrev_b64 v[68:69], 6, v[64:65]
	v_lshl_add_u64 v[68:69], v[136:137], 0, v[68:69]
	s_waitcnt lgkmcnt(0)
	v_add_f32_e32 v70, v70, v71
	v_fmamk_f32 v70, v70, 0x3a800000, v157
	v_rsq_f32_e32 v70, v70
	s_nop 0
	v_pk_mul_f32 v[62:63], v[62:63], v[70:71] op_sel_hi:[1,0]
	v_pk_mul_f32 v[60:61], v[60:61], v[70:71] op_sel_hi:[1,0]
	v_pk_mul_f32 v[58:59], v[58:59], v[70:71] op_sel_hi:[1,0]
	v_pk_mul_f32 v[56:57], v[56:57], v[70:71] op_sel_hi:[1,0]
	v_pk_mul_f32 v[54:55], v[54:55], v[70:71] op_sel_hi:[1,0]
	v_pk_mul_f32 v[52:53], v[52:53], v[70:71] op_sel_hi:[1,0]
	v_pk_mul_f32 v[50:51], v[50:51], v[70:71] op_sel_hi:[1,0]
	v_pk_mul_f32 v[48:49], v[48:49], v[70:71] op_sel_hi:[1,0]
	v_max_f32_e32 v60, 0, v60
	v_max_f32_e32 v56, 0, v56
	v_max_f32_e32 v61, 0, v61
	v_max_f32_e32 v57, 0, v57
	v_max_f32_e32 v62, 0, v62
	v_max_f32_e32 v58, 0, v58
	v_max_f32_e32 v63, 0, v63
	v_max_f32_e32 v59, 0, v59
	v_max_f32_e32 v52, 0, v52
	v_max_f32_e32 v48, 0, v48
	v_max_f32_e32 v53, 0, v53
	v_max_f32_e32 v49, 0, v49
	v_max_f32_e32 v54, 0, v54
	v_max_f32_e32 v50, 0, v50
	v_max_f32_e32 v55, 0, v55
	v_max_f32_e32 v51, 0, v51
	v_pk_mul_f32 v[60:61], v[60:61], v[60:61]
	v_pk_mul_f32 v[56:57], v[56:57], v[56:57]
	v_pk_mul_f32 v[62:63], v[62:63], v[62:63]
	v_pk_mul_f32 v[58:59], v[58:59], v[58:59]
	v_pk_mul_f32 v[52:53], v[52:53], v[52:53]
	v_pk_mul_f32 v[70:71], v[48:49], v[48:49]
	v_pk_mul_f32 v[54:55], v[54:55], v[54:55]
	v_pk_mul_f32 v[72:73], v[50:51], v[50:51]
	v_cvt_pk_bf16_f32 v48, v60, v61
	v_cvt_pk_bf16_f32 v49, v62, v63
	v_cvt_pk_bf16_f32 v50, v56, v57
	v_cvt_pk_bf16_f32 v51, v58, v59
	v_cvt_pk_bf16_f32 v52, v52, v53
	v_cvt_pk_bf16_f32 v53, v54, v55
	v_cvt_pk_bf16_f32 v54, v70, v71
	v_cvt_pk_bf16_f32 v55, v72, v73
	global_store_dwordx4 v[66:67], v[48:51], off
	global_store_dwordx4 v[66:67], v[52:55], off offset:256
	s_waitcnt vmcnt(12)
	s_nop 1
	v_add_f32_e32 v48, v190, v191
	v_add_f32_e32 v49, v192, v193
	v_lshlrev_b64 v[50:51], 13, v[64:65]
	v_add_f32_e32 v48, v48, v49
	ds_bpermute_b32 v49, v158, v48
	v_lshl_add_u64 v[50:51], s[28:29], 0, v[50:51]
	v_lshl_add_u64 v[50:51], v[50:51], 0, v[146:147]
	s_waitcnt lgkmcnt(0)
	v_add_f32_e32 v54, v48, v49
	ds_bpermute_b32 v55, v159, v54
	v_add_u32_e32 v48, 0xa0, v148
	v_ashrrev_i32_e32 v49, 31, v48
	v_lshlrev_b64 v[52:53], 6, v[48:49]
	v_lshl_add_u64 v[52:53], v[136:137], 0, v[52:53]
	s_waitcnt lgkmcnt(0)
; __device__ __forceinline__ unsigned cvt_pk_bf16(float lo, float hi) { const f32x2c_t v = {lo, hi}; const bf16x2c_t b = __builtin_convertvector(v, bf16x2c_t); return __builtin_bit_cast(unsigned, b); }
; #define PG8_BAR __builtin_amdgcn_s_barrier()
; template <class Epi, class Sched, bool ALIGN_EPI = false, bool SP2 = false, bool FP8 = false>
; __device__ __forceinline__ void gemm_phase(PG8_LAS unsigned char* lds, const Gemm g, const Sched& S, const Epi& E) {
;     ...
;         if constexpr (ALIGN_EPI) { if (wr == 1) PG8_BAR; }
;     __device__ __forceinline__ void operator()(const f32x4 (&acc)[2][2][4][2], const Unit& u, int wr, int wc, int fr, int fq) const {
;     ...
;             for (int m = 0; m < 4; ++m) { const size_t r = (size_t)(row0 + ai * HALF + m * 16);
;                 const f32x4 pq = *(const f32x4*)(ssq + r * 16 + 4 * fq);
;                 float ss = (pq[0] + pq[1]) + (pq[2] + pq[3]); ss += __shfl_xor(ss, 16); ss += __shfl_xor(ss, 32);
;                 const float rs = __builtin_amdgcn_rsqf(ss * (1.f / DM) + RMS_EPS);
; #pragma unroll
;                 for (int bj = 0; bj < 2; ++bj) { f32x4 v0 = acc[ai][bj][m][0] * rs, v1 = acc[ai][bj][m][1] * rs;
; #pragma unroll
;                     for (int e = 0; e < 4; ++e) { const float a = fmaxf(v0[e], 0.f), b = fmaxf(v1[e], 0.f); v0[e] = a * a; v1[e] = b * b; }
;                     u32x4 w; w.x = cvt_pk_bf16(v0[0], v0[1]); w.y = cvt_pk_bf16(v0[2], v0[3]); w.z = cvt_pk_bf16(v1[0], v1[1]); w.w = cvt_pk_bf16(v1[2], v1[3]);
;                     *(u32x4*)(O + r * DFF + col0 + bj * HALF) = w; } }
	v_add_f32_e32 v54, v54, v55
	v_fmamk_f32 v54, v54, 0x3a800000, v157
	v_rsq_f32_e32 v54, v54
	s_nop 0
	v_pk_mul_f32 v[46:47], v[46:47], v[54:55] op_sel_hi:[1,0]
	v_pk_mul_f32 v[44:45], v[44:45], v[54:55] op_sel_hi:[1,0]
	v_pk_mul_f32 v[42:43], v[42:43], v[54:55] op_sel_hi:[1,0]
	v_pk_mul_f32 v[40:41], v[40:41], v[54:55] op_sel_hi:[1,0]
	v_pk_mul_f32 v[38:39], v[38:39], v[54:55] op_sel_hi:[1,0]
	v_pk_mul_f32 v[36:37], v[36:37], v[54:55] op_sel_hi:[1,0]
	v_pk_mul_f32 v[34:35], v[34:35], v[54:55] op_sel_hi:[1,0]
	v_pk_mul_f32 v[32:33], v[32:33], v[54:55] op_sel_hi:[1,0]
	v_max_f32_e32 v44, 0, v44
	v_max_f32_e32 v40, 0, v40
	v_max_f32_e32 v45, 0, v45
	v_max_f32_e32 v41, 0, v41
	v_max_f32_e32 v46, 0, v46
	v_max_f32_e32 v42, 0, v42
	v_max_f32_e32 v47, 0, v47
	v_max_f32_e32 v43, 0, v43
	v_max_f32_e32 v36, 0, v36
	v_max_f32_e32 v32, 0, v32
	v_max_f32_e32 v37, 0, v37
	v_max_f32_e32 v33, 0, v33
	v_max_f32_e32 v38, 0, v38
	v_max_f32_e32 v34, 0, v34
	v_max_f32_e32 v39, 0, v39
	v_max_f32_e32 v35, 0, v35
	v_pk_mul_f32 v[44:45], v[44:45], v[44:45]
	v_pk_mul_f32 v[40:41], v[40:41], v[40:41]
	v_pk_mul_f32 v[46:47], v[46:47], v[46:47]
	v_pk_mul_f32 v[42:43], v[42:43], v[42:43]
	v_pk_mul_f32 v[36:37], v[36:37], v[36:37]
	v_pk_mul_f32 v[54:55], v[32:33], v[32:33]
	v_pk_mul_f32 v[38:39], v[38:39], v[38:39]
	v_pk_mul_f32 v[56:57], v[34:35], v[34:35]
	v_cvt_pk_bf16_f32 v32, v44, v45
	v_cvt_pk_bf16_f32 v33, v46, v47
	v_cvt_pk_bf16_f32 v34, v40, v41
	v_cvt_pk_bf16_f32 v35, v42, v43
	v_cvt_pk_bf16_f32 v36, v36, v37
	v_cvt_pk_bf16_f32 v37, v38, v39
	v_cvt_pk_bf16_f32 v38, v54, v55
	v_cvt_pk_bf16_f32 v39, v56, v57
	global_store_dwordx4 v[50:51], v[32:35], off
	global_store_dwordx4 v[50:51], v[36:39], off offset:256
	s_waitcnt vmcnt(13)
	s_nop 1
	v_add_f32_e32 v32, v194, v195
	v_add_f32_e32 v33, v196, v197
	v_lshlrev_b64 v[34:35], 13, v[48:49]
	v_add_f32_e32 v32, v32, v33
	ds_bpermute_b32 v33, v158, v32
	v_lshl_add_u64 v[34:35], s[28:29], 0, v[34:35]
	v_lshl_add_u64 v[34:35], v[34:35], 0, v[146:147]
	s_waitcnt lgkmcnt(0)
	v_add_f32_e32 v38, v32, v33
	ds_bpermute_b32 v39, v159, v38
	v_add_u32_e32 v32, 0xb0, v148
	v_ashrrev_i32_e32 v33, 31, v32
	v_lshlrev_b64 v[36:37], 6, v[32:33]
	v_lshl_add_u64 v[36:37], v[136:137], 0, v[36:37]
	s_waitcnt lgkmcnt(0)
	v_add_f32_e32 v38, v38, v39
	v_fmamk_f32 v38, v38, 0x3a800000, v157
	v_rsq_f32_e32 v38, v38
	s_nop 0
	v_pk_mul_f32 v[30:31], v[30:31], v[38:39] op_sel_hi:[1,0]
	v_pk_mul_f32 v[28:29], v[28:29], v[38:39] op_sel_hi:[1,0]
	v_pk_mul_f32 v[26:27], v[26:27], v[38:39] op_sel_hi:[1,0]
	v_pk_mul_f32 v[24:25], v[24:25], v[38:39] op_sel_hi:[1,0]
	v_pk_mul_f32 v[22:23], v[22:23], v[38:39] op_sel_hi:[1,0]
	v_pk_mul_f32 v[20:21], v[20:21], v[38:39] op_sel_hi:[1,0]
	v_pk_mul_f32 v[18:19], v[18:19], v[38:39] op_sel_hi:[1,0]
	v_pk_mul_f32 v[16:17], v[16:17], v[38:39] op_sel_hi:[1,0]
	v_max_f32_e32 v28, 0, v28
	v_max_f32_e32 v24, 0, v24
	v_max_f32_e32 v29, 0, v29
	v_max_f32_e32 v25, 0, v25
	v_max_f32_e32 v30, 0, v30
	v_max_f32_e32 v26, 0, v26
	v_max_f32_e32 v31, 0, v31
	v_max_f32_e32 v27, 0, v27
	v_max_f32_e32 v20, 0, v20
	v_max_f32_e32 v16, 0, v16
	v_max_f32_e32 v21, 0, v21
	v_max_f32_e32 v17, 0, v17
	v_max_f32_e32 v22, 0, v22
	v_max_f32_e32 v18, 0, v18
	v_max_f32_e32 v23, 0, v23
	v_max_f32_e32 v19, 0, v19
	v_pk_mul_f32 v[28:29], v[28:29], v[28:29]
	v_pk_mul_f32 v[24:25], v[24:25], v[24:25]
	v_pk_mul_f32 v[30:31], v[30:31], v[30:31]
	v_pk_mul_f32 v[26:27], v[26:27], v[26:27]
	v_pk_mul_f32 v[20:21], v[20:21], v[20:21]
	v_pk_mul_f32 v[38:39], v[16:17], v[16:17]
	v_pk_mul_f32 v[22:23], v[22:23], v[22:23]
	v_pk_mul_f32 v[40:41], v[18:19], v[18:19]
	v_cvt_pk_bf16_f32 v16, v28, v29
	v_cvt_pk_bf16_f32 v17, v30, v31
	v_cvt_pk_bf16_f32 v18, v24, v25
	v_cvt_pk_bf16_f32 v19, v26, v27
	v_cvt_pk_bf16_f32 v20, v20, v21
	v_cvt_pk_bf16_f32 v21, v22, v23
	v_cvt_pk_bf16_f32 v22, v38, v39
	v_cvt_pk_bf16_f32 v23, v40, v41
	global_store_dwordx4 v[34:35], v[16:19], off
	global_store_dwordx4 v[34:35], v[20:23], off offset:256
	s_waitcnt vmcnt(14)
	s_nop 1
	v_add_f32_e32 v16, v198, v199
	v_add_f32_e32 v17, v200, v201
	v_lshlrev_b64 v[18:19], 13, v[32:33]
	v_add_f32_e32 v16, v16, v17
	ds_bpermute_b32 v17, v158, v16
	v_lshl_add_u64 v[18:19], s[28:29], 0, v[18:19]
	v_lshl_add_u64 v[18:19], v[18:19], 0, v[146:147]
	s_waitcnt lgkmcnt(0)
	v_add_f32_e32 v16, v16, v17
	ds_bpermute_b32 v17, v159, v16
	s_waitcnt lgkmcnt(0)
	v_add_f32_e32 v16, v16, v17
	v_fmamk_f32 v16, v16, 0x3a800000, v157
	v_rsq_f32_e32 v16, v16
	s_nop 0
	v_pk_mul_f32 v[14:15], v[14:15], v[16:17] op_sel_hi:[1,0]
	v_pk_mul_f32 v[12:13], v[12:13], v[16:17] op_sel_hi:[1,0]
	v_pk_mul_f32 v[10:11], v[10:11], v[16:17] op_sel_hi:[1,0]
	v_pk_mul_f32 v[8:9], v[8:9], v[16:17] op_sel_hi:[1,0]
	v_pk_mul_f32 v[6:7], v[6:7], v[16:17] op_sel_hi:[1,0]
	v_pk_mul_f32 v[4:5], v[4:5], v[16:17] op_sel_hi:[1,0]
	v_pk_mul_f32 v[2:3], v[2:3], v[16:17] op_sel_hi:[1,0]
	v_pk_mul_f32 v[0:1], v[0:1], v[16:17] op_sel_hi:[1,0]
	v_max_f32_e32 v12, 0, v12
	v_max_f32_e32 v8, 0, v8
	v_max_f32_e32 v13, 0, v13
	v_max_f32_e32 v9, 0, v9
	v_max_f32_e32 v14, 0, v14
	v_max_f32_e32 v10, 0, v10
	v_max_f32_e32 v15, 0, v15
	v_max_f32_e32 v11, 0, v11
	v_max_f32_e32 v4, 0, v4
	v_max_f32_e32 v0, 0, v0
	v_max_f32_e32 v5, 0, v5
	v_max_f32_e32 v1, 0, v1
	v_max_f32_e32 v6, 0, v6
	v_max_f32_e32 v2, 0, v2
	v_max_f32_e32 v7, 0, v7
	v_max_f32_e32 v3, 0, v3
	v_pk_mul_f32 v[12:13], v[12:13], v[12:13]
	v_pk_mul_f32 v[8:9], v[8:9], v[8:9]
	v_pk_mul_f32 v[14:15], v[14:15], v[14:15]
	v_pk_mul_f32 v[10:11], v[10:11], v[10:11]
	v_pk_mul_f32 v[4:5], v[4:5], v[4:5]
	v_pk_mul_f32 v[16:17], v[0:1], v[0:1]
	v_pk_mul_f32 v[6:7], v[6:7], v[6:7]
	v_pk_mul_f32 v[20:21], v[2:3], v[2:3]
	v_cvt_pk_bf16_f32 v0, v12, v13
	v_cvt_pk_bf16_f32 v1, v14, v15
	v_cvt_pk_bf16_f32 v2, v8, v9
	v_cvt_pk_bf16_f32 v3, v10, v11
	v_cvt_pk_bf16_f32 v4, v4, v5
	v_cvt_pk_bf16_f32 v5, v6, v7
	v_cvt_pk_bf16_f32 v6, v16, v17
	v_cvt_pk_bf16_f32 v7, v20, v21
	global_store_dwordx4 v[18:19], v[0:3], off
	global_store_dwordx4 v[18:19], v[4:7], off offset:256
	s_cbranch_vccnz .LBB0_387
	s_andn2_b64 vcc, exec, s[6:7]
	s_cbranch_vccnz .LBB0_386
	s_mov_b32 s100, 1
	s_branch .LBB0_386

; #define PG8_BAR __builtin_amdgcn_s_barrier()
; template <class Epi, class Sched, bool ALIGN_EPI = false, bool SP2 = false, bool FP8 = false>
; __device__ __forceinline__ void gemm_phase(PG8_LAS unsigned char* lds, const Gemm g, const Sched& S, const Epi& E) {
;     ...
;         const bool has_next = S.next(ui + 1, nxt);
;         const char* nA = has_next ? (const char*)g.A + (size_t)nxt.pm * tstep : cA; const char* nB = has_next ? (const char*)g.Bt + (size_t)nxt.pn * tstep : cB;
; #pragma unroll 1
;         for (int t = 0; t < nt; t += 2) {
;             if constexpr (Epi::MID_T > 0) { if (t == Epi::MID_T) E.mid(acc, cur, wr, wc, fr, fq); }
;             const bool last = (t == nt - 2);
;             const char* a1 = cA + (size_t)(t + 1) * kstep;
;             const char* a2 = last ? nA : cA + (size_t)(t + 2) * kstep; const char* b2 = last ? nB : cB + (size_t)(t + 2) * kstep;
;             const char* a3 = a2 + kstep; const char* b3 = b2 + kstep;
;     ...
; #pragma unroll
;         for (int a = 0; a < 2; ++a)
; #pragma unroll
;             for (int b = 0; b < 2; ++b)
; #pragma unroll
;                 for (int m = 0; m < 4; ++m)
; #pragma unroll
;                     for (int n = 0; n < 2; ++n) { acc[a][b][m][n] = (f32x4){0.f, 0.f, 0.f, 0.f}; if constexpr (FP8) asm volatile("" : "+v"(acc[a][b][m][n])); }
;         cur = nxt; cA = nA; cB = nB; ++ui;
;         if constexpr (ALIGN_EPI) { if (wr == 1) PG8_BAR; }
.LBB0_426:
	s_ashr_i32 s31, s30, 31
	s_lshl_b64 s[34:35], s[30:31], 21
	s_add_u32 s34, s28, s34
	s_addc_u32 s35, s29, s35
	s_and_b64 s[36:37], s[4:5], exec
	s_cselect_b32 s31, s35, s41
	s_cselect_b32 s39, s34, s40
	s_ashr_i32 s23, s22, 31
	s_lshl_b64 s[36:37], s[22:23], 21
	s_add_u32 s36, s26, s36
	s_addc_u32 s37, s27, s37
	s_and_b64 s[44:45], s[4:5], exec
	s_cselect_b32 s23, s37, s43
	s_cselect_b32 s60, s36, s42
	s_add_u32 s40, s40, 0x100080
	s_addc_u32 s41, s41, 0
	s_add_u32 s61, s42, 0x100
	v_mov_b32_e32 v0, 0
	s_addc_u32 s62, s43, 0
	s_mov_b32 s63, -2
	v_mov_b32_e32 v1, v0
	v_mov_b32_e32 v2, v0
	v_mov_b32_e32 v3, v0
	v_mov_b32_e32 v4, v0
	v_mov_b32_e32 v5, v0
	v_mov_b32_e32 v6, v0
	v_mov_b32_e32 v7, v0
	v_mov_b32_e32 v16, v0
	v_mov_b32_e32 v17, v0
	v_mov_b32_e32 v18, v0
	v_mov_b32_e32 v19, v0
	v_mov_b32_e32 v20, v0
	v_mov_b32_e32 v21, v0
	v_mov_b32_e32 v22, v0
	v_mov_b32_e32 v23, v0
	v_mov_b32_e32 v32, v0
	v_mov_b32_e32 v33, v0
	v_mov_b32_e32 v34, v0
	v_mov_b32_e32 v35, v0
	v_mov_b32_e32 v36, v0
	v_mov_b32_e32 v37, v0
	v_mov_b32_e32 v38, v0
	v_mov_b32_e32 v39, v0
	v_mov_b32_e32 v48, v0
	v_mov_b32_e32 v49, v0
	v_mov_b32_e32 v50, v0
	v_mov_b32_e32 v51, v0
	v_mov_b32_e32 v52, v0
	v_mov_b32_e32 v53, v0
	v_mov_b32_e32 v54, v0
	v_mov_b32_e32 v55, v0
	v_mov_b32_e32 v8, v0
	v_mov_b32_e32 v9, v0
	v_mov_b32_e32 v10, v0
	v_mov_b32_e32 v11, v0
	v_mov_b32_e32 v12, v0
	v_mov_b32_e32 v13, v0
	v_mov_b32_e32 v14, v0
	v_mov_b32_e32 v15, v0
	v_mov_b32_e32 v24, v0
	v_mov_b32_e32 v25, v0
	v_mov_b32_e32 v26, v0
	v_mov_b32_e32 v27, v0
	v_mov_b32_e32 v28, v0
	v_mov_b32_e32 v29, v0
	v_mov_b32_e32 v30, v0
	v_mov_b32_e32 v31, v0
	v_mov_b32_e32 v40, v0
	v_mov_b32_e32 v41, v0
	v_mov_b32_e32 v42, v0
	v_mov_b32_e32 v43, v0
	v_mov_b32_e32 v44, v0
	v_mov_b32_e32 v45, v0
	v_mov_b32_e32 v46, v0
	v_mov_b32_e32 v47, v0
	v_mov_b32_e32 v56, v0
	v_mov_b32_e32 v57, v0
	v_mov_b32_e32 v58, v0
	v_mov_b32_e32 v59, v0
	v_mov_b32_e32 v60, v0
	v_mov_b32_e32 v61, v0
	v_mov_b32_e32 v62, v0
	v_mov_b32_e32 v63, v0
	v_mov_b32_e32 v64, v0
	v_mov_b32_e32 v65, v0
	v_mov_b32_e32 v66, v0
	v_mov_b32_e32 v67, v0
	v_mov_b32_e32 v68, v0
	v_mov_b32_e32 v69, v0
	v_mov_b32_e32 v70, v0
	v_mov_b32_e32 v71, v0
	v_mov_b32_e32 v80, v0
	v_mov_b32_e32 v81, v0
	v_mov_b32_e32 v82, v0
	v_mov_b32_e32 v83, v0
	v_mov_b32_e32 v84, v0
	v_mov_b32_e32 v85, v0
	v_mov_b32_e32 v86, v0
	v_mov_b32_e32 v87, v0
	v_mov_b32_e32 v96, v0
	v_mov_b32_e32 v97, v0
	v_mov_b32_e32 v98, v0
	v_mov_b32_e32 v99, v0
	v_mov_b32_e32 v100, v0
	v_mov_b32_e32 v101, v0
	v_mov_b32_e32 v102, v0
	v_mov_b32_e32 v103, v0
	v_mov_b32_e32 v112, v0
	v_mov_b32_e32 v113, v0
	v_mov_b32_e32 v114, v0
	v_mov_b32_e32 v115, v0
	v_mov_b32_e32 v116, v0
	v_mov_b32_e32 v117, v0
	v_mov_b32_e32 v118, v0
	v_mov_b32_e32 v119, v0
	v_mov_b32_e32 v72, v0
	v_mov_b32_e32 v73, v0
	v_mov_b32_e32 v74, v0
	v_mov_b32_e32 v75, v0
	v_mov_b32_e32 v76, v0
	v_mov_b32_e32 v77, v0
	v_mov_b32_e32 v78, v0
	v_mov_b32_e32 v79, v0
	v_mov_b32_e32 v88, v0
	v_mov_b32_e32 v89, v0
	v_mov_b32_e32 v90, v0
	v_mov_b32_e32 v91, v0
	v_mov_b32_e32 v92, v0
	v_mov_b32_e32 v93, v0
	v_mov_b32_e32 v94, v0
	v_mov_b32_e32 v95, v0
	v_mov_b32_e32 v104, v0
	v_mov_b32_e32 v105, v0
	v_mov_b32_e32 v106, v0
	v_mov_b32_e32 v107, v0
	v_mov_b32_e32 v108, v0
	v_mov_b32_e32 v109, v0
	v_mov_b32_e32 v110, v0
	v_mov_b32_e32 v111, v0
	v_mov_b32_e32 v120, v0
	v_mov_b32_e32 v121, v0
	v_mov_b32_e32 v122, v0
	v_mov_b32_e32 v123, v0
	v_mov_b32_e32 v124, v0
	v_mov_b32_e32 v125, v0
	v_mov_b32_e32 v126, v0
	v_mov_b32_e32 v127, v0
	s_cmp_eq_u32 s100, 0
	s_cbranch_scc1 .Lmy_nobar_P6
	s_barrier
	s_mov_b32 s100, 0
.Lmy_nobar_P6:
.LBB0_427:
	ds_read_b128 v[128:131], v201
	ds_read_b128 v[132:135], v201 offset:1024
	ds_read_b128 v[136:139], v201 offset:2048
	ds_read_b128 v[140:143], v201 offset:3072
	ds_read_b128 v[144:147], v202
	ds_read_b128 v[148:151], v202 offset:1024
	ds_read_b128 v[170:173], v202 offset:2048
	ds_read_b128 v[174:177], v202 offset:3072
	s_add_u32 s42, s40, 0xfff00080
	s_addc_u32 s43, s41, -1
	s_cmp_eq_u32 s63, 60
	s_cselect_b32 s45, s31, s43
	s_cselect_b32 s44, s39, s42
	s_cselect_b32 s43, s23, s62
	s_cselect_b32 s42, s60, s61
	v_lshl_add_u64 v[218:219], s[40:41], 0, v[162:163]
	s_add_i32 m0, s47, 0xc000
	ds_read_b128 v[178:181], v203
	ds_read_b128 v[182:185], v203 offset:1024
	ds_read_b128 v[186:189], v203 offset:2048
	ds_read_b128 v[190:193], v203 offset:3072
	ds_read_b128 v[194:197], v203 offset:4096
	ds_read_b128 v[206:209], v203 offset:5120
	ds_read_b128 v[210:213], v203 offset:6144
	ds_read_b128 v[214:217], v203 offset:7168
	global_load_lds_dwordx4 v[218:219], off
	v_lshl_add_u64 v[218:219], s[40:41], 0, v[164:165]
	s_add_i32 m0, s47, 0xe000
	s_nop 0
	global_load_lds_dwordx4 v[218:219], off
	s_waitcnt vmcnt(8)
	s_waitcnt lgkmcnt(0)
	s_barrier
; #define PG8_STAGE(bufoff, gbase, voff) do { _Pragma("unroll") for (int _i = 0; _i < 2; ++_i) { unsigned vo_ = (voff)[_i]; if constexpr (FP8) asm volatile("" : "+v"(vo_)); \
;         __builtin_amdgcn_global_load_lds((const unsigned*)((const char*)(gbase) + vo_), (PG8_LAS unsigned*)(lds + (bufoff) + ldsw + _i * 8192), 16, 0, 0); } } while (0)
; #define PG8_LDA(dst, b, h) do { _Pragma("unroll") for (int m = 0; m < 4; ++m) _Pragma("unroll") for (int k = 0; k < 2; ++k) dst[m][k] = *(const PG8_LAS bf16x8*)(lds + PG8_SA(b, h) + aoff + m * 2048 + k * 1024); } while (0)
; #define PG8_LDB(dst, b, h) do { _Pragma("unroll") for (int n = 0; n < 2; ++n) _Pragma("unroll") for (int k = 0; k < 2; ++k) dst[n][k] = *(const PG8_LAS bf16x8*)(lds + PG8_SB(b, h) + boff + n * 2048 + k * 1024); } while (0)
; #define PG8_WAIT_V(n) asm volatile("s_waitcnt vmcnt(" #n ")" ::: "memory")
; #define PG8_WAIT_L(n) asm volatile("s_waitcnt lgkmcnt(" #n ")" ::: "memory")
; #define PG8_BAR __builtin_amdgcn_s_barrier()
; #define PG8_SCHED __builtin_amdgcn_sched_barrier(0)
; template <class Epi, class Sched, bool ALIGN_EPI = false, bool SP2 = false, bool FP8 = false>
; __device__ __forceinline__ void gemm_phase(PG8_LAS unsigned char* lds, const Gemm g, const Sched& S, const Epi& E) {
;     ...
;             PG8_LDB(B0, 0, 0); PG8_LDB(B1, 0, 1); PG8_SCHED; PG8_LDA(At, 0, 0); PG8_STAGE(PG8_SA(1, 1), a1 + hstep, voffA);
;             PG8_WAIT_V(8); PG8_WAIT_L(0); PG8_BAR; PG8_MMA(0, 0, At, B0); PG8_MMA(0, 1, At, B1); PG8_BAR; PG8_SCHED;
;             PG8_LDA(At, 0, 1); PG8_STAGE(PG8_SB(0, 0), b2, voffB); PG8_STAGE(PG8_SB(0, 1), b2 + hstep, voffB); PG8_STAGE(PG8_SA(0, 0), a2, voffA);
;             PG8_WAIT_V(8); PG8_WAIT_L(0); PG8_BAR; PG8_MMA(1, 0, At, B0); PG8_MMA(1, 1, At, B1); PG8_BAR; PG8_SCHED;
	s_setprio 1
	s_waitcnt lgkmcnt(0)
	v_mfma_f32_16x16x32_bf16 v[124:127], v[128:131], v[178:181], v[124:127]
	v_mfma_f32_16x16x32_bf16 v[120:123], v[136:139], v[178:181], v[120:123]
	v_mfma_f32_16x16x32_bf16 v[108:111], v[128:131], v[186:189], v[108:111]
	v_mfma_f32_16x16x32_bf16 v[104:107], v[136:139], v[186:189], v[104:107]
	v_mfma_f32_16x16x32_bf16 v[92:95], v[128:131], v[194:197], v[92:95]
	v_mfma_f32_16x16x32_bf16 v[88:91], v[136:139], v[194:197], v[88:91]
	v_mfma_f32_16x16x32_bf16 v[76:79], v[128:131], v[210:213], v[76:79]
	v_mfma_f32_16x16x32_bf16 v[72:75], v[136:139], v[210:213], v[72:75]
	v_mfma_f32_16x16x32_bf16 v[124:127], v[132:135], v[182:185], v[124:127]
	v_mfma_f32_16x16x32_bf16 v[120:123], v[140:143], v[182:185], v[120:123]
	v_mfma_f32_16x16x32_bf16 v[108:111], v[132:135], v[190:193], v[108:111]
	v_mfma_f32_16x16x32_bf16 v[104:107], v[140:143], v[190:193], v[104:107]
	v_mfma_f32_16x16x32_bf16 v[92:95], v[132:135], v[206:209], v[92:95]
	v_mfma_f32_16x16x32_bf16 v[88:91], v[140:143], v[206:209], v[88:91]
	v_mfma_f32_16x16x32_bf16 v[76:79], v[132:135], v[214:217], v[76:79]
	v_mfma_f32_16x16x32_bf16 v[72:75], v[140:143], v[214:217], v[72:75]
	s_setprio 0
	s_setprio 1
	v_mfma_f32_16x16x32_bf16 v[116:119], v[144:147], v[178:181], v[116:119]
	v_mfma_f32_16x16x32_bf16 v[112:115], v[170:173], v[178:181], v[112:115]
	v_mfma_f32_16x16x32_bf16 v[100:103], v[144:147], v[186:189], v[100:103]
	v_mfma_f32_16x16x32_bf16 v[96:99], v[170:173], v[186:189], v[96:99]
	v_mfma_f32_16x16x32_bf16 v[84:87], v[144:147], v[194:197], v[84:87]
	v_mfma_f32_16x16x32_bf16 v[80:83], v[170:173], v[194:197], v[80:83]
	v_mfma_f32_16x16x32_bf16 v[68:71], v[144:147], v[210:213], v[68:71]
	v_mfma_f32_16x16x32_bf16 v[64:67], v[170:173], v[210:213], v[64:67]
	v_mfma_f32_16x16x32_bf16 v[116:119], v[148:151], v[182:185], v[116:119]
	v_mfma_f32_16x16x32_bf16 v[112:115], v[174:177], v[182:185], v[112:115]
	v_mfma_f32_16x16x32_bf16 v[100:103], v[148:151], v[190:193], v[100:103]
	v_mfma_f32_16x16x32_bf16 v[96:99], v[174:177], v[190:193], v[96:99]
	v_mfma_f32_16x16x32_bf16 v[84:87], v[148:151], v[206:209], v[84:87]
	v_mfma_f32_16x16x32_bf16 v[80:83], v[174:177], v[206:209], v[80:83]
	v_mfma_f32_16x16x32_bf16 v[68:71], v[148:151], v[214:217], v[68:71]
	v_mfma_f32_16x16x32_bf16 v[64:67], v[174:177], v[214:217], v[64:67]
	s_setprio 0
	s_barrier
	s_add_i32 s64, s57, s46
	v_lshl_add_u64 v[218:219], s[42:43], 0, v[154:155]
	s_mov_b32 m0, s64
	ds_read_b128 v[178:181], v203 offset:16384
	ds_read_b128 v[182:185], v203 offset:17408
	ds_read_b128 v[186:189], v203 offset:18432
	ds_read_b128 v[190:193], v203 offset:19456
	ds_read_b128 v[194:197], v203 offset:20480
	ds_read_b128 v[206:209], v203 offset:21504
	ds_read_b128 v[210:213], v203 offset:22528
	ds_read_b128 v[214:217], v203 offset:23552
	global_load_lds_dwordx4 v[218:219], off
	s_add_i32 m0, s64, 0x2000
	s_add_u32 s64, s42, 0x100000
	v_lshl_add_u64 v[220:221], s[42:43], 0, v[158:159]
	s_addc_u32 s65, s43, 0
	s_add_i32 s66, s58, s46
	global_load_lds_dwordx4 v[220:221], off
	v_lshl_add_u64 v[222:223], s[64:65], 0, v[154:155]
	s_mov_b32 m0, s66
	v_lshl_add_u64 v[224:225], s[44:45], 0, v[156:157]
	global_load_lds_dwordx4 v[222:223], off
	v_lshl_add_u64 v[222:223], s[64:65], 0, v[158:159]
	s_add_i32 m0, s66, 0x2000
	s_nop 0
	global_load_lds_dwordx4 v[222:223], off
	v_lshl_add_u64 v[222:223], s[44:45], 0, v[152:153]
	s_mov_b32 m0, s47
	s_nop 0
	global_load_lds_dwordx4 v[222:223], off
	s_mov_b32 m0, s48
	s_nop 0
	global_load_lds_dwordx4 v[224:225], off
	s_waitcnt vmcnt(8)
	s_waitcnt lgkmcnt(0)
	s_barrier
	s_setprio 1
	s_waitcnt lgkmcnt(0)
	v_mfma_f32_16x16x32_bf16 v[60:63], v[128:131], v[178:181], v[60:63]
	v_mfma_f32_16x16x32_bf16 v[56:59], v[136:139], v[178:181], v[56:59]
	v_mfma_f32_16x16x32_bf16 v[44:47], v[128:131], v[186:189], v[44:47]
	v_mfma_f32_16x16x32_bf16 v[40:43], v[136:139], v[186:189], v[40:43]
	v_mfma_f32_16x16x32_bf16 v[28:31], v[128:131], v[194:197], v[28:31]
	v_mfma_f32_16x16x32_bf16 v[24:27], v[136:139], v[194:197], v[24:27]
	v_mfma_f32_16x16x32_bf16 v[12:15], v[128:131], v[210:213], v[12:15]
	v_mfma_f32_16x16x32_bf16 v[8:11], v[136:139], v[210:213], v[8:11]
	v_mfma_f32_16x16x32_bf16 v[60:63], v[132:135], v[182:185], v[60:63]
	v_mfma_f32_16x16x32_bf16 v[56:59], v[140:143], v[182:185], v[56:59]
	v_mfma_f32_16x16x32_bf16 v[44:47], v[132:135], v[190:193], v[44:47]
	v_mfma_f32_16x16x32_bf16 v[40:43], v[140:143], v[190:193], v[40:43]
	v_mfma_f32_16x16x32_bf16 v[28:31], v[132:135], v[206:209], v[28:31]
	v_mfma_f32_16x16x32_bf16 v[24:27], v[140:143], v[206:209], v[24:27]
	v_mfma_f32_16x16x32_bf16 v[12:15], v[132:135], v[214:217], v[12:15]
	v_mfma_f32_16x16x32_bf16 v[8:11], v[140:143], v[214:217], v[8:11]
	s_setprio 0
	s_setprio 1
	v_mfma_f32_16x16x32_bf16 v[52:55], v[144:147], v[178:181], v[52:55]
	v_mfma_f32_16x16x32_bf16 v[48:51], v[170:173], v[178:181], v[48:51]
	v_mfma_f32_16x16x32_bf16 v[36:39], v[144:147], v[186:189], v[36:39]
	v_mfma_f32_16x16x32_bf16 v[32:35], v[170:173], v[186:189], v[32:35]
	v_mfma_f32_16x16x32_bf16 v[20:23], v[144:147], v[194:197], v[20:23]
	v_mfma_f32_16x16x32_bf16 v[16:19], v[170:173], v[194:197], v[16:19]
	v_mfma_f32_16x16x32_bf16 v[4:7], v[144:147], v[210:213], v[4:7]
	v_mfma_f32_16x16x32_bf16 v[0:3], v[170:173], v[210:213], v[0:3]
	v_mfma_f32_16x16x32_bf16 v[52:55], v[148:151], v[182:185], v[52:55]
	v_mfma_f32_16x16x32_bf16 v[48:51], v[174:177], v[182:185], v[48:51]
	v_mfma_f32_16x16x32_bf16 v[36:39], v[148:151], v[190:193], v[36:39]
	v_mfma_f32_16x16x32_bf16 v[32:35], v[174:177], v[190:193], v[32:35]
	v_mfma_f32_16x16x32_bf16 v[20:23], v[148:151], v[206:209], v[20:23]
	v_mfma_f32_16x16x32_bf16 v[16:19], v[174:177], v[206:209], v[16:19]
	v_mfma_f32_16x16x32_bf16 v[4:7], v[148:151], v[214:217], v[4:7]
	v_mfma_f32_16x16x32_bf16 v[0:3], v[174:177], v[214:217], v[0:3]
	s_setprio 0
	s_barrier
; #define PG8_STAGE(bufoff, gbase, voff) do { _Pragma("unroll") for (int _i = 0; _i < 2; ++_i) { unsigned vo_ = (voff)[_i]; if constexpr (FP8) asm volatile("" : "+v"(vo_)); \
;         __builtin_amdgcn_global_load_lds((const unsigned*)((const char*)(gbase) + vo_), (PG8_LAS unsigned*)(lds + (bufoff) + ldsw + _i * 8192), 16, 0, 0); } } while (0)
; #define PG8_LDA(dst, b, h) do { _Pragma("unroll") for (int m = 0; m < 4; ++m) _Pragma("unroll") for (int k = 0; k < 2; ++k) dst[m][k] = *(const PG8_LAS bf16x8*)(lds + PG8_SA(b, h) + aoff + m * 2048 + k * 1024); } while (0)
; #define PG8_LDB(dst, b, h) do { _Pragma("unroll") for (int n = 0; n < 2; ++n) _Pragma("unroll") for (int k = 0; k < 2; ++k) dst[n][k] = *(const PG8_LAS bf16x8*)(lds + PG8_SB(b, h) + boff + n * 2048 + k * 1024); } while (0)
; #define PG8_WAIT_V(n) asm volatile("s_waitcnt vmcnt(" #n ")" ::: "memory")
; #define PG8_WAIT_L(n) asm volatile("s_waitcnt lgkmcnt(" #n ")" ::: "memory")
; #define PG8_BAR __builtin_amdgcn_s_barrier()
; #define PG8_SCHED __builtin_amdgcn_sched_barrier(0)
; template <class Epi, class Sched, bool ALIGN_EPI = false, bool SP2 = false, bool FP8 = false>
; __device__ __forceinline__ void gemm_phase(PG8_LAS unsigned char* lds, const Gemm g, const Sched& S, const Epi& E) {
;     ...
;             PG8_LDB(B0, 1, 0); PG8_LDB(B1, 1, 1); PG8_SCHED; PG8_LDA(At, 1, 0); PG8_STAGE(PG8_SA(0, 1), a2 + hstep, voffA);
;             PG8_WAIT_V(8); PG8_WAIT_L(0); PG8_BAR; PG8_MMA(0, 0, At, B0); PG8_MMA(0, 1, At, B1); PG8_BAR; PG8_SCHED;
	s_add_i32 s64, 0, 0x18000
	s_add_i32 s65, 0, 0x1c000
	v_add_u32_e32 v140, s64, v199
	v_add_u32_e32 v174, s65, v199
	ds_read_b128 v[128:131], v140
	ds_read_b128 v[132:135], v140 offset:1024
	ds_read_b128 v[136:139], v140 offset:2048
	ds_read_b128 v[140:143], v140 offset:3072
	ds_read_b128 v[144:147], v174
	ds_read_b128 v[148:151], v174 offset:1024
	ds_read_b128 v[170:173], v174 offset:2048
	ds_read_b128 v[174:177], v174 offset:3072
	s_add_u32 s44, s44, 0x100000
	s_addc_u32 s45, s45, 0
	s_mov_b32 m0, s49
	v_lshl_add_u64 v[226:227], s[44:45], 0, v[152:153]
	ds_read_b128 v[178:181], v203 offset:32768
	ds_read_b128 v[182:185], v203 offset:33792
	ds_read_b128 v[186:189], v203 offset:34816
	ds_read_b128 v[190:193], v203 offset:35840
	ds_read_b128 v[194:197], v203 offset:36864
	ds_read_b128 v[206:209], v203 offset:37888
	ds_read_b128 v[210:213], v203 offset:38912
	ds_read_b128 v[214:217], v203 offset:39936
	global_load_lds_dwordx4 v[226:227], off
	v_lshl_add_u64 v[226:227], s[44:45], 0, v[156:157]
	s_mov_b32 m0, s50
	s_nop 0
	global_load_lds_dwordx4 v[226:227], off
	s_waitcnt vmcnt(8)
	s_waitcnt lgkmcnt(0)
	s_barrier
	s_setprio 1
	s_waitcnt lgkmcnt(0)
	v_mfma_f32_16x16x32_bf16 v[124:127], v[128:131], v[178:181], v[124:127]
	v_mfma_f32_16x16x32_bf16 v[120:123], v[136:139], v[178:181], v[120:123]
	v_mfma_f32_16x16x32_bf16 v[108:111], v[128:131], v[186:189], v[108:111]
	v_mfma_f32_16x16x32_bf16 v[104:107], v[136:139], v[186:189], v[104:107]
	v_mfma_f32_16x16x32_bf16 v[92:95], v[128:131], v[194:197], v[92:95]
	v_mfma_f32_16x16x32_bf16 v[88:91], v[136:139], v[194:197], v[88:91]
	v_mfma_f32_16x16x32_bf16 v[76:79], v[128:131], v[210:213], v[76:79]
	v_mfma_f32_16x16x32_bf16 v[72:75], v[136:139], v[210:213], v[72:75]
	v_mfma_f32_16x16x32_bf16 v[124:127], v[132:135], v[182:185], v[124:127]
	v_mfma_f32_16x16x32_bf16 v[120:123], v[140:143], v[182:185], v[120:123]
	v_mfma_f32_16x16x32_bf16 v[108:111], v[132:135], v[190:193], v[108:111]
	v_mfma_f32_16x16x32_bf16 v[104:107], v[140:143], v[190:193], v[104:107]
	v_mfma_f32_16x16x32_bf16 v[92:95], v[132:135], v[206:209], v[92:95]
	v_mfma_f32_16x16x32_bf16 v[88:91], v[140:143], v[206:209], v[88:91]
	v_mfma_f32_16x16x32_bf16 v[76:79], v[132:135], v[214:217], v[76:79]
	v_mfma_f32_16x16x32_bf16 v[72:75], v[140:143], v[214:217], v[72:75]
	s_setprio 0
	s_setprio 1
	v_mfma_f32_16x16x32_bf16 v[116:119], v[144:147], v[178:181], v[116:119]
	v_mfma_f32_16x16x32_bf16 v[112:115], v[170:173], v[178:181], v[112:115]
	v_mfma_f32_16x16x32_bf16 v[100:103], v[144:147], v[186:189], v[100:103]
	v_mfma_f32_16x16x32_bf16 v[96:99], v[170:173], v[186:189], v[96:99]
	v_mfma_f32_16x16x32_bf16 v[84:87], v[144:147], v[194:197], v[84:87]
	v_mfma_f32_16x16x32_bf16 v[80:83], v[170:173], v[194:197], v[80:83]
	v_mfma_f32_16x16x32_bf16 v[68:71], v[144:147], v[210:213], v[68:71]
	v_mfma_f32_16x16x32_bf16 v[64:67], v[170:173], v[210:213], v[64:67]
	v_mfma_f32_16x16x32_bf16 v[116:119], v[148:151], v[182:185], v[116:119]
	v_mfma_f32_16x16x32_bf16 v[112:115], v[174:177], v[182:185], v[112:115]
	v_mfma_f32_16x16x32_bf16 v[100:103], v[148:151], v[190:193], v[100:103]
	v_mfma_f32_16x16x32_bf16 v[96:99], v[174:177], v[190:193], v[96:99]
	v_mfma_f32_16x16x32_bf16 v[84:87], v[148:151], v[206:209], v[84:87]
	v_mfma_f32_16x16x32_bf16 v[80:83], v[174:177], v[206:209], v[80:83]
	v_mfma_f32_16x16x32_bf16 v[68:71], v[148:151], v[214:217], v[68:71]
	v_mfma_f32_16x16x32_bf16 v[64:67], v[174:177], v[214:217], v[64:67]
	s_setprio 0
	s_barrier
; #define PG8_STAGE(bufoff, gbase, voff) do { _Pragma("unroll") for (int _i = 0; _i < 2; ++_i) { unsigned vo_ = (voff)[_i]; if constexpr (FP8) asm volatile("" : "+v"(vo_)); \
;         __builtin_amdgcn_global_load_lds((const unsigned*)((const char*)(gbase) + vo_), (PG8_LAS unsigned*)(lds + (bufoff) + ldsw + _i * 8192), 16, 0, 0); } } while (0)
; #define PG8_LDA(dst, b, h) do { _Pragma("unroll") for (int m = 0; m < 4; ++m) _Pragma("unroll") for (int k = 0; k < 2; ++k) dst[m][k] = *(const PG8_LAS bf16x8*)(lds + PG8_SA(b, h) + aoff + m * 2048 + k * 1024); } while (0)
; #define PG8_WAIT_V(n) asm volatile("s_waitcnt vmcnt(" #n ")" ::: "memory")
; #define PG8_WAIT_L(n) asm volatile("s_waitcnt lgkmcnt(" #n ")" ::: "memory")
; #define PG8_BAR __builtin_amdgcn_s_barrier()
; #define PG8_SCHED __builtin_amdgcn_sched_barrier(0)
; template <class Epi, class Sched, bool ALIGN_EPI = false, bool SP2 = false, bool FP8 = false>
; __device__ __forceinline__ void gemm_phase(PG8_LAS unsigned char* lds, const Gemm g, const Sched& S, const Epi& E) {
;     ...
;             PG8_LDA(At, 1, 1); PG8_STAGE(PG8_SB(1, 0), b3, voffB); PG8_STAGE(PG8_SB(1, 1), b3 + hstep, voffB); PG8_STAGE(PG8_SA(1, 0), a3, voffA);
;             PG8_WAIT_V(8); PG8_WAIT_L(0); PG8_BAR; PG8_MMA(1, 0, At, B0); PG8_MMA(1, 1, At, B1); PG8_BAR; PG8_SCHED;
;     ...
;         if constexpr (ALIGN_EPI) { if (wr == 0) PG8_BAR; }
	s_add_i32 s44, s64, s46
	v_lshl_add_u64 v[218:219], v[218:219], 0, s[12:13]
	s_mov_b32 m0, s44
	ds_read_b128 v[178:181], v203 offset:49152
	ds_read_b128 v[182:185], v203 offset:50176
	ds_read_b128 v[186:189], v203 offset:51200
	ds_read_b128 v[190:193], v203 offset:52224
	ds_read_b128 v[194:197], v203 offset:53248
	ds_read_b128 v[206:209], v203 offset:54272
	ds_read_b128 v[210:213], v203 offset:55296
	ds_read_b128 v[214:217], v203 offset:56320
	global_load_lds_dwordx4 v[218:219], off
	s_add_i32 m0, s44, 0x2000
	s_add_u32 s42, s42, 0x100080
	v_lshl_add_u64 v[218:219], v[220:221], 0, s[12:13]
	s_addc_u32 s43, s43, 0
	s_add_i32 s44, s65, s46
	global_load_lds_dwordx4 v[218:219], off
	v_lshl_add_u64 v[218:219], s[42:43], 0, v[154:155]
	s_mov_b32 m0, s44
	s_nop 0
	global_load_lds_dwordx4 v[218:219], off
	v_lshl_add_u64 v[218:219], s[42:43], 0, v[158:159]
	s_add_i32 m0, s44, 0x2000
	s_nop 0
	global_load_lds_dwordx4 v[218:219], off
	v_lshl_add_u64 v[218:219], v[222:223], 0, s[12:13]
	s_mov_b32 m0, s54
	s_nop 0
	global_load_lds_dwordx4 v[218:219], off
	v_lshl_add_u64 v[218:219], v[224:225], 0, s[12:13]
	s_mov_b32 m0, s55
	s_nop 0
	global_load_lds_dwordx4 v[218:219], off
	s_waitcnt vmcnt(8)
	s_waitcnt lgkmcnt(0)
	s_barrier
	s_setprio 1
	s_waitcnt lgkmcnt(0)
	v_mfma_f32_16x16x32_bf16 v[60:63], v[128:131], v[178:181], v[60:63]
	v_mfma_f32_16x16x32_bf16 v[56:59], v[136:139], v[178:181], v[56:59]
	v_mfma_f32_16x16x32_bf16 v[44:47], v[128:131], v[186:189], v[44:47]
	v_mfma_f32_16x16x32_bf16 v[40:43], v[136:139], v[186:189], v[40:43]
	v_mfma_f32_16x16x32_bf16 v[28:31], v[128:131], v[194:197], v[28:31]
	v_mfma_f32_16x16x32_bf16 v[24:27], v[136:139], v[194:197], v[24:27]
	v_mfma_f32_16x16x32_bf16 v[12:15], v[128:131], v[210:213], v[12:15]
	v_mfma_f32_16x16x32_bf16 v[8:11], v[136:139], v[210:213], v[8:11]
	v_mfma_f32_16x16x32_bf16 v[60:63], v[132:135], v[182:185], v[60:63]
	v_mfma_f32_16x16x32_bf16 v[56:59], v[140:143], v[182:185], v[56:59]
	v_mfma_f32_16x16x32_bf16 v[44:47], v[132:135], v[190:193], v[44:47]
	v_mfma_f32_16x16x32_bf16 v[40:43], v[140:143], v[190:193], v[40:43]
	v_mfma_f32_16x16x32_bf16 v[28:31], v[132:135], v[206:209], v[28:31]
	v_mfma_f32_16x16x32_bf16 v[24:27], v[140:143], v[206:209], v[24:27]
	v_mfma_f32_16x16x32_bf16 v[12:15], v[132:135], v[214:217], v[12:15]
	v_mfma_f32_16x16x32_bf16 v[8:11], v[140:143], v[214:217], v[8:11]
	s_setprio 0
	s_setprio 1
	v_mfma_f32_16x16x32_bf16 v[52:55], v[144:147], v[178:181], v[52:55]
	v_mfma_f32_16x16x32_bf16 v[48:51], v[170:173], v[178:181], v[48:51]
	v_mfma_f32_16x16x32_bf16 v[36:39], v[144:147], v[186:189], v[36:39]
	v_mfma_f32_16x16x32_bf16 v[32:35], v[170:173], v[186:189], v[32:35]
	v_mfma_f32_16x16x32_bf16 v[20:23], v[144:147], v[194:197], v[20:23]
	v_mfma_f32_16x16x32_bf16 v[16:19], v[170:173], v[194:197], v[16:19]
	v_mfma_f32_16x16x32_bf16 v[4:7], v[144:147], v[210:213], v[4:7]
	v_mfma_f32_16x16x32_bf16 v[0:3], v[170:173], v[210:213], v[0:3]
	v_mfma_f32_16x16x32_bf16 v[52:55], v[148:151], v[182:185], v[52:55]
	v_mfma_f32_16x16x32_bf16 v[48:51], v[174:177], v[182:185], v[48:51]
	v_mfma_f32_16x16x32_bf16 v[36:39], v[148:151], v[190:193], v[36:39]
	v_mfma_f32_16x16x32_bf16 v[32:35], v[174:177], v[190:193], v[32:35]
	v_mfma_f32_16x16x32_bf16 v[20:23], v[148:151], v[206:209], v[20:23]
	v_mfma_f32_16x16x32_bf16 v[16:19], v[174:177], v[206:209], v[16:19]
	v_mfma_f32_16x16x32_bf16 v[4:7], v[148:151], v[214:217], v[4:7]
	v_mfma_f32_16x16x32_bf16 v[0:3], v[174:177], v[214:217], v[0:3]
	s_setprio 0
	s_barrier
	s_add_i32 s63, s63, 2
	s_add_u32 s40, s40, 0x100
	s_addc_u32 s41, s41, 0
	s_add_u32 s61, s61, 0x100
	s_addc_u32 s62, s62, 0
	s_cmp_gt_u32 s63, 61
	s_cbranch_scc0 .LBB0_427
	s_and_b64 vcc, exec, s[14:15]
	s_cbranch_vccz .LBB0_430
	s_barrier

;     __device__ __forceinline__ void operator()(f32x4 (&acc)[2][2][4][2], const Unit& u, int wr, int wc, int fr, int fq) const {
;     ...
; #pragma unroll
;         for (int ai = 0; ai < 2; ++ai)
; #pragma unroll
;             for (int m = 0; m < 4; ++m) { const size_t r = (size_t)(row0 + ai * HALF + m * 16);
;                 const float* pp = ssq + r * 16 + 4 * fq + dep0;
;                 const float q0 = __hip_atomic_load(pp + 0, __ATOMIC_RELAXED, __HIP_MEMORY_SCOPE_AGENT), q1 = __hip_atomic_load(pp + 1, __ATOMIC_RELAXED, __HIP_MEMORY_SCOPE_AGENT),
;                             q2 = __hip_atomic_load(pp + 2, __ATOMIC_RELAXED, __HIP_MEMORY_SCOPE_AGENT), q3 = __hip_atomic_load(pp + 3, __ATOMIC_RELAXED, __HIP_MEMORY_SCOPE_AGENT);
;                 float tot = (q0 + q1) + (q2 + q3); tot += __shfl_xor(tot, 16); tot += __shfl_xor(tot, 32);
;                 const float rs = __builtin_amdgcn_rsqf(tot * (1.f / DM) + RMS_EPS);
; #pragma unroll
;                 for (int bj = 0; bj < 2; ++bj) { const size_t off = r * DM + col0 + bj * HALF;
;                     *(f32x4*)(out + off) = acc[ai][bj][m][0] * rs * gv[bj][0]; *(f32x4*)(out + off + 4) = acc[ai][bj][m][1] * rs * gv[bj][1]; } }
.LBB0_458:
	s_lshr_b32 s6, s6, 29
	v_lshlrev_b64 v[86:87], 2, v[178:179]
	v_lshl_add_u64 v[178:179], v[160:161], 0, v[188:189]
	s_and_b32 s6, s6, 4
	v_lshl_add_u64 v[8:9], s[18:19], 0, v[86:87]
	v_lshl_add_u64 v[178:179], v[178:179], 0, s[6:7]
	global_load_dwordx4 v[4:7], v[8:9], off offset:16
	global_load_dwordx4 v[12:15], v[8:9], off
	s_waitcnt lgkmcnt(0)
	global_load_dwordx4 v[0:3], v[8:9], off offset:528
	s_nop 0
	global_load_dwordx4 v[8:11], v[8:9], off offset:512
	s_nop 0
	global_load_dword v188, v[178:179], off sc1
	global_load_dword v208, v[178:179], off offset:4 sc1
	global_load_dword v189, v[178:179], off offset:8 sc1
	global_load_dword v209, v[178:179], off offset:12 sc1
	v_lshlrev_b64 v[176:177], 12, v[176:177]
	v_lshl_add_u64 v[176:177], s[20:21], 0, v[176:177]
	v_lshl_add_u64 v[176:177], v[176:177], 0, v[86:87]
	v_lshl_add_u64 v[82:83], v[160:161], 0, v[82:83]
	v_lshl_add_u64 v[82:83], v[82:83], 0, s[6:7]
	s_andn2_b64 vcc, exec, s[4:5]
	s_mov_b64 s[4:5], -1
	s_waitcnt vmcnt(0)
	v_pk_add_f32 v[178:179], v[188:189], v[208:209]
	s_nop 0
	v_add_f32_e32 v178, v178, v179
	ds_bpermute_b32 v179, v206, v178
	s_waitcnt lgkmcnt(0)
	v_add_f32_e32 v188, v178, v179
	ds_bpermute_b32 v189, v207, v188
	v_lshl_add_u64 v[178:179], v[160:161], 0, v[190:191]
	v_lshl_add_u64 v[178:179], v[178:179], 0, s[6:7]
	s_waitcnt lgkmcnt(0)
	v_add_f32_e32 v188, v188, v189
	v_fmamk_f32 v188, v188, 0x3a800000, v205
	v_rsq_f32_e32 v188, v188
	s_nop 0
	v_pk_mul_f32 v[124:125], v[124:125], v[188:189] op_sel_hi:[1,0]
	v_pk_mul_f32 v[126:127], v[126:127], v[188:189] op_sel_hi:[1,0]
	v_pk_mul_f32 v[120:121], v[120:121], v[188:189] op_sel_hi:[1,0]
	v_pk_mul_f32 v[122:123], v[122:123], v[188:189] op_sel_hi:[1,0]
	v_pk_mul_f32 v[190:191], v[116:117], v[188:189] op_sel_hi:[1,0]
	v_pk_mul_f32 v[208:209], v[118:119], v[188:189] op_sel_hi:[1,0]
	v_pk_mul_f32 v[210:211], v[112:113], v[188:189] op_sel_hi:[1,0]
	v_pk_mul_f32 v[188:189], v[114:115], v[188:189] op_sel_hi:[1,0]
	v_pk_mul_f32 v[114:115], v[14:15], v[126:127]
	v_pk_mul_f32 v[112:113], v[12:13], v[124:125]
	v_pk_mul_f32 v[118:119], v[6:7], v[122:123]
	v_pk_mul_f32 v[116:117], v[4:5], v[120:121]
	v_pk_mul_f32 v[122:123], v[10:11], v[208:209]
	v_pk_mul_f32 v[120:121], v[8:9], v[190:191]
	v_pk_mul_f32 v[126:127], v[2:3], v[188:189]
	v_pk_mul_f32 v[124:125], v[0:1], v[210:211]
	global_store_dwordx4 v[176:177], v[112:115], off
	global_store_dwordx4 v[176:177], v[116:119], off offset:16
	global_store_dwordx4 v[176:177], v[120:123], off offset:512
	global_store_dwordx4 v[176:177], v[124:127], off offset:528
	global_load_dword v112, v[178:179], off sc1
	s_nop 0
	global_load_dword v114, v[178:179], off offset:4 sc1
	global_load_dword v113, v[178:179], off offset:8 sc1
	global_load_dword v115, v[178:179], off offset:12 sc1
	s_waitcnt vmcnt(0)
	v_pk_add_f32 v[112:113], v[112:113], v[114:115]
	s_nop 0
	v_add_f32_e32 v112, v112, v113
	ds_bpermute_b32 v113, v206, v112
	v_lshl_add_u64 v[114:115], v[160:161], 0, v[192:193]
	v_lshl_add_u64 v[122:123], v[114:115], 0, s[6:7]
	s_waitcnt lgkmcnt(0)
	v_add_f32_e32 v116, v112, v113
	ds_bpermute_b32 v117, v207, v116
	v_lshlrev_b64 v[112:113], 12, v[174:175]
	v_lshl_add_u64 v[112:113], s[20:21], 0, v[112:113]
	v_lshl_add_u64 v[120:121], v[112:113], 0, v[86:87]
	s_waitcnt lgkmcnt(0)
	v_add_f32_e32 v116, v116, v117
	v_fmamk_f32 v116, v116, 0x3a800000, v205
	v_rsq_f32_e32 v116, v116
	s_nop 0
	v_pk_mul_f32 v[108:109], v[108:109], v[116:117] op_sel_hi:[1,0]
	v_pk_mul_f32 v[110:111], v[110:111], v[116:117] op_sel_hi:[1,0]
	v_pk_mul_f32 v[112:113], v[104:105], v[116:117] op_sel_hi:[1,0]
	v_pk_mul_f32 v[114:115], v[106:107], v[116:117] op_sel_hi:[1,0]
	v_pk_mul_f32 v[118:119], v[146:147], v[116:117] op_sel_hi:[1,0]
	v_pk_mul_f32 v[124:125], v[144:145], v[116:117] op_sel_hi:[1,0]
	v_pk_mul_f32 v[126:127], v[150:151], v[116:117] op_sel_hi:[1,0]
	v_pk_mul_f32 v[116:117], v[148:149], v[116:117] op_sel_hi:[1,0]
	v_pk_mul_f32 v[106:107], v[14:15], v[110:111]
	v_pk_mul_f32 v[104:105], v[12:13], v[108:109]
	v_pk_mul_f32 v[110:111], v[6:7], v[114:115]
	v_pk_mul_f32 v[108:109], v[4:5], v[112:113]
	v_pk_mul_f32 v[114:115], v[10:11], v[124:125]
	v_pk_mul_f32 v[112:113], v[8:9], v[118:119]
	v_pk_mul_f32 v[118:119], v[2:3], v[116:117]
	v_pk_mul_f32 v[116:117], v[0:1], v[126:127]
	global_store_dwordx4 v[120:121], v[104:107], off
	global_store_dwordx4 v[120:121], v[108:111], off offset:16
	global_store_dwordx4 v[120:121], v[112:115], off offset:512
	global_store_dwordx4 v[120:121], v[116:119], off offset:528
	global_load_dword v104, v[122:123], off sc1
	s_nop 0
	global_load_dword v106, v[122:123], off offset:4 sc1
	global_load_dword v105, v[122:123], off offset:8 sc1
	global_load_dword v107, v[122:123], off offset:12 sc1
	s_waitcnt vmcnt(0)
	v_pk_add_f32 v[104:105], v[104:105], v[106:107]
	s_nop 0
	v_add_f32_e32 v104, v104, v105
	ds_bpermute_b32 v105, v206, v104
	v_lshl_add_u64 v[106:107], v[160:161], 0, v[194:195]
	v_lshl_add_u64 v[116:117], v[106:107], 0, s[6:7]
	s_waitcnt lgkmcnt(0)
	v_add_f32_e32 v108, v104, v105
	ds_bpermute_b32 v109, v207, v108
	v_lshlrev_b64 v[104:105], 12, v[172:173]
	v_lshl_add_u64 v[104:105], s[20:21], 0, v[104:105]
	v_lshl_add_u64 v[114:115], v[104:105], 0, v[86:87]
	s_waitcnt lgkmcnt(0)
;     __device__ __forceinline__ void operator()(f32x4 (&acc)[2][2][4][2], const Unit& u, int wr, int wc, int fr, int fq) const {
;     ...
;             for (int m = 0; m < 4; ++m) { const size_t r = (size_t)(row0 + ai * HALF + m * 16);
;                 const float* pp = ssq + r * 16 + 4 * fq + dep0;
;                 const float q0 = __hip_atomic_load(pp + 0, __ATOMIC_RELAXED, __HIP_MEMORY_SCOPE_AGENT), q1 = __hip_atomic_load(pp + 1, __ATOMIC_RELAXED, __HIP_MEMORY_SCOPE_AGENT),
;                             q2 = __hip_atomic_load(pp + 2, __ATOMIC_RELAXED, __HIP_MEMORY_SCOPE_AGENT), q3 = __hip_atomic_load(pp + 3, __ATOMIC_RELAXED, __HIP_MEMORY_SCOPE_AGENT);
;                 float tot = (q0 + q1) + (q2 + q3); tot += __shfl_xor(tot, 16); tot += __shfl_xor(tot, 32);
;                 const float rs = __builtin_amdgcn_rsqf(tot * (1.f / DM) + RMS_EPS);
; #pragma unroll
;                 for (int bj = 0; bj < 2; ++bj) { const size_t off = r * DM + col0 + bj * HALF;
;                     *(f32x4*)(out + off) = acc[ai][bj][m][0] * rs * gv[bj][0]; *(f32x4*)(out + off + 4) = acc[ai][bj][m][1] * rs * gv[bj][1]; } }
	v_add_f32_e32 v108, v108, v109
	v_fmamk_f32 v108, v108, 0x3a800000, v205
	v_rsq_f32_e32 v108, v108
	s_nop 0
	v_pk_mul_f32 v[104:105], v[96:97], v[108:109] op_sel_hi:[1,0]
	v_pk_mul_f32 v[94:95], v[94:95], v[108:109] op_sel_hi:[1,0]
	v_pk_mul_f32 v[102:103], v[102:103], v[108:109] op_sel_hi:[1,0]
	v_pk_mul_f32 v[98:99], v[98:99], v[108:109] op_sel_hi:[1,0]
	v_pk_mul_f32 v[106:107], v[140:141], v[108:109] op_sel_hi:[1,0]
	v_pk_mul_f32 v[110:111], v[138:139], v[108:109] op_sel_hi:[1,0]
	v_pk_mul_f32 v[118:119], v[180:181], v[108:109] op_sel_hi:[1,0]
	v_pk_mul_f32 v[112:113], v[142:143], v[108:109] op_sel_hi:[1,0]
	v_pk_mul_f32 v[96:97], v[14:15], v[94:95]
	v_pk_mul_f32 v[94:95], v[12:13], v[104:105]
	v_pk_mul_f32 v[104:105], v[6:7], v[98:99]
	v_pk_mul_f32 v[102:103], v[4:5], v[102:103]
	v_pk_mul_f32 v[108:109], v[10:11], v[110:111]
	v_pk_mul_f32 v[106:107], v[8:9], v[106:107]
	v_pk_mul_f32 v[112:113], v[2:3], v[112:113]
	v_pk_mul_f32 v[110:111], v[0:1], v[118:119]
	global_store_dwordx4 v[114:115], v[94:97], off
	global_store_dwordx4 v[114:115], v[102:105], off offset:16
	global_store_dwordx4 v[114:115], v[106:109], off offset:512
	global_store_dwordx4 v[114:115], v[110:113], off offset:528
	global_load_dword v94, v[116:117], off sc1
	s_nop 0
	global_load_dword v96, v[116:117], off offset:4 sc1
	global_load_dword v95, v[116:117], off offset:8 sc1
	global_load_dword v97, v[116:117], off offset:12 sc1
	s_waitcnt vmcnt(0)
	v_pk_add_f32 v[94:95], v[94:95], v[96:97]
	s_nop 0
	v_add_f32_e32 v94, v94, v95
	ds_bpermute_b32 v95, v206, v94
	v_lshl_add_u64 v[96:97], v[160:161], 0, v[196:197]
	v_lshl_add_u64 v[112:113], v[96:97], 0, s[6:7]
	s_waitcnt lgkmcnt(0)
	v_add_f32_e32 v98, v94, v95
	ds_bpermute_b32 v99, v207, v98
	v_lshlrev_b64 v[94:95], 12, v[170:171]
	v_lshl_add_u64 v[94:95], s[20:21], 0, v[94:95]
	v_lshl_add_u64 v[110:111], v[94:95], 0, v[86:87]
	s_waitcnt lgkmcnt(0)
	v_add_f32_e32 v98, v98, v99
	v_fmamk_f32 v98, v98, 0x3a800000, v205
	v_rsq_f32_e32 v98, v98
	s_nop 0
	v_pk_mul_f32 v[94:95], v[132:133], v[98:99] op_sel_hi:[1,0]
	v_pk_mul_f32 v[96:97], v[100:101], v[98:99] op_sel_hi:[1,0]
	v_pk_mul_f32 v[102:103], v[136:137], v[98:99] op_sel_hi:[1,0]
	v_pk_mul_f32 v[100:101], v[134:135], v[98:99] op_sel_hi:[1,0]
	v_pk_mul_f32 v[106:107], v[130:131], v[98:99] op_sel_hi:[1,0]
	v_pk_mul_f32 v[104:105], v[128:129], v[98:99] op_sel_hi:[1,0]
	v_pk_mul_f32 v[114:115], v[184:185], v[98:99] op_sel_hi:[1,0]
	v_pk_mul_f32 v[108:109], v[182:183], v[98:99] op_sel_hi:[1,0]
	v_pk_mul_f32 v[96:97], v[14:15], v[96:97]
	v_pk_mul_f32 v[94:95], v[12:13], v[94:95]
	v_pk_mul_f32 v[100:101], v[6:7], v[100:101]
	v_pk_mul_f32 v[98:99], v[4:5], v[102:103]
	v_pk_mul_f32 v[104:105], v[10:11], v[104:105]
	v_pk_mul_f32 v[102:103], v[8:9], v[106:107]
	v_pk_mul_f32 v[108:109], v[2:3], v[108:109]
	v_pk_mul_f32 v[106:107], v[0:1], v[114:115]
	global_store_dwordx4 v[110:111], v[94:97], off
	global_store_dwordx4 v[110:111], v[98:101], off offset:16
	global_store_dwordx4 v[110:111], v[102:105], off offset:512
	global_store_dwordx4 v[110:111], v[106:109], off offset:528
	global_load_dword v94, v[112:113], off sc1
	s_nop 0
	global_load_dword v96, v[112:113], off offset:4 sc1
	global_load_dword v95, v[112:113], off offset:8 sc1
	global_load_dword v97, v[112:113], off offset:12 sc1
	s_waitcnt vmcnt(0)
	v_pk_add_f32 v[94:95], v[94:95], v[96:97]
	s_nop 0
	v_add_f32_e32 v94, v94, v95
	ds_bpermute_b32 v95, v206, v94
	s_waitcnt lgkmcnt(0)
	v_add_f32_e32 v96, v94, v95
	ds_bpermute_b32 v97, v207, v96
	v_lshlrev_b64 v[94:95], 12, v[186:187]
	v_lshl_add_u64 v[94:95], s[20:21], 0, v[94:95]
	v_lshl_add_u64 v[94:95], v[94:95], 0, v[86:87]
	s_waitcnt lgkmcnt(0)
	v_add_f32_e32 v96, v96, v97
	v_fmamk_f32 v96, v96, 0x3a800000, v205
	v_rsq_f32_e32 v96, v96
	s_nop 0
	v_pk_mul_f32 v[60:61], v[60:61], v[96:97] op_sel_hi:[1,0]
	v_pk_mul_f32 v[62:63], v[62:63], v[96:97] op_sel_hi:[1,0]
	v_pk_mul_f32 v[56:57], v[56:57], v[96:97] op_sel_hi:[1,0]
	v_pk_mul_f32 v[58:59], v[58:59], v[96:97] op_sel_hi:[1,0]
	v_pk_mul_f32 v[98:99], v[52:53], v[96:97] op_sel_hi:[1,0]
	v_pk_mul_f32 v[100:101], v[54:55], v[96:97] op_sel_hi:[1,0]
	v_pk_mul_f32 v[102:103], v[48:49], v[96:97] op_sel_hi:[1,0]
	v_pk_mul_f32 v[96:97], v[50:51], v[96:97] op_sel_hi:[1,0]
	v_pk_mul_f32 v[50:51], v[14:15], v[62:63]
	v_pk_mul_f32 v[48:49], v[12:13], v[60:61]
	v_pk_mul_f32 v[54:55], v[6:7], v[58:59]
	v_pk_mul_f32 v[52:53], v[4:5], v[56:57]
	v_pk_mul_f32 v[58:59], v[10:11], v[100:101]
	v_pk_mul_f32 v[56:57], v[8:9], v[98:99]
	v_pk_mul_f32 v[62:63], v[2:3], v[96:97]
	v_pk_mul_f32 v[60:61], v[0:1], v[102:103]
	global_store_dwordx4 v[94:95], v[48:51], off
	global_store_dwordx4 v[94:95], v[52:55], off offset:16
	global_store_dwordx4 v[94:95], v[56:59], off offset:512
	global_store_dwordx4 v[94:95], v[60:63], off offset:528
	global_load_dword v48, v[82:83], off sc1
	s_nop 0
	global_load_dword v50, v[82:83], off offset:4 sc1
	global_load_dword v49, v[82:83], off offset:8 sc1
	global_load_dword v51, v[82:83], off offset:12 sc1
	s_waitcnt vmcnt(0)
; #define PG8_BAR __builtin_amdgcn_s_barrier()
; template <class Epi, class Sched, bool ALIGN_EPI = false, bool SP2 = false, bool FP8 = false>
; __device__ __forceinline__ void gemm_phase(PG8_LAS unsigned char* lds, const Gemm g, const Sched& S, const Epi& E) {
;     ...
;         if constexpr (ALIGN_EPI) { if (wr == 1) PG8_BAR; }
;     __device__ __forceinline__ void operator()(f32x4 (&acc)[2][2][4][2], const Unit& u, int wr, int wc, int fr, int fq) const {
;     ...
;             for (int m = 0; m < 4; ++m) { const size_t r = (size_t)(row0 + ai * HALF + m * 16);
;                 const float* pp = ssq + r * 16 + 4 * fq + dep0;
;                 const float q0 = __hip_atomic_load(pp + 0, __ATOMIC_RELAXED, __HIP_MEMORY_SCOPE_AGENT), q1 = __hip_atomic_load(pp + 1, __ATOMIC_RELAXED, __HIP_MEMORY_SCOPE_AGENT),
;                             q2 = __hip_atomic_load(pp + 2, __ATOMIC_RELAXED, __HIP_MEMORY_SCOPE_AGENT), q3 = __hip_atomic_load(pp + 3, __ATOMIC_RELAXED, __HIP_MEMORY_SCOPE_AGENT);
;                 float tot = (q0 + q1) + (q2 + q3); tot += __shfl_xor(tot, 16); tot += __shfl_xor(tot, 32);
;                 const float rs = __builtin_amdgcn_rsqf(tot * (1.f / DM) + RMS_EPS);
; #pragma unroll
;                 for (int bj = 0; bj < 2; ++bj) { const size_t off = r * DM + col0 + bj * HALF;
;                     *(f32x4*)(out + off) = acc[ai][bj][m][0] * rs * gv[bj][0]; *(f32x4*)(out + off + 4) = acc[ai][bj][m][1] * rs * gv[bj][1]; } }
	v_pk_add_f32 v[48:49], v[48:49], v[50:51]
	s_nop 0
	v_add_f32_e32 v48, v48, v49
	ds_bpermute_b32 v49, v206, v48
	v_lshl_add_u64 v[50:51], v[160:161], 0, v[78:79]
	v_lshl_add_u64 v[50:51], v[50:51], 0, s[6:7]
	s_waitcnt lgkmcnt(0)
	v_add_f32_e32 v52, v48, v49
	ds_bpermute_b32 v53, v207, v52
	v_lshlrev_b64 v[48:49], 12, v[92:93]
	v_lshl_add_u64 v[48:49], s[20:21], 0, v[48:49]
	v_lshl_add_u64 v[54:55], v[48:49], 0, v[86:87]
	s_waitcnt lgkmcnt(0)
	v_add_f32_e32 v52, v52, v53
	v_fmamk_f32 v52, v52, 0x3a800000, v205
	v_rsq_f32_e32 v52, v52
	s_nop 0
	v_pk_mul_f32 v[44:45], v[44:45], v[52:53] op_sel_hi:[1,0]
	v_pk_mul_f32 v[46:47], v[46:47], v[52:53] op_sel_hi:[1,0]
	v_pk_mul_f32 v[48:49], v[40:41], v[52:53] op_sel_hi:[1,0]
	v_pk_mul_f32 v[40:41], v[42:43], v[52:53] op_sel_hi:[1,0]
	v_pk_mul_f32 v[42:43], v[36:37], v[52:53] op_sel_hi:[1,0]
	v_pk_mul_f32 v[56:57], v[38:39], v[52:53] op_sel_hi:[1,0]
	v_pk_mul_f32 v[58:59], v[80:81], v[52:53] op_sel_hi:[1,0]
	v_pk_mul_f32 v[52:53], v[34:35], v[52:53] op_sel_hi:[1,0]
	v_pk_mul_f32 v[36:37], v[14:15], v[46:47]
	v_pk_mul_f32 v[34:35], v[12:13], v[44:45]
	v_pk_mul_f32 v[40:41], v[6:7], v[40:41]
	v_pk_mul_f32 v[38:39], v[4:5], v[48:49]
	v_pk_mul_f32 v[44:45], v[10:11], v[56:57]
	v_pk_mul_f32 v[42:43], v[8:9], v[42:43]
	v_pk_mul_f32 v[48:49], v[2:3], v[52:53]
	v_pk_mul_f32 v[46:47], v[0:1], v[58:59]
	global_store_dwordx4 v[54:55], v[34:37], off
	global_store_dwordx4 v[54:55], v[38:41], off offset:16
	global_store_dwordx4 v[54:55], v[42:45], off offset:512
	global_store_dwordx4 v[54:55], v[46:49], off offset:528
	global_load_dword v34, v[50:51], off sc1
	s_nop 0
	global_load_dword v36, v[50:51], off offset:4 sc1
	global_load_dword v35, v[50:51], off offset:8 sc1
	global_load_dword v37, v[50:51], off offset:12 sc1
	s_waitcnt vmcnt(0)
	v_pk_add_f32 v[34:35], v[34:35], v[36:37]
	s_nop 0
	v_add_f32_e32 v34, v34, v35
	ds_bpermute_b32 v35, v206, v34
	v_lshl_add_u64 v[36:37], v[160:161], 0, v[84:85]
	v_lshl_add_u64 v[42:43], v[36:37], 0, s[6:7]
	s_waitcnt lgkmcnt(0)
	v_add_f32_e32 v38, v34, v35
	ds_bpermute_b32 v39, v207, v38
	v_lshlrev_b64 v[34:35], 12, v[90:91]
	v_lshl_add_u64 v[34:35], s[20:21], 0, v[34:35]
	v_lshl_add_u64 v[40:41], v[34:35], 0, v[86:87]
	s_waitcnt lgkmcnt(0)
	v_add_f32_e32 v38, v38, v39
	v_fmamk_f32 v38, v38, 0x3a800000, v205
	v_rsq_f32_e32 v38, v38
	s_nop 0
	v_pk_mul_f32 v[28:29], v[28:29], v[38:39] op_sel_hi:[1,0]
	v_pk_mul_f32 v[30:31], v[30:31], v[38:39] op_sel_hi:[1,0]
	v_pk_mul_f32 v[34:35], v[24:25], v[38:39] op_sel_hi:[1,0]
	v_pk_mul_f32 v[36:37], v[26:27], v[38:39] op_sel_hi:[1,0]
	v_pk_mul_f32 v[44:45], v[72:73], v[38:39] op_sel_hi:[1,0]
	v_pk_mul_f32 v[32:33], v[32:33], v[38:39] op_sel_hi:[1,0]
	v_pk_mul_f32 v[46:47], v[76:77], v[38:39] op_sel_hi:[1,0]
	v_pk_mul_f32 v[38:39], v[74:75], v[38:39] op_sel_hi:[1,0]
	v_pk_mul_f32 v[26:27], v[14:15], v[30:31]
	v_pk_mul_f32 v[24:25], v[12:13], v[28:29]
	v_pk_mul_f32 v[30:31], v[6:7], v[36:37]
	v_pk_mul_f32 v[28:29], v[4:5], v[34:35]
	v_pk_mul_f32 v[34:35], v[10:11], v[32:33]
	v_pk_mul_f32 v[32:33], v[8:9], v[44:45]
	v_pk_mul_f32 v[38:39], v[2:3], v[38:39]
	v_pk_mul_f32 v[36:37], v[0:1], v[46:47]
	global_store_dwordx4 v[40:41], v[24:27], off
	global_store_dwordx4 v[40:41], v[28:31], off offset:16
	global_store_dwordx4 v[40:41], v[32:35], off offset:512
	global_store_dwordx4 v[40:41], v[36:39], off offset:528
	global_load_dword v24, v[42:43], off sc1
	s_nop 0
	global_load_dword v26, v[42:43], off offset:4 sc1
	global_load_dword v25, v[42:43], off offset:8 sc1
	global_load_dword v27, v[42:43], off offset:12 sc1
	s_waitcnt vmcnt(0)
	v_pk_add_f32 v[24:25], v[24:25], v[26:27]
	s_nop 0
	v_add_f32_e32 v24, v24, v25
	ds_bpermute_b32 v25, v206, v24
	s_waitcnt lgkmcnt(0)
	v_add_f32_e32 v26, v24, v25
	ds_bpermute_b32 v27, v207, v26
	v_lshlrev_b64 v[24:25], 12, v[88:89]
	v_lshl_add_u64 v[24:25], s[20:21], 0, v[24:25]
	v_lshl_add_u64 v[24:25], v[24:25], 0, v[86:87]
	s_waitcnt lgkmcnt(0)
	v_add_f32_e32 v26, v26, v27
	v_fmamk_f32 v26, v26, 0x3a800000, v205
	v_rsq_f32_e32 v26, v26
	s_nop 0
	v_pk_mul_f32 v[18:19], v[18:19], v[26:27] op_sel_hi:[1,0]
	v_pk_mul_f32 v[16:17], v[16:17], v[26:27] op_sel_hi:[1,0]
	v_pk_mul_f32 v[22:23], v[22:23], v[26:27] op_sel_hi:[1,0]
	v_pk_mul_f32 v[20:21], v[20:21], v[26:27] op_sel_hi:[1,0]
	v_pk_mul_f32 v[28:29], v[66:67], v[26:27] op_sel_hi:[1,0]
	v_pk_mul_f32 v[30:31], v[64:65], v[26:27] op_sel_hi:[1,0]
	v_pk_mul_f32 v[32:33], v[70:71], v[26:27] op_sel_hi:[1,0]
	v_pk_mul_f32 v[26:27], v[68:69], v[26:27] op_sel_hi:[1,0]
	v_pk_mul_f32 v[14:15], v[14:15], v[16:17]
	v_pk_mul_f32 v[12:13], v[12:13], v[18:19]
	v_pk_mul_f32 v[6:7], v[6:7], v[20:21]
	v_pk_mul_f32 v[4:5], v[4:5], v[22:23]
	v_pk_mul_f32 v[10:11], v[10:11], v[30:31]
	v_pk_mul_f32 v[8:9], v[8:9], v[28:29]
	v_pk_mul_f32 v[2:3], v[2:3], v[26:27]
	v_pk_mul_f32 v[0:1], v[0:1], v[32:33]
	global_store_dwordx4 v[24:25], v[12:15], off
	global_store_dwordx4 v[24:25], v[4:7], off offset:16
	global_store_dwordx4 v[24:25], v[8:11], off offset:512
	global_store_dwordx4 v[24:25], v[0:3], off offset:528
	s_cbranch_vccnz .LBB0_423
	s_andn2_b64 vcc, exec, s[8:9]
	s_cbranch_vccnz .LBB0_422
	s_mov_b32 s100, 1
	s_branch .LBB0_422

; __global__ void __launch_bounds__(512, 2) mk_fwd(Args a) {
	.amdhsa_kernel _Z6mk_fwd4Args
		.amdhsa_group_segment_fixed_size 0
		.amdhsa_private_segment_fixed_size 0
		.amdhsa_kernarg_size 384
		.amdhsa_user_sgpr_count 2
		.amdhsa_user_sgpr_dispatch_ptr 0
		.amdhsa_user_sgpr_queue_ptr 0
		.amdhsa_user_sgpr_kernarg_segment_ptr 1
		.amdhsa_user_sgpr_dispatch_id 0
		.amdhsa_user_sgpr_kernarg_preload_length 0
		.amdhsa_user_sgpr_kernarg_preload_offset 0
		.amdhsa_user_sgpr_private_segment_size 0
		.amdhsa_uses_dynamic_stack 0
		.amdhsa_enable_private_segment 0
		.amdhsa_system_sgpr_workgroup_id_x 1
		.amdhsa_system_sgpr_workgroup_id_y 0
		.amdhsa_system_sgpr_workgroup_id_z 0
		.amdhsa_system_sgpr_workgroup_info 0
		.amdhsa_system_vgpr_workitem_id 2
		.amdhsa_next_free_vgpr 256
		.amdhsa_next_free_sgpr 102
		.amdhsa_accum_offset 256
		.amdhsa_reserve_vcc 1
		.amdhsa_float_round_mode_32 0
		.amdhsa_float_round_mode_16_64 0
		.amdhsa_float_denorm_mode_32 3
		.amdhsa_float_denorm_mode_16_64 3
		.amdhsa_dx10_clamp 1
		.amdhsa_ieee_mode 1
		.amdhsa_fp16_overflow 0
		.amdhsa_tg_split 0
		.amdhsa_exception_fp_ieee_invalid_op 0
		.amdhsa_exception_fp_denorm_src 0
		.amdhsa_exception_fp_ieee_div_zero 0
		.amdhsa_exception_fp_ieee_overflow 0
		.amdhsa_exception_fp_ieee_underflow 0
		.amdhsa_exception_fp_ieee_inexact 0
		.amdhsa_exception_int_div_zero 0
	.end_amdhsa_kernel
